# tile epilogues of the two wave-halves run concurrently: un-stagger barrier before the epilogue, re-stagger before the next tile K-loop (all 6 GEMM phases), on top of saddr LDS-DMA
# speedup vs baseline: 1.0409x; 1.0278x over previous
.LBB0_124:
	s_cmpk_gt_i32 s30, 0x107f
	v_readfirstlane_b32 s37, v146
	s_waitcnt lgkmcnt(0)
	s_barrier
	s_cbranch_scc1 .LBB0_136
	s_waitcnt vmcnt(3)
	v_lshlrev_b32_e32 v0, 4, v146
	v_add_u32_e32 v1, 0x2000, v0
	v_ashrrev_i32_e32 v2, 31, v1
	v_lshrrev_b32_e32 v2, 22, v2
	v_add_u32_e32 v2, v1, v2
	s_waitcnt vmcnt(1)
	v_ashrrev_i32_e32 v8, 10, v2
	v_mul_i32_i24_e32 v2, 0x400, v8
	v_sub_u32_e32 v1, v1, v2
	v_lshrrev_b32_e32 v2, 4, v1
	v_bitop3_b32 v1, v2, v1, 32 bitop3:0x6c
	v_ashrrev_i32_e32 v2, 31, v1
	v_lshrrev_b32_e32 v2, 26, v2
	v_add_u32_e32 v2, v1, v2
	v_lshlrev_b32_e32 v3, 3, v8
	v_ashrrev_i32_e32 v9, 6, v2
	v_and_b32_e32 v3, -16, v3
	v_add_u32_e32 v3, v9, v3
	v_and_b32_e32 v4, 3, v9
	s_mov_b32 s4, 0x1fffe0
	v_lshrrev_b32_e32 v5, 2, v3
	v_lshlrev_b32_e32 v6, 1, v3
	v_and_b32_e32 v2, 0xc0, v2
	v_and_or_b32 v4, v3, s4, v4
	v_and_b32_e32 v5, 4, v5
	v_and_b32_e32 v6, 24, v6
	v_sub_u32_e32 v1, v1, v2
	v_mov_b32_e32 v2, 1
	v_or3_b32 v4, v4, v5, v6
	v_lshlrev_b32_e32 v5, 5, v8
	v_ashrrev_i16_sdwa v1, v2, sext(v1) dst_sel:DWORD dst_unused:UNUSED_PAD src0_sel:DWORD src1_sel:BYTE_0
	v_and_b32_e32 v5, 32, v5
	v_bfe_i32 v10, v1, 0, 16
	v_add_lshl_u32 v1, v5, v10, 1
	v_lshl_add_u32 v128, v4, 11, v1
	v_lshl_add_u32 v130, v3, 11, v1
	v_bfe_i32 v1, v146, 27, 1
	v_lshrrev_b32_e32 v1, 22, v1
	v_add_u32_e32 v1, v0, v1
	v_and_b32_e32 v1, 0xfffffc00, v1
	v_sub_u32_e32 v0, v0, v1
	v_lshrrev_b32_e32 v1, 4, v0
	v_ashrrev_i32_e32 v3, 31, v146
	v_bitop3_b32 v0, v1, v0, 32 bitop3:0x6c
	v_lshrrev_b32_e32 v3, 26, v3
	v_ashrrev_i32_e32 v1, 31, v0
	v_add_u32_e32 v3, v146, v3
	v_lshrrev_b32_e32 v1, 26, v1
	s_waitcnt vmcnt(0)
	v_ashrrev_i32_e32 v12, 6, v3
	s_ashr_i32 s6, s37, 6
	v_add_u32_e32 v1, v0, v1
	v_lshlrev_b32_e32 v3, 3, v12
	s_ashr_i32 s5, s37, 8
	s_lshl_b32 s38, s6, 10
	v_ashrrev_i32_e32 v11, 6, v1
	v_and_b32_e32 v3, -16, v3
	s_add_u32 s39, s33, 0x3800000
	v_add_u32_e32 v3, v11, v3
	v_and_b32_e32 v4, 3, v11
	s_addc_u32 s40, s34, 0
	v_and_or_b32 v4, v3, s4, v4
	s_ashr_i32 s4, s30, 31
	s_lshr_b32 s4, s4, 29
	s_add_i32 s4, s30, s4
	s_ashr_i32 s7, s4, 3
	s_and_b32 s4, s4, -8
	s_sub_i32 s4, s30, s4
	s_cmp_lt_i32 s4, 0
	s_movk_i32 s41, 0x211
	s_cselect_b32 s8, s41, 0x210
	s_mul_i32 s4, s4, s8
	s_add_i32 s4, s4, s7
	s_mul_hi_i32 s7, s4, 0x2e8ba2e9
	s_lshr_b32 s8, s7, 31
	s_ashr_i32 s7, s7, 5
	s_add_i32 s7, s7, s8
	s_lshl_b32 s8, s7, 3
	s_mulk_i32 s7, 0xb0
	s_sub_i32 s7, s4, s7
	s_bfe_u32 s4, s7, 0x3001c
	s_add_i32 s9, s7, s4
	s_sext_i32_i16 s4, s9
	s_and_b32 s9, s9, 0xfff8
	s_sub_i32 s7, s7, s9
	s_sext_i32_i16 s7, s7
	v_lshrrev_b32_e32 v5, 2, v3
	v_lshlrev_b32_e32 v6, 1, v3
	v_and_b32_e32 v1, 0xc0, v1
	s_lshr_b32 s4, s4, 3
	s_add_i32 s18, s8, s7
	v_and_b32_e32 v5, 4, v5
	v_and_b32_e32 v6, 24, v6
	v_sub_u32_e32 v0, v0, v1
	s_ashr_i32 s19, s18, 31
	s_bfe_i64 s[10:11], s[4:5], 0x100000
	v_or3_b32 v4, v4, v5, v6
	v_lshlrev_b32_e32 v5, 5, v12
	v_ashrrev_i16_sdwa v0, v2, sext(v0) dst_sel:DWORD dst_unused:UNUSED_PAD src0_sel:DWORD src1_sel:BYTE_0
	s_lshl_b64 s[8:9], s[18:19], 19
	s_lshl_b64 s[10:11], s[10:11], 19
	v_and_b32_e32 v5, 32, v5
	v_bfe_i32 v13, v0, 0, 16
	s_add_u32 s26, s33, s10
	v_add_lshl_u32 v0, v5, v13, 1
	s_addc_u32 s27, s34, s11
	s_add_i32 s19, s38, 0
	v_lshl_add_u32 v132, v4, 11, v0
	s_add_i32 m0, s19, 0x10000
	v_lshl_add_u32 v134, v3, 11, v0
	global_load_lds_dwordx4 v132, s[26:27]
	s_add_i32 m0, s19, 0x12000
	s_add_u32 s20, s39, s8
	global_load_lds_dwordx4 v128, s[26:27]
	s_addc_u32 s21, s40, s9
	s_mov_b32 m0, s19
	s_add_i32 s42, s19, 0x2000
	global_load_lds_dwordx4 v134, s[20:21]
	s_mov_b32 m0, s42
	s_add_u32 s8, s26, 0x40000
	global_load_lds_dwordx4 v130, s[20:21]
	s_addc_u32 s9, s27, 0
	s_add_i32 m0, s19, 0x14000
	v_mov_b32_e32 v133, 0
	global_load_lds_dwordx4 v132, s[8:9]
	s_add_i32 m0, s19, 0x16000
	v_mov_b32_e32 v129, v133
	global_load_lds_dwordx4 v128, s[8:9]
	s_add_u32 s8, s20, 0x40000
	s_addc_u32 s9, s21, 0
	s_add_i32 s43, s19, 0x4000
	s_mov_b32 m0, s43
	s_add_i32 s44, s19, 0x6000
	global_load_lds_dwordx4 v134, s[8:9]
	s_mov_b32 m0, s44
	v_mov_b32_e32 v135, v133
	global_load_lds_dwordx4 v130, s[8:9]
	v_mov_b32_e32 v131, v133
	s_mov_b32 s51, 0
	v_lshl_add_u64 v[6:7], s[26:27], 0, v[132:133]
	v_lshl_add_u64 v[4:5], s[26:27], 0, v[128:129]
	v_lshl_add_u64 v[2:3], s[20:21], 0, v[134:135]
	s_cmp_lg_u32 s5, 1
	v_lshl_add_u64 v[0:1], s[20:21], 0, v[130:131]
	s_cbranch_scc1 .LBB0_127
.LBB0_127:
	s_lshl_b32 s6, s6, 5
	s_and_b32 s13, s6, 0x60
	s_lshl_b32 s12, s5, 13
	s_lshl_b32 s14, s13, 7
	s_add_u32 s6, s33, 0x9800000
	s_mov_b64 s[8:9], 0x80
	s_addc_u32 s7, s34, 0
	s_add_i32 m0, s19, 0x18000
	v_lshl_add_u64 v[6:7], v[6:7], 0, s[8:9]
	s_waitcnt vmcnt(4)
	s_barrier
	global_load_lds_dwordx4 v[6:7], off
	v_lshl_add_u64 v[4:5], v[4:5], 0, s[8:9]
	s_add_i32 m0, s19, 0x1a000
	s_add_i32 s45, s19, 0x8000
	s_add_i32 s46, s19, 0xa000
	global_load_lds_dwordx4 v[4:5], off
	v_lshl_add_u64 v[2:3], v[2:3], 0, s[8:9]
	s_mov_b32 m0, s45
	s_add_u32 s10, s26, 0x40080
	global_load_lds_dwordx4 v[2:3], off
	v_lshl_add_u64 v[0:1], v[0:1], 0, s[8:9]
	s_mov_b32 m0, s46
	s_addc_u32 s11, s27, 0
	global_load_lds_dwordx4 v[0:1], off
	s_add_i32 m0, s19, 0x1c000
	v_lshl_add_u64 v[0:1], s[10:11], 0, v[132:133]
	global_load_lds_dwordx4 v[0:1], off
	v_lshl_add_u64 v[0:1], s[10:11], 0, v[128:129]
	s_add_i32 m0, s19, 0x1e000
	s_sext_i32_i16 s52, s4
	global_load_lds_dwordx4 v[0:1], off
	v_lshrrev_b32_e32 v1, 1, v146
	v_and_b32_e32 v1, 24, v1
	s_lshl_b32 s4, s5, 8
	v_and_b32_e32 v0, 15, v146
	v_lshlrev_b32_e32 v2, 1, v1
	s_add_i32 s4, s4, 0
	v_lshl_or_b32 v144, s5, 6, v0
	v_lshl_or_b32 v2, v0, 6, v2
	v_lshlrev_b32_e32 v0, 2, v0
	s_add_i32 s4, s4, 0x20000
	v_and_b32_e32 v3, 32, v0
	v_add_u32_e32 v147, s4, v0
	v_lshlrev_b32_e32 v0, 14, v12
	v_and_b32_e32 v0, 0xffff8000, v0
	v_or_b32_e32 v148, s13, v1
	v_lshl_add_u32 v0, v11, 11, v0
	v_and_b32_e32 v1, 1, v12
	v_lshl_or_b32 v0, v1, 6, v0
	v_lshl_add_u32 v136, v13, 1, v0
	v_lshlrev_b32_e32 v0, 14, v8
	v_and_b32_e32 v0, 0xffff8000, v0
	s_waitcnt vmcnt(6)
	v_lshl_add_u32 v0, v9, 11, v0
	v_and_b32_e32 v1, 1, v8
	v_bitop3_b32 v4, v2, s12, v3 bitop3:0xde
	v_bitop3_b32 v145, s14, v2, v3 bitop3:0xf6
	v_lshl_or_b32 v0, v1, 6, v0
	s_add_i32 s47, 0, 0x10000
	s_add_i32 s48, 0, 0x14000
	v_mov_b32_e32 v137, v133
	v_lshl_add_u32 v138, v10, 1, v0
	v_mov_b32_e32 v139, v133
	v_mov_b64_e32 v[140:141], 0x1080
	v_mov_b64_e32 v[142:143], 0x107f
	v_add_u32_e32 v149, s47, v145
	v_add_u32_e32 v150, 0, v4
	v_add_u32_e32 v151, s48, v145
	s_movk_i32 s49, 0x1600
	s_barrier

.LBB0_130:
	s_ashr_i32 s13, s12, 31
	v_cmp_lt_i64_e32 vcc, s[14:15], v[140:141]
	s_lshl_b64 s[14:15], s[12:13], 19
	s_add_u32 s14, s39, s14
	s_addc_u32 s15, s40, s15
	s_and_b64 s[16:17], vcc, exec
	s_cselect_b32 s13, s15, s21
	s_cselect_b32 s53, s14, s20
	s_ashr_i32 s11, s10, 31
	s_lshl_b64 s[16:17], s[10:11], 19
	s_add_u32 s16, s33, s16
	s_addc_u32 s17, s34, s17
	s_and_b64 s[28:29], vcc, exec
	s_cselect_b32 s11, s17, s27
	s_cselect_b32 s54, s16, s26
	s_add_u32 s20, s20, 0x40080
	s_addc_u32 s21, s21, 0
	s_add_u32 s55, s26, 0x100
	v_mov_b32_e32 v0, 0
	s_addc_u32 s56, s27, 0
	s_mov_b32 s57, -2
	v_mov_b32_e32 v1, v0
	v_mov_b32_e32 v2, v0
	v_mov_b32_e32 v3, v0
	v_mov_b32_e32 v4, v0
	v_mov_b32_e32 v5, v0
	v_mov_b32_e32 v6, v0
	v_mov_b32_e32 v7, v0
	v_mov_b32_e32 v16, v0
	v_mov_b32_e32 v17, v0
	v_mov_b32_e32 v18, v0
	v_mov_b32_e32 v19, v0
	v_mov_b32_e32 v20, v0
	v_mov_b32_e32 v21, v0
	v_mov_b32_e32 v22, v0
	v_mov_b32_e32 v23, v0
	v_mov_b32_e32 v32, v0
	v_mov_b32_e32 v33, v0
	v_mov_b32_e32 v34, v0
	v_mov_b32_e32 v35, v0
	v_mov_b32_e32 v36, v0
	v_mov_b32_e32 v37, v0
	v_mov_b32_e32 v38, v0
	v_mov_b32_e32 v39, v0
	v_mov_b32_e32 v48, v0
	v_mov_b32_e32 v49, v0
	v_mov_b32_e32 v50, v0
	v_mov_b32_e32 v51, v0
	v_mov_b32_e32 v52, v0
	v_mov_b32_e32 v53, v0
	v_mov_b32_e32 v54, v0
	v_mov_b32_e32 v55, v0
	v_mov_b32_e32 v8, v0
	v_mov_b32_e32 v9, v0
	v_mov_b32_e32 v10, v0
	v_mov_b32_e32 v11, v0
	v_mov_b32_e32 v12, v0
	v_mov_b32_e32 v13, v0
	v_mov_b32_e32 v14, v0
	v_mov_b32_e32 v15, v0
	v_mov_b32_e32 v24, v0
	v_mov_b32_e32 v25, v0
	v_mov_b32_e32 v26, v0
	v_mov_b32_e32 v27, v0
	v_mov_b32_e32 v28, v0
	v_mov_b32_e32 v29, v0
	v_mov_b32_e32 v30, v0
	v_mov_b32_e32 v31, v0
	v_mov_b32_e32 v40, v0
	v_mov_b32_e32 v41, v0
	v_mov_b32_e32 v42, v0
	v_mov_b32_e32 v43, v0
	v_mov_b32_e32 v44, v0
	v_mov_b32_e32 v45, v0
	v_mov_b32_e32 v46, v0
	v_mov_b32_e32 v47, v0
	v_mov_b32_e32 v56, v0
	v_mov_b32_e32 v57, v0
	v_mov_b32_e32 v58, v0
	v_mov_b32_e32 v59, v0
	v_mov_b32_e32 v60, v0
	v_mov_b32_e32 v61, v0
	v_mov_b32_e32 v62, v0
	v_mov_b32_e32 v63, v0
	v_mov_b32_e32 v64, v0
	v_mov_b32_e32 v65, v0
	v_mov_b32_e32 v66, v0
	v_mov_b32_e32 v67, v0
	v_mov_b32_e32 v68, v0
	v_mov_b32_e32 v69, v0
	v_mov_b32_e32 v70, v0
	v_mov_b32_e32 v71, v0
	v_mov_b32_e32 v80, v0
	v_mov_b32_e32 v81, v0
	v_mov_b32_e32 v82, v0
	v_mov_b32_e32 v83, v0
	v_mov_b32_e32 v84, v0
	v_mov_b32_e32 v85, v0
	v_mov_b32_e32 v86, v0
	v_mov_b32_e32 v87, v0
	v_mov_b32_e32 v96, v0
	v_mov_b32_e32 v97, v0
	v_mov_b32_e32 v98, v0
	v_mov_b32_e32 v99, v0
	v_mov_b32_e32 v100, v0
	v_mov_b32_e32 v101, v0
	v_mov_b32_e32 v102, v0
	v_mov_b32_e32 v103, v0
	v_mov_b32_e32 v112, v0
	v_mov_b32_e32 v113, v0
	v_mov_b32_e32 v114, v0
	v_mov_b32_e32 v115, v0
	v_mov_b32_e32 v116, v0
	v_mov_b32_e32 v117, v0
	v_mov_b32_e32 v118, v0
	v_mov_b32_e32 v119, v0
	v_mov_b32_e32 v72, v0
	v_mov_b32_e32 v73, v0
	v_mov_b32_e32 v74, v0
	v_mov_b32_e32 v75, v0
	v_mov_b32_e32 v76, v0
	v_mov_b32_e32 v77, v0
	v_mov_b32_e32 v78, v0
	v_mov_b32_e32 v79, v0
	v_mov_b32_e32 v88, v0
	v_mov_b32_e32 v89, v0
	v_mov_b32_e32 v90, v0
	v_mov_b32_e32 v91, v0
	v_mov_b32_e32 v92, v0
	v_mov_b32_e32 v93, v0
	v_mov_b32_e32 v94, v0
	v_mov_b32_e32 v95, v0
	v_mov_b32_e32 v104, v0
	v_mov_b32_e32 v105, v0
	v_mov_b32_e32 v106, v0
	v_mov_b32_e32 v107, v0
	v_mov_b32_e32 v108, v0
	v_mov_b32_e32 v109, v0
	v_mov_b32_e32 v110, v0
	v_mov_b32_e32 v111, v0
	v_mov_b32_e32 v120, v0
	v_mov_b32_e32 v121, v0
	v_mov_b32_e32 v122, v0
	v_mov_b32_e32 v123, v0
	v_mov_b32_e32 v124, v0
	v_mov_b32_e32 v125, v0
	v_mov_b32_e32 v126, v0
	v_mov_b32_e32 v127, v0
	s_cmpk_lt_u32 s37, 0x100
	s_cbranch_scc1 .Lg131_noy
	s_barrier
.Lg131_noy:
.LBB0_131:
	ds_read_b128 v[152:155], v149
	ds_read_b128 v[156:159], v149 offset:1024
	ds_read_b128 v[160:163], v149 offset:2048
	ds_read_b128 v[164:167], v149 offset:3072
	s_add_u32 s26, s20, 0xfffc0080
	s_addc_u32 s27, s21, -1
	s_cmp_eq_u32 s57, 12
	s_cselect_b32 s29, s13, s27
	s_cselect_b32 s28, s53, s26
	s_cselect_b32 s27, s11, s56
	s_cselect_b32 s26, s54, s55
	s_add_i32 m0, s19, 0xc000
	ds_read_b128 v[168:171], v150
	ds_read_b128 v[172:175], v150 offset:1024
	ds_read_b128 v[176:179], v150 offset:2048
	ds_read_b128 v[180:183], v150 offset:3072
	ds_read_b128 v[184:187], v150 offset:4096
	ds_read_b128 v[188:191], v150 offset:5120
	ds_read_b128 v[192:195], v150 offset:6144
	ds_read_b128 v[196:199], v150 offset:7168
	global_load_lds_dwordx4 v136, s[20:21]
	s_add_i32 m0, s19, 0xe000
	s_nop 0
	global_load_lds_dwordx4 v138, s[20:21]
	s_waitcnt lgkmcnt(8)
	s_barrier
	s_waitcnt lgkmcnt(0)
	s_setprio 1
	s_waitcnt lgkmcnt(0)
	v_mfma_f32_16x16x32_bf16 v[124:127], v[152:155], v[168:171], v[124:127]
	v_mfma_f32_16x16x32_bf16 v[120:123], v[160:163], v[168:171], v[120:123]
	v_mfma_f32_16x16x32_bf16 v[108:111], v[152:155], v[176:179], v[108:111]
	v_mfma_f32_16x16x32_bf16 v[104:107], v[160:163], v[176:179], v[104:107]
	v_mfma_f32_16x16x32_bf16 v[92:95], v[152:155], v[184:187], v[92:95]
	v_mfma_f32_16x16x32_bf16 v[88:91], v[160:163], v[184:187], v[88:91]
	v_mfma_f32_16x16x32_bf16 v[76:79], v[152:155], v[192:195], v[76:79]
	v_mfma_f32_16x16x32_bf16 v[72:75], v[160:163], v[192:195], v[72:75]
	v_mfma_f32_16x16x32_bf16 v[124:127], v[156:159], v[172:175], v[124:127]
	v_mfma_f32_16x16x32_bf16 v[120:123], v[164:167], v[172:175], v[120:123]
	v_mfma_f32_16x16x32_bf16 v[108:111], v[156:159], v[180:183], v[108:111]
	v_mfma_f32_16x16x32_bf16 v[104:107], v[164:167], v[180:183], v[104:107]
	v_mfma_f32_16x16x32_bf16 v[92:95], v[156:159], v[188:191], v[92:95]
	v_mfma_f32_16x16x32_bf16 v[88:91], v[164:167], v[188:191], v[88:91]
	v_mfma_f32_16x16x32_bf16 v[76:79], v[156:159], v[196:199], v[76:79]
	v_mfma_f32_16x16x32_bf16 v[72:75], v[164:167], v[196:199], v[72:75]
	s_setprio 0
	s_barrier
	s_add_i32 s58, s47, s38
	s_add_u32 s80, s26, 0x80
	s_addc_u32 s81, s27, 0
	s_mov_b32 m0, s58
	ds_read_b128 v[200:203], v151
	ds_read_b128 v[204:207], v151 offset:1024
	ds_read_b128 v[208:211], v151 offset:2048
	ds_read_b128 v[212:215], v151 offset:3072
	global_load_lds_dwordx4 v132, s[26:27]
	s_add_i32 m0, s58, 0x2000
	s_nop 0
	global_load_lds_dwordx4 v128, s[26:27]
	s_barrier
	s_waitcnt lgkmcnt(0)
	s_setprio 1
	s_waitcnt lgkmcnt(0)
	v_mfma_f32_16x16x32_bf16 v[116:119], v[200:203], v[168:171], v[116:119]
	v_mfma_f32_16x16x32_bf16 v[112:115], v[208:211], v[168:171], v[112:115]
	v_mfma_f32_16x16x32_bf16 v[100:103], v[200:203], v[176:179], v[100:103]
	v_mfma_f32_16x16x32_bf16 v[96:99], v[208:211], v[176:179], v[96:99]
	v_mfma_f32_16x16x32_bf16 v[84:87], v[200:203], v[184:187], v[84:87]
	v_mfma_f32_16x16x32_bf16 v[80:83], v[208:211], v[184:187], v[80:83]
	v_mfma_f32_16x16x32_bf16 v[68:71], v[200:203], v[192:195], v[68:71]
	v_mfma_f32_16x16x32_bf16 v[64:67], v[208:211], v[192:195], v[64:67]
	v_mfma_f32_16x16x32_bf16 v[116:119], v[204:207], v[172:175], v[116:119]
	v_mfma_f32_16x16x32_bf16 v[112:115], v[212:215], v[172:175], v[112:115]
	v_mfma_f32_16x16x32_bf16 v[100:103], v[204:207], v[180:183], v[100:103]
	v_mfma_f32_16x16x32_bf16 v[96:99], v[212:215], v[180:183], v[96:99]
	v_mfma_f32_16x16x32_bf16 v[84:87], v[204:207], v[188:191], v[84:87]
	v_mfma_f32_16x16x32_bf16 v[80:83], v[212:215], v[188:191], v[80:83]
	v_mfma_f32_16x16x32_bf16 v[68:71], v[204:207], v[196:199], v[68:71]
	v_mfma_f32_16x16x32_bf16 v[64:67], v[212:215], v[196:199], v[64:67]
	s_setprio 0
	s_mov_b32 m0, s19
	s_add_u32 s82, s28, 0x80
	s_addc_u32 s83, s29, 0
	s_barrier
	ds_read_b128 v[168:171], v150 offset:16384
	ds_read_b128 v[172:175], v150 offset:17408
	ds_read_b128 v[176:179], v150 offset:18432
	ds_read_b128 v[180:183], v150 offset:19456
	ds_read_b128 v[184:187], v150 offset:20480
	ds_read_b128 v[188:191], v150 offset:21504
	ds_read_b128 v[192:195], v150 offset:22528
	ds_read_b128 v[196:199], v150 offset:23552
	global_load_lds_dwordx4 v134, s[28:29]
	s_mov_b32 m0, s42
	s_nop 0
	global_load_lds_dwordx4 v130, s[28:29]
	s_barrier
	s_waitcnt lgkmcnt(0)
	s_setprio 1
	s_waitcnt lgkmcnt(0)
	v_mfma_f32_16x16x32_bf16 v[60:63], v[152:155], v[168:171], v[60:63]
	v_mfma_f32_16x16x32_bf16 v[56:59], v[160:163], v[168:171], v[56:59]
	v_mfma_f32_16x16x32_bf16 v[44:47], v[152:155], v[176:179], v[44:47]
	v_mfma_f32_16x16x32_bf16 v[40:43], v[160:163], v[176:179], v[40:43]
	v_mfma_f32_16x16x32_bf16 v[28:31], v[152:155], v[184:187], v[28:31]
	v_mfma_f32_16x16x32_bf16 v[24:27], v[160:163], v[184:187], v[24:27]
	v_mfma_f32_16x16x32_bf16 v[12:15], v[152:155], v[192:195], v[12:15]
	v_mfma_f32_16x16x32_bf16 v[8:11], v[160:163], v[192:195], v[8:11]
	v_mfma_f32_16x16x32_bf16 v[60:63], v[156:159], v[172:175], v[60:63]
	v_mfma_f32_16x16x32_bf16 v[56:59], v[164:167], v[172:175], v[56:59]
	v_mfma_f32_16x16x32_bf16 v[44:47], v[156:159], v[180:183], v[44:47]
	v_mfma_f32_16x16x32_bf16 v[40:43], v[164:167], v[180:183], v[40:43]
	v_mfma_f32_16x16x32_bf16 v[28:31], v[156:159], v[188:191], v[28:31]
	v_mfma_f32_16x16x32_bf16 v[24:27], v[164:167], v[188:191], v[24:27]
	v_mfma_f32_16x16x32_bf16 v[12:15], v[156:159], v[196:199], v[12:15]
	v_mfma_f32_16x16x32_bf16 v[8:11], v[164:167], v[196:199], v[8:11]
	s_setprio 0
	s_barrier
	s_add_u32 s58, s26, 0x40000
	s_addc_u32 s59, s27, 0
	s_add_i32 s60, s48, s38
	s_mov_b32 m0, s60
	s_nop 0
	global_load_lds_dwordx4 v132, s[58:59]
	s_add_i32 m0, s60, 0x2000
	s_nop 0
	global_load_lds_dwordx4 v128, s[58:59]
	s_waitcnt vmcnt(6)
	s_barrier
	s_setprio 1
	v_mfma_f32_16x16x32_bf16 v[52:55], v[200:203], v[168:171], v[52:55]
	v_mfma_f32_16x16x32_bf16 v[48:51], v[208:211], v[168:171], v[48:51]
	v_mfma_f32_16x16x32_bf16 v[36:39], v[200:203], v[176:179], v[36:39]
	v_mfma_f32_16x16x32_bf16 v[32:35], v[208:211], v[176:179], v[32:35]
	v_mfma_f32_16x16x32_bf16 v[20:23], v[200:203], v[184:187], v[20:23]
	v_mfma_f32_16x16x32_bf16 v[16:19], v[208:211], v[184:187], v[16:19]
	v_mfma_f32_16x16x32_bf16 v[4:7], v[200:203], v[192:195], v[4:7]
	v_mfma_f32_16x16x32_bf16 v[0:3], v[208:211], v[192:195], v[0:3]
	v_mfma_f32_16x16x32_bf16 v[52:55], v[204:207], v[172:175], v[52:55]
	v_mfma_f32_16x16x32_bf16 v[48:51], v[212:215], v[172:175], v[48:51]
	v_mfma_f32_16x16x32_bf16 v[36:39], v[204:207], v[180:183], v[36:39]
	v_mfma_f32_16x16x32_bf16 v[32:35], v[212:215], v[180:183], v[32:35]
	v_mfma_f32_16x16x32_bf16 v[20:23], v[204:207], v[188:191], v[20:23]
	v_mfma_f32_16x16x32_bf16 v[16:19], v[212:215], v[188:191], v[16:19]
	v_mfma_f32_16x16x32_bf16 v[4:7], v[204:207], v[196:199], v[4:7]
	v_mfma_f32_16x16x32_bf16 v[0:3], v[212:215], v[196:199], v[0:3]
	s_setprio 0
	s_add_i32 s58, 0, 0x18000
	v_add_u32_e32 v164, s58, v145
	s_barrier
	ds_read_b128 v[152:155], v164
	ds_read_b128 v[156:159], v164 offset:1024
	ds_read_b128 v[160:163], v164 offset:2048
	ds_read_b128 v[164:167], v164 offset:3072
	s_add_u32 s28, s28, 0x40000
	s_addc_u32 s29, s29, 0
	s_mov_b32 m0, s43
	ds_read_b128 v[168:171], v150 offset:32768
	ds_read_b128 v[172:175], v150 offset:33792
	ds_read_b128 v[176:179], v150 offset:34816
	ds_read_b128 v[180:183], v150 offset:35840
	ds_read_b128 v[184:187], v150 offset:36864
	ds_read_b128 v[188:191], v150 offset:37888
	ds_read_b128 v[192:195], v150 offset:38912
	ds_read_b128 v[196:199], v150 offset:39936
	global_load_lds_dwordx4 v134, s[28:29]
	s_mov_b32 m0, s44
	s_nop 0
	global_load_lds_dwordx4 v130, s[28:29]
	s_waitcnt lgkmcnt(8)
	s_barrier
	s_waitcnt lgkmcnt(0)
	s_setprio 1
	s_waitcnt lgkmcnt(0)
	v_mfma_f32_16x16x32_bf16 v[124:127], v[152:155], v[168:171], v[124:127]
	v_mfma_f32_16x16x32_bf16 v[120:123], v[160:163], v[168:171], v[120:123]
	v_mfma_f32_16x16x32_bf16 v[108:111], v[152:155], v[176:179], v[108:111]
	v_mfma_f32_16x16x32_bf16 v[104:107], v[160:163], v[176:179], v[104:107]
	v_mfma_f32_16x16x32_bf16 v[92:95], v[152:155], v[184:187], v[92:95]
	v_mfma_f32_16x16x32_bf16 v[88:91], v[160:163], v[184:187], v[88:91]
	v_mfma_f32_16x16x32_bf16 v[76:79], v[152:155], v[192:195], v[76:79]
	v_mfma_f32_16x16x32_bf16 v[72:75], v[160:163], v[192:195], v[72:75]
	v_mfma_f32_16x16x32_bf16 v[124:127], v[156:159], v[172:175], v[124:127]
	v_mfma_f32_16x16x32_bf16 v[120:123], v[164:167], v[172:175], v[120:123]
	v_mfma_f32_16x16x32_bf16 v[108:111], v[156:159], v[180:183], v[108:111]
	v_mfma_f32_16x16x32_bf16 v[104:107], v[164:167], v[180:183], v[104:107]
	v_mfma_f32_16x16x32_bf16 v[92:95], v[156:159], v[188:191], v[92:95]
	v_mfma_f32_16x16x32_bf16 v[88:91], v[164:167], v[188:191], v[88:91]
	v_mfma_f32_16x16x32_bf16 v[76:79], v[156:159], v[196:199], v[76:79]
	v_mfma_f32_16x16x32_bf16 v[72:75], v[164:167], v[196:199], v[72:75]
	s_setprio 0
	s_barrier
	s_add_i32 s28, 0, 0x1c000
	s_add_i32 s29, s58, s38
	v_add_u32_e32 v212, s28, v145
	s_mov_b32 m0, s29
	ds_read_b128 v[200:203], v212
	ds_read_b128 v[204:207], v212 offset:1024
	ds_read_b128 v[208:211], v212 offset:2048
	ds_read_b128 v[212:215], v212 offset:3072
	global_load_lds_dwordx4 v132, s[80:81]
	s_add_i32 m0, s29, 0x2000
	s_nop 0
	global_load_lds_dwordx4 v128, s[80:81]
	s_barrier
	s_waitcnt lgkmcnt(0)
	s_setprio 1
	s_waitcnt lgkmcnt(0)
	v_mfma_f32_16x16x32_bf16 v[116:119], v[200:203], v[168:171], v[116:119]
	v_mfma_f32_16x16x32_bf16 v[112:115], v[208:211], v[168:171], v[112:115]
	v_mfma_f32_16x16x32_bf16 v[100:103], v[200:203], v[176:179], v[100:103]
	v_mfma_f32_16x16x32_bf16 v[96:99], v[208:211], v[176:179], v[96:99]
	v_mfma_f32_16x16x32_bf16 v[84:87], v[200:203], v[184:187], v[84:87]
	v_mfma_f32_16x16x32_bf16 v[80:83], v[208:211], v[184:187], v[80:83]
	v_mfma_f32_16x16x32_bf16 v[68:71], v[200:203], v[192:195], v[68:71]
	v_mfma_f32_16x16x32_bf16 v[64:67], v[208:211], v[192:195], v[64:67]
	v_mfma_f32_16x16x32_bf16 v[116:119], v[204:207], v[172:175], v[116:119]
	v_mfma_f32_16x16x32_bf16 v[112:115], v[212:215], v[172:175], v[112:115]
	v_mfma_f32_16x16x32_bf16 v[100:103], v[204:207], v[180:183], v[100:103]
	v_mfma_f32_16x16x32_bf16 v[96:99], v[212:215], v[180:183], v[96:99]
	v_mfma_f32_16x16x32_bf16 v[84:87], v[204:207], v[188:191], v[84:87]
	v_mfma_f32_16x16x32_bf16 v[80:83], v[212:215], v[188:191], v[80:83]
	v_mfma_f32_16x16x32_bf16 v[68:71], v[204:207], v[196:199], v[68:71]
	v_mfma_f32_16x16x32_bf16 v[64:67], v[212:215], v[196:199], v[64:67]
	s_setprio 0
	s_mov_b32 m0, s45
	s_barrier
	ds_read_b128 v[168:171], v150 offset:49152
	ds_read_b128 v[172:175], v150 offset:50176
	ds_read_b128 v[176:179], v150 offset:51200
	ds_read_b128 v[180:183], v150 offset:52224
	ds_read_b128 v[184:187], v150 offset:53248
	ds_read_b128 v[188:191], v150 offset:54272
	ds_read_b128 v[192:195], v150 offset:55296
	ds_read_b128 v[196:199], v150 offset:56320
	global_load_lds_dwordx4 v134, s[82:83]
	s_mov_b32 m0, s46
	s_nop 0
	global_load_lds_dwordx4 v130, s[82:83]
	s_barrier
	s_waitcnt lgkmcnt(0)
	s_setprio 1
	s_waitcnt lgkmcnt(0)
	v_mfma_f32_16x16x32_bf16 v[60:63], v[152:155], v[168:171], v[60:63]
	v_mfma_f32_16x16x32_bf16 v[56:59], v[160:163], v[168:171], v[56:59]
	v_mfma_f32_16x16x32_bf16 v[44:47], v[152:155], v[176:179], v[44:47]
	v_mfma_f32_16x16x32_bf16 v[40:43], v[160:163], v[176:179], v[40:43]
	v_mfma_f32_16x16x32_bf16 v[28:31], v[152:155], v[184:187], v[28:31]
	v_mfma_f32_16x16x32_bf16 v[24:27], v[160:163], v[184:187], v[24:27]
	v_mfma_f32_16x16x32_bf16 v[12:15], v[152:155], v[192:195], v[12:15]
	v_mfma_f32_16x16x32_bf16 v[8:11], v[160:163], v[192:195], v[8:11]
	v_mfma_f32_16x16x32_bf16 v[60:63], v[156:159], v[172:175], v[60:63]
	v_mfma_f32_16x16x32_bf16 v[56:59], v[164:167], v[172:175], v[56:59]
	v_mfma_f32_16x16x32_bf16 v[44:47], v[156:159], v[180:183], v[44:47]
	v_mfma_f32_16x16x32_bf16 v[40:43], v[164:167], v[180:183], v[40:43]
	v_mfma_f32_16x16x32_bf16 v[28:31], v[156:159], v[188:191], v[28:31]
	v_mfma_f32_16x16x32_bf16 v[24:27], v[164:167], v[188:191], v[24:27]
	v_mfma_f32_16x16x32_bf16 v[12:15], v[156:159], v[196:199], v[12:15]
	v_mfma_f32_16x16x32_bf16 v[8:11], v[164:167], v[196:199], v[8:11]
	s_setprio 0
	s_barrier
	s_add_u32 s26, s26, 0x40080
	s_addc_u32 s27, s27, 0
	s_add_i32 s28, s28, s38
	s_mov_b32 m0, s28
	s_nop 0
	global_load_lds_dwordx4 v132, s[26:27]
	s_add_i32 m0, s28, 0x2000
	s_nop 0
	global_load_lds_dwordx4 v128, s[26:27]
	s_waitcnt vmcnt(6)
	s_barrier
	s_setprio 1
	v_mfma_f32_16x16x32_bf16 v[52:55], v[200:203], v[168:171], v[52:55]
	v_mfma_f32_16x16x32_bf16 v[48:51], v[208:211], v[168:171], v[48:51]
	v_mfma_f32_16x16x32_bf16 v[36:39], v[200:203], v[176:179], v[36:39]
	v_mfma_f32_16x16x32_bf16 v[32:35], v[208:211], v[176:179], v[32:35]
	v_mfma_f32_16x16x32_bf16 v[20:23], v[200:203], v[184:187], v[20:23]
	v_mfma_f32_16x16x32_bf16 v[16:19], v[208:211], v[184:187], v[16:19]
	v_mfma_f32_16x16x32_bf16 v[4:7], v[200:203], v[192:195], v[4:7]
	v_mfma_f32_16x16x32_bf16 v[0:3], v[208:211], v[192:195], v[0:3]
	v_mfma_f32_16x16x32_bf16 v[52:55], v[204:207], v[172:175], v[52:55]
	v_mfma_f32_16x16x32_bf16 v[48:51], v[212:215], v[172:175], v[48:51]
	v_mfma_f32_16x16x32_bf16 v[36:39], v[204:207], v[180:183], v[36:39]
	v_mfma_f32_16x16x32_bf16 v[32:35], v[212:215], v[180:183], v[32:35]
	v_mfma_f32_16x16x32_bf16 v[20:23], v[204:207], v[188:191], v[20:23]
	v_mfma_f32_16x16x32_bf16 v[16:19], v[212:215], v[188:191], v[16:19]
	v_mfma_f32_16x16x32_bf16 v[4:7], v[204:207], v[196:199], v[4:7]
	v_mfma_f32_16x16x32_bf16 v[0:3], v[212:215], v[196:199], v[0:3]
	s_setprio 0
	s_add_i32 s57, s57, 2
	s_add_u32 s20, s20, 0x100
	s_addc_u32 s21, s21, 0
	s_add_u32 s55, s55, 0x100
	s_addc_u32 s56, s56, 0
	s_cmp_gt_u32 s57, 13
	s_barrier
	s_cbranch_scc0 .LBB0_131
	s_cmpk_gt_u32 s37, 0xff
	s_cbranch_scc1 .Lg131_nox
	s_barrier
.Lg131_nox:
	v_lshl_add_u32 v153, s51, 10, v147
	ds_read2_b32 v[154:155], v153 offset1:16
	v_lshl_or_b32 v156, s52, 7, v148
	v_lshl_add_u32 v152, s18, 8, v144
	s_and_b64 vcc, exec, s[4:5]
	s_mov_b32 s52, s10
	s_waitcnt lgkmcnt(0)
	v_pk_mul_f32 v[124:125], v[124:125], v[154:155] op_sel_hi:[1,0]
	v_pk_mul_f32 v[126:127], v[126:127], v[154:155] op_sel_hi:[1,0]
	v_mul_f32_e32 v157, 0xbfb8aa3b, v124
	v_mul_f32_e32 v158, 0xbfb8aa3b, v125
	v_exp_f32_e32 v159, v157
	v_exp_f32_e32 v158, v158
	v_pk_mul_f32 v[116:117], v[116:117], v[154:155] op_sel_hi:[1,0]
	v_pk_mul_f32 v[120:121], v[120:121], v[154:155] op_sel_hi:[1,0]
	v_add_f32_e32 v159, 1.0, v159
	v_add_f32_e32 v160, 1.0, v158
	v_rcp_f32_e32 v158, v159
	v_mul_f32_e32 v159, 0xbfb8aa3b, v126
	v_exp_f32_e32 v161, v159
	v_mul_f32_e32 v159, 0xbfb8aa3b, v127
	v_exp_f32_e32 v162, v159
	v_rcp_f32_e32 v159, v160
	v_add_f32_e32 v160, 1.0, v161
	v_rcp_f32_e32 v160, v160
	v_add_f32_e32 v161, 1.0, v162
	v_rcp_f32_e32 v161, v161
	v_pk_mul_f32 v[124:125], v[124:125], v[158:159]
	v_pk_mul_f32 v[118:119], v[118:119], v[154:155] op_sel_hi:[1,0]
	v_pk_mul_f32 v[116:117], v[116:117], v[124:125]
	v_pk_mul_f32 v[124:125], v[126:127], v[160:161]
	v_mul_f32_e32 v126, 0xbfb8aa3b, v120
	v_exp_f32_e32 v126, v126
	v_pk_mul_f32 v[118:119], v[118:119], v[124:125]
	v_mul_f32_e32 v124, 0xbfb8aa3b, v121
	v_pk_mul_f32 v[122:123], v[122:123], v[154:155] op_sel_hi:[1,0]
	v_exp_f32_e32 v125, v124
	v_add_f32_e32 v124, 1.0, v126
	v_mul_f32_e32 v126, 0xbfb8aa3b, v122
	v_mul_f32_e32 v127, 0xbfb8aa3b, v123
	v_exp_f32_e32 v126, v126
	v_exp_f32_e32 v127, v127
	v_add_f32_e32 v125, 1.0, v125
	v_rcp_f32_e32 v124, v124
	v_rcp_f32_e32 v125, v125
	v_add_f32_e32 v126, 1.0, v126
	v_add_f32_e32 v127, 1.0, v127
	v_rcp_f32_e32 v126, v126
	v_rcp_f32_e32 v127, v127
	v_pk_mul_f32 v[112:113], v[112:113], v[154:155] op_sel_hi:[1,0]
	v_pk_mul_f32 v[120:121], v[120:121], v[124:125]
	v_pk_mul_f32 v[114:115], v[114:115], v[154:155] op_sel_hi:[1,0]
	v_pk_mul_f32 v[112:113], v[112:113], v[120:121]
	v_pk_mul_f32 v[120:121], v[122:123], v[126:127]
	v_mov_b32_e32 v122, v155
	v_pk_mul_f32 v[108:109], v[108:109], v[122:123] op_sel_hi:[1,0]
	v_ashrrev_i32_e32 v157, 31, v156
	v_mul_f32_e32 v123, 0xbfb8aa3b, v108
	v_exp_f32_e32 v123, v123
	v_pk_mul_f32 v[114:115], v[114:115], v[120:121]
	v_cvt_pk_bf16_f32 v116, v116, v117
	v_cvt_pk_bf16_f32 v117, v118, v119
	v_cvt_pk_bf16_f32 v118, v112, v113
	v_mov_b64_e32 v[112:113], s[6:7]
	v_cvt_pk_bf16_f32 v119, v114, v115
	v_mad_i64_i32 v[120:121], s[20:21], v152, s49, v[112:113]
	v_lshlrev_b64 v[114:115], 1, v[156:157]
	v_lshl_add_u64 v[120:121], v[120:121], 0, v[114:115]
	global_store_dwordx4 v[120:121], v[116:119], off nt
	v_pk_mul_f32 v[110:111], v[110:111], v[122:123] op_sel_hi:[1,0]
	v_pk_mul_f32 v[100:101], v[100:101], v[122:123] op_sel_hi:[1,0]
	v_mul_f32_e32 v116, 0xbfb8aa3b, v109
	v_exp_f32_e32 v117, v116
	v_mul_f32_e32 v118, 0xbfb8aa3b, v110
	v_mul_f32_e32 v119, 0xbfb8aa3b, v111
	v_exp_f32_e32 v118, v118
	v_exp_f32_e32 v119, v119
	v_add_f32_e32 v116, 1.0, v123
	v_add_f32_e32 v117, 1.0, v117
	v_rcp_f32_e32 v116, v116
	v_rcp_f32_e32 v117, v117
	v_add_f32_e32 v118, 1.0, v118
	v_add_f32_e32 v119, 1.0, v119
	v_rcp_f32_e32 v118, v118
	v_rcp_f32_e32 v119, v119
	v_pk_mul_f32 v[108:109], v[108:109], v[116:117]
	v_pk_mul_f32 v[104:105], v[104:105], v[122:123] op_sel_hi:[1,0]
	v_pk_mul_f32 v[100:101], v[100:101], v[108:109]
	v_pk_mul_f32 v[108:109], v[110:111], v[118:119]
	v_mul_f32_e32 v110, 0xbfb8aa3b, v104
	v_exp_f32_e32 v110, v110
	v_pk_mul_f32 v[102:103], v[102:103], v[122:123] op_sel_hi:[1,0]
	v_pk_mul_f32 v[106:107], v[106:107], v[122:123] op_sel_hi:[1,0]
	v_pk_mul_f32 v[102:103], v[102:103], v[108:109]
	v_mul_f32_e32 v108, 0xbfb8aa3b, v105
	v_exp_f32_e32 v109, v108
	v_add_f32_e32 v108, 1.0, v110
	v_mul_f32_e32 v110, 0xbfb8aa3b, v106
	v_mul_f32_e32 v111, 0xbfb8aa3b, v107
	v_exp_f32_e32 v110, v110
	v_exp_f32_e32 v111, v111
	v_add_f32_e32 v109, 1.0, v109
	v_rcp_f32_e32 v108, v108
	v_rcp_f32_e32 v109, v109
	v_add_f32_e32 v110, 1.0, v110
	v_add_f32_e32 v111, 1.0, v111
	v_rcp_f32_e32 v110, v110
	v_rcp_f32_e32 v111, v111
	v_pk_mul_f32 v[96:97], v[96:97], v[122:123] op_sel_hi:[1,0]
	v_pk_mul_f32 v[104:105], v[104:105], v[108:109]
	v_or_b32_e32 v108, 16, v152
	v_pk_mul_f32 v[104:105], v[96:97], v[104:105]
	v_pk_mul_f32 v[96:97], v[98:99], v[122:123] op_sel_hi:[1,0]
	v_pk_mul_f32 v[98:99], v[106:107], v[110:111]
	s_mov_b32 s18, s12
	v_pk_mul_f32 v[106:107], v[96:97], v[98:99]
	v_cvt_pk_bf16_f32 v96, v100, v101
	ds_read2_b32 v[100:101], v153 offset0:32 offset1:48
	v_cvt_pk_bf16_f32 v97, v102, v103
	v_mad_i64_i32 v[102:103], s[20:21], v108, s49, v[112:113]
	v_cvt_pk_bf16_f32 v98, v104, v105
	v_cvt_pk_bf16_f32 v99, v106, v107
	v_lshl_add_u64 v[102:103], v[102:103], 0, v[114:115]
	s_waitcnt lgkmcnt(0)
	v_pk_mul_f32 v[92:93], v[92:93], v[100:101] op_sel_hi:[1,0]
	global_store_dwordx4 v[102:103], v[96:99], off nt
	v_mul_f32_e32 v104, 0xbfb8aa3b, v92
	v_pk_mul_f32 v[94:95], v[94:95], v[100:101] op_sel_hi:[1,0]
	v_mul_f32_e32 v96, 0xbfb8aa3b, v93
	v_exp_f32_e32 v104, v104
	v_exp_f32_e32 v97, v96
	v_mul_f32_e32 v98, 0xbfb8aa3b, v94
	v_mul_f32_e32 v99, 0xbfb8aa3b, v95
	v_exp_f32_e32 v98, v98
	v_exp_f32_e32 v99, v99
	v_add_f32_e32 v96, 1.0, v104
	v_add_f32_e32 v97, 1.0, v97
	v_rcp_f32_e32 v96, v96
	v_rcp_f32_e32 v97, v97
	v_add_f32_e32 v98, 1.0, v98
	v_add_f32_e32 v99, 1.0, v99
	v_rcp_f32_e32 v98, v98
	v_rcp_f32_e32 v99, v99
	v_pk_mul_f32 v[84:85], v[84:85], v[100:101] op_sel_hi:[1,0]
	v_pk_mul_f32 v[92:93], v[92:93], v[96:97]
	v_pk_mul_f32 v[88:89], v[88:89], v[100:101] op_sel_hi:[1,0]
	v_pk_mul_f32 v[84:85], v[84:85], v[92:93]
	v_pk_mul_f32 v[92:93], v[94:95], v[98:99]
	v_mul_f32_e32 v94, 0xbfb8aa3b, v88
	v_exp_f32_e32 v94, v94
	v_pk_mul_f32 v[86:87], v[86:87], v[100:101] op_sel_hi:[1,0]
	v_pk_mul_f32 v[90:91], v[90:91], v[100:101] op_sel_hi:[1,0]
	v_pk_mul_f32 v[86:87], v[86:87], v[92:93]
	v_mul_f32_e32 v92, 0xbfb8aa3b, v89
	v_exp_f32_e32 v93, v92
	v_add_f32_e32 v92, 1.0, v94
	v_mul_f32_e32 v94, 0xbfb8aa3b, v90
	v_mul_f32_e32 v95, 0xbfb8aa3b, v91
	v_exp_f32_e32 v94, v94
	v_exp_f32_e32 v95, v95
	v_add_f32_e32 v93, 1.0, v93
	v_rcp_f32_e32 v92, v92
	v_rcp_f32_e32 v93, v93
	v_add_f32_e32 v94, 1.0, v94
	v_add_f32_e32 v95, 1.0, v95
	v_rcp_f32_e32 v94, v94
	v_rcp_f32_e32 v95, v95
	v_pk_mul_f32 v[80:81], v[80:81], v[100:101] op_sel_hi:[1,0]
	v_pk_mul_f32 v[88:89], v[88:89], v[92:93]
	v_or_b32_e32 v92, 32, v152
	v_pk_mul_f32 v[88:89], v[80:81], v[88:89]
	v_pk_mul_f32 v[80:81], v[82:83], v[100:101] op_sel_hi:[1,0]
	v_pk_mul_f32 v[82:83], v[90:91], v[94:95]
	s_mov_b64 s[26:27], s[16:17]
	v_pk_mul_f32 v[90:91], v[80:81], v[82:83]
	v_cvt_pk_bf16_f32 v81, v86, v87
	v_mov_b32_e32 v86, v101
	v_pk_mul_f32 v[76:77], v[76:77], v[86:87] op_sel_hi:[1,0]
	v_cvt_pk_bf16_f32 v80, v84, v85
	v_mul_f32_e32 v87, 0xbfb8aa3b, v76
	v_exp_f32_e32 v87, v87
	v_mad_i64_i32 v[84:85], s[20:21], v92, s49, v[112:113]
	v_cvt_pk_bf16_f32 v82, v88, v89
	v_cvt_pk_bf16_f32 v83, v90, v91
	v_lshl_add_u64 v[84:85], v[84:85], 0, v[114:115]
	global_store_dwordx4 v[84:85], v[80:83], off nt
	v_pk_mul_f32 v[78:79], v[78:79], v[86:87] op_sel_hi:[1,0]
	v_pk_mul_f32 v[68:69], v[68:69], v[86:87] op_sel_hi:[1,0]
	v_mul_f32_e32 v80, 0xbfb8aa3b, v77
	v_exp_f32_e32 v81, v80
	v_mul_f32_e32 v82, 0xbfb8aa3b, v78
	v_mul_f32_e32 v83, 0xbfb8aa3b, v79
	v_exp_f32_e32 v82, v82
	v_exp_f32_e32 v83, v83
	v_add_f32_e32 v80, 1.0, v87
	v_add_f32_e32 v81, 1.0, v81
	v_rcp_f32_e32 v80, v80
	v_rcp_f32_e32 v81, v81
	v_add_f32_e32 v82, 1.0, v82
	v_add_f32_e32 v83, 1.0, v83
	v_rcp_f32_e32 v82, v82
	v_rcp_f32_e32 v83, v83
	v_pk_mul_f32 v[76:77], v[76:77], v[80:81]
	v_pk_mul_f32 v[72:73], v[72:73], v[86:87] op_sel_hi:[1,0]
	v_pk_mul_f32 v[68:69], v[68:69], v[76:77]
	v_pk_mul_f32 v[76:77], v[78:79], v[82:83]
	v_mul_f32_e32 v78, 0xbfb8aa3b, v72
	v_exp_f32_e32 v78, v78
	v_pk_mul_f32 v[70:71], v[70:71], v[86:87] op_sel_hi:[1,0]
	v_pk_mul_f32 v[74:75], v[74:75], v[86:87] op_sel_hi:[1,0]
	v_pk_mul_f32 v[70:71], v[70:71], v[76:77]
	v_mul_f32_e32 v76, 0xbfb8aa3b, v73
	v_exp_f32_e32 v77, v76
	v_add_f32_e32 v76, 1.0, v78
	v_mul_f32_e32 v78, 0xbfb8aa3b, v74
	v_mul_f32_e32 v79, 0xbfb8aa3b, v75
	v_exp_f32_e32 v78, v78
	v_exp_f32_e32 v79, v79
	v_add_f32_e32 v77, 1.0, v77
	v_rcp_f32_e32 v76, v76
	v_rcp_f32_e32 v77, v77
	v_add_f32_e32 v78, 1.0, v78
	v_add_f32_e32 v79, 1.0, v79
	v_rcp_f32_e32 v78, v78
	v_rcp_f32_e32 v79, v79
	v_pk_mul_f32 v[64:65], v[64:65], v[86:87] op_sel_hi:[1,0]
	v_pk_mul_f32 v[72:73], v[72:73], v[76:77]
	v_or_b32_e32 v76, 48, v152
	v_pk_mul_f32 v[72:73], v[64:65], v[72:73]
	v_pk_mul_f32 v[64:65], v[66:67], v[86:87] op_sel_hi:[1,0]
	v_pk_mul_f32 v[66:67], v[74:75], v[78:79]
	s_mov_b32 s51, s50
	v_pk_mul_f32 v[74:75], v[64:65], v[66:67]
	v_cvt_pk_bf16_f32 v64, v68, v69
	ds_read2_b32 v[68:69], v153 offset0:128 offset1:144
	v_cvt_pk_bf16_f32 v65, v70, v71
	v_mad_i64_i32 v[70:71], s[20:21], v76, s49, v[112:113]
	v_cvt_pk_bf16_f32 v66, v72, v73
	v_cvt_pk_bf16_f32 v67, v74, v75
	v_lshl_add_u64 v[70:71], v[70:71], 0, v[114:115]
	s_waitcnt lgkmcnt(0)
	v_pk_mul_f32 v[60:61], v[60:61], v[68:69] op_sel_hi:[1,0]
	global_store_dwordx4 v[70:71], v[64:67], off nt
	v_pk_mul_f32 v[62:63], v[62:63], v[68:69] op_sel_hi:[1,0]
	v_pk_mul_f32 v[52:53], v[52:53], v[68:69] op_sel_hi:[1,0]
	v_mul_f32_e32 v64, 0xbfb8aa3b, v60
	v_mul_f32_e32 v65, 0xbfb8aa3b, v61
	v_exp_f32_e32 v64, v64
	v_exp_f32_e32 v65, v65
	v_mul_f32_e32 v66, 0xbfb8aa3b, v62
	v_mul_f32_e32 v67, 0xbfb8aa3b, v63
	v_exp_f32_e32 v66, v66
	v_exp_f32_e32 v67, v67
	v_add_f32_e32 v64, 1.0, v64
	v_add_f32_e32 v65, 1.0, v65
	v_rcp_f32_e32 v64, v64
	v_rcp_f32_e32 v65, v65
	v_add_f32_e32 v66, 1.0, v66
	v_add_f32_e32 v67, 1.0, v67
	v_rcp_f32_e32 v66, v66
	v_rcp_f32_e32 v67, v67
	v_pk_mul_f32 v[60:61], v[60:61], v[64:65]
	v_pk_mul_f32 v[56:57], v[56:57], v[68:69] op_sel_hi:[1,0]
	v_pk_mul_f32 v[52:53], v[52:53], v[60:61]
	v_pk_mul_f32 v[60:61], v[62:63], v[66:67]
	v_mul_f32_e32 v62, 0xbfb8aa3b, v56
	v_exp_f32_e32 v62, v62
	v_pk_mul_f32 v[54:55], v[54:55], v[68:69] op_sel_hi:[1,0]
	v_pk_mul_f32 v[58:59], v[58:59], v[68:69] op_sel_hi:[1,0]
	v_pk_mul_f32 v[54:55], v[54:55], v[60:61]
	v_mul_f32_e32 v60, 0xbfb8aa3b, v57
	v_exp_f32_e32 v61, v60
	v_add_f32_e32 v60, 1.0, v62
	v_mul_f32_e32 v62, 0xbfb8aa3b, v58
	v_mul_f32_e32 v63, 0xbfb8aa3b, v59
	v_exp_f32_e32 v62, v62
	v_exp_f32_e32 v63, v63
	v_add_f32_e32 v61, 1.0, v61
	v_rcp_f32_e32 v60, v60
	v_rcp_f32_e32 v61, v61
	v_add_f32_e32 v62, 1.0, v62
	v_add_f32_e32 v63, 1.0, v63
	v_rcp_f32_e32 v62, v62
	v_rcp_f32_e32 v63, v63
	v_pk_mul_f32 v[48:49], v[48:49], v[68:69] op_sel_hi:[1,0]
	v_pk_mul_f32 v[56:57], v[56:57], v[60:61]
	v_add_u32_e32 v70, 0x80, v152
	v_pk_mul_f32 v[56:57], v[48:49], v[56:57]
	v_pk_mul_f32 v[48:49], v[50:51], v[68:69] op_sel_hi:[1,0]
	v_pk_mul_f32 v[50:51], v[58:59], v[62:63]
	s_nop 0
	v_pk_mul_f32 v[58:59], v[48:49], v[50:51]
	v_cvt_pk_bf16_f32 v49, v54, v55
	v_mov_b32_e32 v54, v69
	v_pk_mul_f32 v[44:45], v[44:45], v[54:55] op_sel_hi:[1,0]
	v_cvt_pk_bf16_f32 v48, v52, v53
	v_mul_f32_e32 v55, 0xbfb8aa3b, v44
	v_exp_f32_e32 v55, v55
	v_mad_i64_i32 v[52:53], s[20:21], v70, s49, v[112:113]
	v_cvt_pk_bf16_f32 v50, v56, v57
	v_cvt_pk_bf16_f32 v51, v58, v59
	v_lshl_add_u64 v[52:53], v[52:53], 0, v[114:115]
	global_store_dwordx4 v[52:53], v[48:51], off nt
	v_pk_mul_f32 v[46:47], v[46:47], v[54:55] op_sel_hi:[1,0]
	v_pk_mul_f32 v[36:37], v[36:37], v[54:55] op_sel_hi:[1,0]
	v_mul_f32_e32 v48, 0xbfb8aa3b, v45
	v_exp_f32_e32 v49, v48
	v_mul_f32_e32 v50, 0xbfb8aa3b, v46
	v_mul_f32_e32 v51, 0xbfb8aa3b, v47
	v_exp_f32_e32 v50, v50
	v_exp_f32_e32 v51, v51
	v_add_f32_e32 v48, 1.0, v55
	v_add_f32_e32 v49, 1.0, v49
	v_rcp_f32_e32 v48, v48
	v_rcp_f32_e32 v49, v49
	v_add_f32_e32 v50, 1.0, v50
	v_add_f32_e32 v51, 1.0, v51
	v_rcp_f32_e32 v50, v50
	v_rcp_f32_e32 v51, v51
	v_pk_mul_f32 v[44:45], v[44:45], v[48:49]
	v_pk_mul_f32 v[40:41], v[40:41], v[54:55] op_sel_hi:[1,0]
	v_pk_mul_f32 v[36:37], v[36:37], v[44:45]
	v_pk_mul_f32 v[44:45], v[46:47], v[50:51]
	v_mul_f32_e32 v46, 0xbfb8aa3b, v40
	v_exp_f32_e32 v46, v46
	v_pk_mul_f32 v[38:39], v[38:39], v[54:55] op_sel_hi:[1,0]
	v_pk_mul_f32 v[42:43], v[42:43], v[54:55] op_sel_hi:[1,0]
	v_pk_mul_f32 v[38:39], v[38:39], v[44:45]
	v_mul_f32_e32 v44, 0xbfb8aa3b, v41
	v_exp_f32_e32 v45, v44
	v_add_f32_e32 v44, 1.0, v46
	v_mul_f32_e32 v46, 0xbfb8aa3b, v42
	v_mul_f32_e32 v47, 0xbfb8aa3b, v43
	v_exp_f32_e32 v46, v46
	v_exp_f32_e32 v47, v47
	v_add_f32_e32 v45, 1.0, v45
	v_rcp_f32_e32 v44, v44
	v_rcp_f32_e32 v45, v45
	v_add_f32_e32 v46, 1.0, v46
	v_add_f32_e32 v47, 1.0, v47
	v_rcp_f32_e32 v46, v46
	v_rcp_f32_e32 v47, v47
	v_pk_mul_f32 v[32:33], v[32:33], v[54:55] op_sel_hi:[1,0]
	v_pk_mul_f32 v[40:41], v[40:41], v[44:45]
	v_add_u32_e32 v44, 0x90, v152
	v_pk_mul_f32 v[40:41], v[32:33], v[40:41]
	v_pk_mul_f32 v[32:33], v[34:35], v[54:55] op_sel_hi:[1,0]
	v_pk_mul_f32 v[34:35], v[42:43], v[46:47]
	s_nop 0
	v_pk_mul_f32 v[42:43], v[32:33], v[34:35]
	v_cvt_pk_bf16_f32 v32, v36, v37
	ds_read2_b32 v[36:37], v153 offset0:160 offset1:176
	v_cvt_pk_bf16_f32 v33, v38, v39
	v_mad_i64_i32 v[38:39], s[20:21], v44, s49, v[112:113]
	v_cvt_pk_bf16_f32 v34, v40, v41
	v_cvt_pk_bf16_f32 v35, v42, v43
	v_lshl_add_u64 v[38:39], v[38:39], 0, v[114:115]
	s_waitcnt lgkmcnt(0)
	v_pk_mul_f32 v[28:29], v[28:29], v[36:37] op_sel_hi:[1,0]
	global_store_dwordx4 v[38:39], v[32:35], off nt
	v_mul_f32_e32 v40, 0xbfb8aa3b, v28
	v_pk_mul_f32 v[30:31], v[30:31], v[36:37] op_sel_hi:[1,0]
	v_mul_f32_e32 v32, 0xbfb8aa3b, v29
	v_exp_f32_e32 v40, v40
	v_exp_f32_e32 v33, v32
	v_mul_f32_e32 v34, 0xbfb8aa3b, v30
	v_mul_f32_e32 v35, 0xbfb8aa3b, v31
	v_exp_f32_e32 v34, v34
	v_exp_f32_e32 v35, v35
	v_add_f32_e32 v32, 1.0, v40
	v_add_f32_e32 v33, 1.0, v33
	v_rcp_f32_e32 v32, v32
	v_rcp_f32_e32 v33, v33
	v_add_f32_e32 v34, 1.0, v34
	v_add_f32_e32 v35, 1.0, v35
	v_rcp_f32_e32 v34, v34
	v_rcp_f32_e32 v35, v35
	v_pk_mul_f32 v[20:21], v[20:21], v[36:37] op_sel_hi:[1,0]
	v_pk_mul_f32 v[28:29], v[28:29], v[32:33]
	v_pk_mul_f32 v[24:25], v[24:25], v[36:37] op_sel_hi:[1,0]
	v_pk_mul_f32 v[20:21], v[20:21], v[28:29]
	v_pk_mul_f32 v[28:29], v[30:31], v[34:35]
	v_mul_f32_e32 v30, 0xbfb8aa3b, v24
	v_exp_f32_e32 v30, v30
	v_pk_mul_f32 v[22:23], v[22:23], v[36:37] op_sel_hi:[1,0]
	v_pk_mul_f32 v[26:27], v[26:27], v[36:37] op_sel_hi:[1,0]
	v_pk_mul_f32 v[22:23], v[22:23], v[28:29]
	v_mul_f32_e32 v28, 0xbfb8aa3b, v25
	v_exp_f32_e32 v29, v28
	v_add_f32_e32 v28, 1.0, v30
	v_mul_f32_e32 v30, 0xbfb8aa3b, v26
	v_mul_f32_e32 v31, 0xbfb8aa3b, v27
	v_exp_f32_e32 v30, v30
	v_exp_f32_e32 v31, v31
	v_add_f32_e32 v29, 1.0, v29
	v_rcp_f32_e32 v28, v28
	v_rcp_f32_e32 v29, v29
	v_add_f32_e32 v30, 1.0, v30
	v_add_f32_e32 v31, 1.0, v31
	v_rcp_f32_e32 v30, v30
	v_rcp_f32_e32 v31, v31
	v_pk_mul_f32 v[16:17], v[16:17], v[36:37] op_sel_hi:[1,0]
	v_pk_mul_f32 v[24:25], v[24:25], v[28:29]
	v_add_u32_e32 v28, 0xa0, v152
	v_pk_mul_f32 v[24:25], v[16:17], v[24:25]
	v_pk_mul_f32 v[16:17], v[18:19], v[36:37] op_sel_hi:[1,0]
	v_pk_mul_f32 v[18:19], v[26:27], v[30:31]
	s_nop 0
	v_pk_mul_f32 v[26:27], v[16:17], v[18:19]
	v_cvt_pk_bf16_f32 v17, v22, v23
	v_mov_b32_e32 v22, v37
	v_pk_mul_f32 v[12:13], v[12:13], v[22:23] op_sel_hi:[1,0]
	v_cvt_pk_bf16_f32 v16, v20, v21
	v_mul_f32_e32 v23, 0xbfb8aa3b, v12
	v_exp_f32_e32 v23, v23
	v_mad_i64_i32 v[20:21], s[20:21], v28, s49, v[112:113]
	v_cvt_pk_bf16_f32 v18, v24, v25
	v_cvt_pk_bf16_f32 v19, v26, v27
	v_lshl_add_u64 v[20:21], v[20:21], 0, v[114:115]
	global_store_dwordx4 v[20:21], v[16:19], off nt
	v_pk_mul_f32 v[14:15], v[14:15], v[22:23] op_sel_hi:[1,0]
	v_pk_mul_f32 v[4:5], v[4:5], v[22:23] op_sel_hi:[1,0]
	v_mul_f32_e32 v16, 0xbfb8aa3b, v13
	v_exp_f32_e32 v17, v16
	v_mul_f32_e32 v18, 0xbfb8aa3b, v14
	v_mul_f32_e32 v19, 0xbfb8aa3b, v15
	v_exp_f32_e32 v18, v18
	v_exp_f32_e32 v19, v19
	v_add_f32_e32 v16, 1.0, v23
	v_add_f32_e32 v17, 1.0, v17
	v_rcp_f32_e32 v16, v16
	v_rcp_f32_e32 v17, v17
	v_add_f32_e32 v18, 1.0, v18
	v_add_f32_e32 v19, 1.0, v19
	v_rcp_f32_e32 v18, v18
	v_rcp_f32_e32 v19, v19
	v_pk_mul_f32 v[12:13], v[12:13], v[16:17]
	v_pk_mul_f32 v[8:9], v[8:9], v[22:23] op_sel_hi:[1,0]
	v_pk_mul_f32 v[4:5], v[4:5], v[12:13]
	v_pk_mul_f32 v[12:13], v[14:15], v[18:19]
	v_mul_f32_e32 v14, 0xbfb8aa3b, v8
	v_exp_f32_e32 v14, v14
	v_pk_mul_f32 v[6:7], v[6:7], v[22:23] op_sel_hi:[1,0]
	v_pk_mul_f32 v[10:11], v[10:11], v[22:23] op_sel_hi:[1,0]
	v_pk_mul_f32 v[6:7], v[6:7], v[12:13]
	v_mul_f32_e32 v12, 0xbfb8aa3b, v9
	v_exp_f32_e32 v13, v12
	v_add_f32_e32 v12, 1.0, v14
	v_mul_f32_e32 v14, 0xbfb8aa3b, v10
	v_mul_f32_e32 v15, 0xbfb8aa3b, v11
	v_exp_f32_e32 v14, v14
	v_exp_f32_e32 v15, v15
	v_add_f32_e32 v13, 1.0, v13
	v_rcp_f32_e32 v12, v12
	v_rcp_f32_e32 v13, v13
	v_add_f32_e32 v14, 1.0, v14
	v_add_f32_e32 v15, 1.0, v15
	v_rcp_f32_e32 v14, v14
	v_rcp_f32_e32 v15, v15
	v_pk_mul_f32 v[0:1], v[0:1], v[22:23] op_sel_hi:[1,0]
	v_pk_mul_f32 v[8:9], v[8:9], v[12:13]
	v_add_u32_e32 v12, 0xb0, v152
	v_pk_mul_f32 v[8:9], v[0:1], v[8:9]
	v_pk_mul_f32 v[0:1], v[2:3], v[22:23] op_sel_hi:[1,0]
	v_pk_mul_f32 v[2:3], v[10:11], v[14:15]
	s_nop 0
	v_pk_mul_f32 v[10:11], v[0:1], v[2:3]
	v_cvt_pk_bf16_f32 v0, v4, v5
	v_mad_i64_i32 v[4:5], s[20:21], v12, s49, v[112:113]
	v_cvt_pk_bf16_f32 v1, v6, v7
	v_cvt_pk_bf16_f32 v2, v8, v9
	v_cvt_pk_bf16_f32 v3, v10, v11
	v_lshl_add_u64 v[4:5], v[4:5], 0, v[114:115]
	s_mov_b64 s[20:21], s[14:15]
	global_store_dwordx4 v[4:5], v[0:3], off nt
	s_cbranch_vccz .LBB0_128
	s_waitcnt vmcnt(0)
	s_cmpk_gt_u32 s37, 0xff
	s_cbranch_scc1 .LBB0_135

.LBB0_236:
	s_andn2_b64 vcc, exec, s[4:5]
	s_cbranch_vccnz .LBB0_268
	v_ashrrev_i32_e32 v1, 31, v8
	v_lshrrev_b32_e32 v1, 26, v1
	v_add_u32_e32 v1, v8, v1
	v_ashrrev_i32_e32 v9, 6, v1
	v_bfe_i32 v1, v8, 27, 1
	v_lshlrev_b32_e32 v0, 4, v8
	v_lshrrev_b32_e32 v1, 22, v1
	v_add_u32_e32 v1, v0, v1
	v_and_b32_e32 v1, 0xfffffc00, v1
	v_sub_u32_e32 v1, v0, v1
	v_lshrrev_b32_e32 v2, 4, v1
	v_bitop3_b32 v1, v2, v1, 32 bitop3:0x6c
	v_ashrrev_i32_e32 v3, 31, v1
	v_lshrrev_b32_e32 v3, 26, v3
	v_lshlrev_b32_e32 v2, 3, v9
	v_add_u32_e32 v3, v1, v3
	v_and_b32_e32 v2, -16, v2
	v_ashrrev_i32_e32 v11, 6, v3
	v_and_b32_e32 v3, 0xc0, v3
	v_add_u32_e32 v2, v11, v2
	v_lshlrev_b32_e32 v4, 5, v9
	v_sub_u32_e32 v1, v1, v3
	v_mov_b32_e32 v3, 1
	v_and_b32_e32 v10, 32, v4
	v_ashrrev_i16_sdwa v1, v3, sext(v1) dst_sel:DWORD dst_unused:UNUSED_PAD src0_sel:DWORD src1_sel:BYTE_0
	v_lshlrev_b32_e32 v4, 1, v2
	v_lshrrev_b32_e32 v5, 2, v2
	v_and_b32_e32 v6, 3, v11
	s_mov_b32 s5, 0xffffe0
	v_bfe_i32 v12, v1, 0, 16
	v_and_b32_e32 v4, 24, v4
	v_and_b32_e32 v5, 4, v5
	v_and_or_b32 v6, v2, s5, v6
	s_movk_i32 s8, 0xb00
	v_add_u32_e32 v1, v10, v12
	v_or3_b32 v4, v6, v5, v4
	v_mul_lo_u32 v2, v2, s8
	v_add_lshl_u32 v128, v1, v2, 1
	v_mul_u32_u24_e32 v2, 0xb00, v4
	v_add_u32_e32 v0, 0x2000, v0
	v_add_lshl_u32 v130, v2, v1, 1
	v_ashrrev_i32_e32 v1, 31, v0
	v_lshrrev_b32_e32 v1, 22, v1
	v_add_u32_e32 v1, v0, v1
	v_ashrrev_i32_e32 v13, 10, v1
	v_mul_i32_i24_e32 v1, 0x400, v13
	v_sub_u32_e32 v0, v0, v1
	v_lshrrev_b32_e32 v1, 4, v0
	v_bitop3_b32 v0, v1, v0, 32 bitop3:0x6c
	v_ashrrev_i32_e32 v2, 31, v0
	s_add_u32 s36, s6, 0x9800000
	v_lshrrev_b32_e32 v2, 26, v2
	s_addc_u32 s37, s7, 0
	v_lshlrev_b32_e32 v1, 3, v13
	v_add_u32_e32 v2, v0, v2
	s_add_u32 s38, s6, 0xb00000
	v_and_b32_e32 v1, -16, v1
	v_ashrrev_i32_e32 v14, 6, v2
	v_lshlrev_b32_e32 v4, 5, v13
	s_addc_u32 s39, s7, 0
	s_ashr_i32 s4, s35, 6
	v_add_u32_e32 v1, v14, v1
	v_and_b32_e32 v15, 32, v4
	v_and_b32_e32 v2, 0xc0, v2
	v_and_b32_e32 v4, 3, v14
	v_sub_u32_e32 v0, v0, v2
	v_and_or_b32 v4, v1, s5, v4
	s_ashr_i32 s5, s35, 8
	s_lshl_b32 s40, s4, 10
	s_mul_i32 s13, s12, 0x160000
	v_ashrrev_i16_sdwa v0, v3, sext(v0) dst_sel:DWORD dst_unused:UNUSED_PAD src0_sel:DWORD src1_sel:BYTE_0
	v_lshlrev_b32_e32 v2, 1, v1
	v_lshrrev_b32_e32 v3, 2, v1
	s_mul_hi_i32 s11, s12, 0x160000
	s_add_u32 s26, s38, s13
	v_bfe_i32 v16, v0, 0, 16
	v_and_b32_e32 v2, 24, v2
	v_and_b32_e32 v3, 4, v3
	s_addc_u32 s27, s39, s11
	s_add_i32 s41, s40, 0
	v_add_u32_e32 v0, v15, v16
	v_or3_b32 v2, v4, v3, v2
	v_mul_lo_u32 v1, v1, s8
	s_add_i32 m0, s41, 0x10000
	v_add_lshl_u32 v132, v0, v1, 1
	v_mul_u32_u24_e32 v1, 0xb00, v2
	s_mul_i32 s10, s56, 0x160000
	global_load_lds_dwordx4 v130, s[26:27]
	s_add_i32 m0, s41, 0x12000
	v_add_lshl_u32 v134, v1, v0, 1
	s_mul_hi_i32 s9, s56, 0x160000
	s_add_u32 s20, s36, s10
	global_load_lds_dwordx4 v134, s[26:27]
	s_addc_u32 s21, s37, s9
	s_mov_b32 m0, s41
	s_add_i32 s42, s41, 0x2000
	global_load_lds_dwordx4 v128, s[20:21]
	s_mov_b32 m0, s42
	s_add_u32 s10, s26, 0xb0000
	global_load_lds_dwordx4 v132, s[20:21]
	s_addc_u32 s11, s27, 0
	s_add_i32 m0, s41, 0x14000
	v_mov_b32_e32 v131, 0
	global_load_lds_dwordx4 v130, s[10:11]
	s_add_i32 m0, s41, 0x16000
	v_mov_b32_e32 v135, v131
	global_load_lds_dwordx4 v134, s[10:11]
	s_add_u32 s10, s20, 0xb0000
	s_addc_u32 s11, s21, 0
	s_add_i32 s43, s41, 0x4000
	s_mov_b32 m0, s43
	s_add_i32 s44, s41, 0x6000
	global_load_lds_dwordx4 v128, s[10:11]
	s_mov_b32 m0, s44
	v_mov_b32_e32 v129, v131
	global_load_lds_dwordx4 v132, s[10:11]
	v_mov_b32_e32 v133, v131
	s_mov_b32 s13, 0
	v_lshl_add_u64 v[6:7], s[26:27], 0, v[130:131]
	v_lshl_add_u64 v[4:5], s[26:27], 0, v[134:135]
	v_lshl_add_u64 v[2:3], s[20:21], 0, v[128:129]
	s_cmp_lg_u32 s5, 1
	v_lshl_add_u64 v[0:1], s[20:21], 0, v[132:133]
	s_cbranch_scc1 .LBB0_239
.LBB0_239:
	s_add_u32 s14, s6, 0x3800000
	s_addc_u32 s15, s7, 0
	s_add_u32 s16, s6, 0x2d00000
	s_mov_b64 s[18:19], 0x80
	s_addc_u32 s17, s7, 0
	s_and_b32 s45, s4, 3
	s_add_i32 m0, s41, 0x18000
	v_lshl_add_u64 v[6:7], v[6:7], 0, s[18:19]
	s_lshl_b32 s4, s5, 13
	s_lshl_b32 s9, s45, 12
	s_waitcnt vmcnt(4)
	s_barrier
	global_load_lds_dwordx4 v[6:7], off
	v_lshl_add_u64 v[4:5], v[4:5], 0, s[18:19]
	s_add_i32 m0, s41, 0x1a000
	s_add_i32 s46, s41, 0x8000
	s_add_i32 s47, s41, 0xa000
	global_load_lds_dwordx4 v[4:5], off
	v_lshl_add_u64 v[2:3], v[2:3], 0, s[18:19]
	s_mov_b32 m0, s46
	s_add_u32 s6, s26, 0xb0080
	global_load_lds_dwordx4 v[2:3], off
	v_lshl_add_u64 v[0:1], v[0:1], 0, s[18:19]
	s_mov_b32 m0, s47
	s_addc_u32 s7, s27, 0
	global_load_lds_dwordx4 v[0:1], off
	s_add_i32 m0, s41, 0x1c000
	v_lshl_add_u64 v[0:1], s[6:7], 0, v[130:131]
	global_load_lds_dwordx4 v[0:1], off
	v_lshl_add_u64 v[0:1], s[6:7], 0, v[134:135]
	s_add_i32 m0, s41, 0x1e000
	s_mov_b64 s[6:7], 0xb0080
	global_load_lds_dwordx4 v[0:1], off
	v_bfe_u32 v0, v8, 4, 2
	v_and_b32_e32 v1, 15, v8
	v_lshlrev_b32_e32 v3, 4, v0
	v_lshl_or_b32 v148, s5, 6, v1
	v_lshl_or_b32 v1, v1, 6, v3
	v_lshlrev_b32_e32 v3, 2, v8
	v_and_b32_e32 v3, 32, v3
	v_lshlrev_b32_e32 v2, 3, v0
	v_bitop3_b32 v4, v1, s4, v3 bitop3:0xde
	v_bitop3_b32 v149, s9, v1, v3 bitop3:0xf6
	v_cmp_eq_u32_e64 s[4:5], 0, v0
	v_lshrrev_b32_e32 v1, 1, v9
	v_mul_lo_u32 v0, v11, s8
	s_mov_b32 s9, 0xb000
	v_mad_u64_u32 v[0:1], s[10:11], v1, s9, v[0:1]
	v_or_b32_e32 v0, v0, v10
	v_add_lshl_u32 v0, v0, v12, 1
	v_mov_b32_e32 v1, v131
	v_lshl_add_u64 v[136:137], v[0:1], 0, s[6:7]
	v_lshrrev_b32_e32 v1, 1, v13
	v_mul_lo_u32 v0, v14, s8
	v_mad_u64_u32 v[0:1], s[8:9], v1, s9, v[0:1]
	s_waitcnt vmcnt(6)
	v_or_b32_e32 v0, v0, v15
	v_add_lshl_u32 v0, v0, v16, 1
	v_mov_b32_e32 v1, v131
	s_add_i32 s51, 0, 0x10000
	s_add_i32 s52, 0, 0x14000
	v_lshl_or_b32 v150, s45, 5, v2
	s_ashr_i32 s48, s34, 31
	s_ashr_i32 s49, s33, 31
	v_lshl_add_u64 v[138:139], v[0:1], 0, s[6:7]
	v_mov_b64_e32 v[140:141], 0x300
	v_mov_b64_e32 v[142:143], 0x2ff
	s_movk_i32 s50, 0x61
	v_add_u32_e32 v151, s51, v149
	v_add_u32_e32 v152, 0, v4
	v_add_u32_e32 v153, s52, v149
	v_mbcnt_hi_u32_b32 v154, -1, v241
	s_mov_b32 s53, 0
	s_barrier
	s_branch .LBB0_241

.LBB0_247:
	s_add_u32 s57, s26, 0x100
	v_mov_b32_e32 v0, 0
	s_addc_u32 s58, s27, 0
	s_mov_b32 s59, -2
	s_waitcnt lgkmcnt(0)
	v_mov_b32_e32 v1, v0
	v_mov_b32_e32 v2, v0
	v_mov_b32_e32 v3, v0
	v_mov_b32_e32 v4, v0
	v_mov_b32_e32 v5, v0
	v_mov_b32_e32 v6, v0
	v_mov_b32_e32 v7, v0
	v_mov_b32_e32 v16, v0
	v_mov_b32_e32 v17, v0
	v_mov_b32_e32 v18, v0
	v_mov_b32_e32 v19, v0
	v_mov_b32_e32 v20, v0
	v_mov_b32_e32 v21, v0
	v_mov_b32_e32 v22, v0
	v_mov_b32_e32 v23, v0
	v_mov_b32_e32 v32, v0
	v_mov_b32_e32 v33, v0
	v_mov_b32_e32 v34, v0
	v_mov_b32_e32 v35, v0
	v_mov_b32_e32 v36, v0
	v_mov_b32_e32 v37, v0
	v_mov_b32_e32 v38, v0
	v_mov_b32_e32 v39, v0
	v_mov_b32_e32 v48, v0
	v_mov_b32_e32 v49, v0
	v_mov_b32_e32 v50, v0
	v_mov_b32_e32 v51, v0
	v_mov_b32_e32 v52, v0
	v_mov_b32_e32 v53, v0
	v_mov_b32_e32 v54, v0
	v_mov_b32_e32 v55, v0
	v_mov_b32_e32 v8, v0
	v_mov_b32_e32 v9, v0
	v_mov_b32_e32 v10, v0
	v_mov_b32_e32 v11, v0
	v_mov_b32_e32 v12, v0
	v_mov_b32_e32 v13, v0
	v_mov_b32_e32 v14, v0
	v_mov_b32_e32 v15, v0
	v_mov_b32_e32 v24, v0
	v_mov_b32_e32 v25, v0
	v_mov_b32_e32 v26, v0
	v_mov_b32_e32 v27, v0
	v_mov_b32_e32 v28, v0
	v_mov_b32_e32 v29, v0
	v_mov_b32_e32 v30, v0
	v_mov_b32_e32 v31, v0
	v_mov_b32_e32 v40, v0
	v_mov_b32_e32 v41, v0
	v_mov_b32_e32 v42, v0
	v_mov_b32_e32 v43, v0
	v_mov_b32_e32 v44, v0
	v_mov_b32_e32 v45, v0
	v_mov_b32_e32 v46, v0
	v_mov_b32_e32 v47, v0
	v_mov_b32_e32 v56, v0
	v_mov_b32_e32 v57, v0
	v_mov_b32_e32 v58, v0
	v_mov_b32_e32 v59, v0
	v_mov_b32_e32 v60, v0
	v_mov_b32_e32 v61, v0
	v_mov_b32_e32 v62, v0
	v_mov_b32_e32 v63, v0
	v_mov_b32_e32 v64, v0
	v_mov_b32_e32 v65, v0
	v_mov_b32_e32 v66, v0
	v_mov_b32_e32 v67, v0
	v_mov_b32_e32 v68, v0
	v_mov_b32_e32 v69, v0
	v_mov_b32_e32 v70, v0
	v_mov_b32_e32 v71, v0
	v_mov_b32_e32 v80, v0
	v_mov_b32_e32 v81, v0
	v_mov_b32_e32 v82, v0
	v_mov_b32_e32 v83, v0
	v_mov_b32_e32 v84, v0
	v_mov_b32_e32 v85, v0
	v_mov_b32_e32 v86, v0
	v_mov_b32_e32 v87, v0
	v_mov_b32_e32 v96, v0
	v_mov_b32_e32 v97, v0
	v_mov_b32_e32 v98, v0
	v_mov_b32_e32 v99, v0
	v_mov_b32_e32 v100, v0
	v_mov_b32_e32 v101, v0
	v_mov_b32_e32 v102, v0
	v_mov_b32_e32 v103, v0
	v_mov_b32_e32 v112, v0
	v_mov_b32_e32 v113, v0
	v_mov_b32_e32 v114, v0
	v_mov_b32_e32 v115, v0
	v_mov_b32_e32 v116, v0
	v_mov_b32_e32 v117, v0
	v_mov_b32_e32 v118, v0
	v_mov_b32_e32 v119, v0
	v_mov_b32_e32 v72, v0
	v_mov_b32_e32 v73, v0
	v_mov_b32_e32 v74, v0
	v_mov_b32_e32 v75, v0
	v_mov_b32_e32 v76, v0
	v_mov_b32_e32 v77, v0
	v_mov_b32_e32 v78, v0
	v_mov_b32_e32 v79, v0
	v_mov_b32_e32 v88, v0
	v_mov_b32_e32 v89, v0
	v_mov_b32_e32 v90, v0
	v_mov_b32_e32 v91, v0
	v_mov_b32_e32 v92, v0
	v_mov_b32_e32 v93, v0
	v_mov_b32_e32 v94, v0
	v_mov_b32_e32 v95, v0
	v_mov_b32_e32 v104, v0
	v_mov_b32_e32 v105, v0
	v_mov_b32_e32 v106, v0
	v_mov_b32_e32 v107, v0
	v_mov_b32_e32 v108, v0
	v_mov_b32_e32 v109, v0
	v_mov_b32_e32 v110, v0
	v_mov_b32_e32 v111, v0
	v_mov_b32_e32 v120, v0
	v_mov_b32_e32 v121, v0
	v_mov_b32_e32 v122, v0
	v_mov_b32_e32 v123, v0
	v_mov_b32_e32 v124, v0
	v_mov_b32_e32 v125, v0
	v_mov_b32_e32 v126, v0
	v_mov_b32_e32 v127, v0
	s_cmpk_lt_u32 s35, 0x100
	s_cbranch_scc1 .Lg248_noy
	s_barrier
.Lg248_noy:
.LBB0_248:
	ds_read_b128 v[144:147], v151
	ds_read_b128 v[156:159], v151 offset:1024
	ds_read_b128 v[160:163], v151 offset:2048
	ds_read_b128 v[164:167], v151 offset:3072
	s_add_u32 s26, s20, 0x100
	s_addc_u32 s27, s21, 0
	s_cmp_eq_u32 s59, 40
	s_cselect_b32 s31, s9, s27
	s_cselect_b32 s30, s8, s26
	s_cselect_b32 s29, s11, s58
	s_cselect_b32 s28, s10, s57
	s_add_i32 m0, s41, 0xc000
	ds_read_b128 v[168:171], v152
	ds_read_b128 v[172:175], v152 offset:1024
	ds_read_b128 v[176:179], v152 offset:2048
	ds_read_b128 v[180:183], v152 offset:3072
	ds_read_b128 v[184:187], v152 offset:4096
	ds_read_b128 v[188:191], v152 offset:5120
	ds_read_b128 v[192:195], v152 offset:6144
	ds_read_b128 v[196:199], v152 offset:7168
	global_load_lds_dwordx4 v136, s[20:21]
	s_add_i32 m0, s41, 0xe000
	s_nop 0
	global_load_lds_dwordx4 v138, s[20:21]
	s_waitcnt lgkmcnt(8)
	s_barrier
	s_waitcnt lgkmcnt(0)
	s_setprio 1
	s_waitcnt lgkmcnt(0)
	v_mfma_f32_16x16x32_bf16 v[124:127], v[144:147], v[168:171], v[124:127]
	v_mfma_f32_16x16x32_bf16 v[120:123], v[160:163], v[168:171], v[120:123]
	v_mfma_f32_16x16x32_bf16 v[108:111], v[144:147], v[176:179], v[108:111]
	v_mfma_f32_16x16x32_bf16 v[104:107], v[160:163], v[176:179], v[104:107]
	v_mfma_f32_16x16x32_bf16 v[92:95], v[144:147], v[184:187], v[92:95]
	v_mfma_f32_16x16x32_bf16 v[88:91], v[160:163], v[184:187], v[88:91]
	v_mfma_f32_16x16x32_bf16 v[76:79], v[144:147], v[192:195], v[76:79]
	v_mfma_f32_16x16x32_bf16 v[72:75], v[160:163], v[192:195], v[72:75]
	v_mfma_f32_16x16x32_bf16 v[124:127], v[156:159], v[172:175], v[124:127]
	v_mfma_f32_16x16x32_bf16 v[120:123], v[164:167], v[172:175], v[120:123]
	v_mfma_f32_16x16x32_bf16 v[108:111], v[156:159], v[180:183], v[108:111]
	v_mfma_f32_16x16x32_bf16 v[104:107], v[164:167], v[180:183], v[104:107]
	v_mfma_f32_16x16x32_bf16 v[92:95], v[156:159], v[188:191], v[92:95]
	v_mfma_f32_16x16x32_bf16 v[88:91], v[164:167], v[188:191], v[88:91]
	v_mfma_f32_16x16x32_bf16 v[76:79], v[156:159], v[196:199], v[76:79]
	v_mfma_f32_16x16x32_bf16 v[72:75], v[164:167], v[196:199], v[72:75]
	s_setprio 0
	s_barrier
	s_add_i32 s20, s51, s40
	s_add_u32 s80, s28, 0x80
	s_addc_u32 s81, s29, 0
	s_mov_b32 m0, s20
	ds_read_b128 v[200:203], v153
	ds_read_b128 v[204:207], v153 offset:1024
	ds_read_b128 v[208:211], v153 offset:2048
	ds_read_b128 v[212:215], v153 offset:3072
	global_load_lds_dwordx4 v130, s[28:29]
	s_add_i32 m0, s20, 0x2000
	s_nop 0
	global_load_lds_dwordx4 v134, s[28:29]
	s_barrier
	s_waitcnt lgkmcnt(0)
	s_setprio 1
	s_waitcnt lgkmcnt(0)
	v_mfma_f32_16x16x32_bf16 v[116:119], v[200:203], v[168:171], v[116:119]
	v_mfma_f32_16x16x32_bf16 v[112:115], v[208:211], v[168:171], v[112:115]
	v_mfma_f32_16x16x32_bf16 v[100:103], v[200:203], v[176:179], v[100:103]
	v_mfma_f32_16x16x32_bf16 v[96:99], v[208:211], v[176:179], v[96:99]
	v_mfma_f32_16x16x32_bf16 v[84:87], v[200:203], v[184:187], v[84:87]
	v_mfma_f32_16x16x32_bf16 v[80:83], v[208:211], v[184:187], v[80:83]
	v_mfma_f32_16x16x32_bf16 v[68:71], v[200:203], v[192:195], v[68:71]
	v_mfma_f32_16x16x32_bf16 v[64:67], v[208:211], v[192:195], v[64:67]
	v_mfma_f32_16x16x32_bf16 v[116:119], v[204:207], v[172:175], v[116:119]
	v_mfma_f32_16x16x32_bf16 v[112:115], v[212:215], v[172:175], v[112:115]
	v_mfma_f32_16x16x32_bf16 v[100:103], v[204:207], v[180:183], v[100:103]
	v_mfma_f32_16x16x32_bf16 v[96:99], v[212:215], v[180:183], v[96:99]
	v_mfma_f32_16x16x32_bf16 v[84:87], v[204:207], v[188:191], v[84:87]
	v_mfma_f32_16x16x32_bf16 v[80:83], v[212:215], v[188:191], v[80:83]
	v_mfma_f32_16x16x32_bf16 v[68:71], v[204:207], v[196:199], v[68:71]
	v_mfma_f32_16x16x32_bf16 v[64:67], v[212:215], v[196:199], v[64:67]
	s_setprio 0
	s_mov_b32 m0, s41
	s_add_u32 s82, s30, 0x80
	s_addc_u32 s83, s31, 0
	s_barrier
	ds_read_b128 v[168:171], v152 offset:16384
	ds_read_b128 v[172:175], v152 offset:17408
	ds_read_b128 v[176:179], v152 offset:18432
	ds_read_b128 v[180:183], v152 offset:19456
	ds_read_b128 v[184:187], v152 offset:20480
	ds_read_b128 v[188:191], v152 offset:21504
	ds_read_b128 v[192:195], v152 offset:22528
	ds_read_b128 v[196:199], v152 offset:23552
	global_load_lds_dwordx4 v128, s[30:31]
	s_mov_b32 m0, s42
	s_nop 0
	global_load_lds_dwordx4 v132, s[30:31]
	s_barrier
	s_waitcnt lgkmcnt(0)
	s_setprio 1
	s_waitcnt lgkmcnt(0)
	v_mfma_f32_16x16x32_bf16 v[60:63], v[144:147], v[168:171], v[60:63]
	v_mfma_f32_16x16x32_bf16 v[56:59], v[160:163], v[168:171], v[56:59]
	v_mfma_f32_16x16x32_bf16 v[44:47], v[144:147], v[176:179], v[44:47]
	v_mfma_f32_16x16x32_bf16 v[40:43], v[160:163], v[176:179], v[40:43]
	v_mfma_f32_16x16x32_bf16 v[28:31], v[144:147], v[184:187], v[28:31]
	v_mfma_f32_16x16x32_bf16 v[24:27], v[160:163], v[184:187], v[24:27]
	v_mfma_f32_16x16x32_bf16 v[12:15], v[144:147], v[192:195], v[12:15]
	v_mfma_f32_16x16x32_bf16 v[8:11], v[160:163], v[192:195], v[8:11]
	v_mfma_f32_16x16x32_bf16 v[60:63], v[156:159], v[172:175], v[60:63]
	v_mfma_f32_16x16x32_bf16 v[56:59], v[164:167], v[172:175], v[56:59]
	v_mfma_f32_16x16x32_bf16 v[44:47], v[156:159], v[180:183], v[44:47]
	v_mfma_f32_16x16x32_bf16 v[40:43], v[164:167], v[180:183], v[40:43]
	v_mfma_f32_16x16x32_bf16 v[28:31], v[156:159], v[188:191], v[28:31]
	v_mfma_f32_16x16x32_bf16 v[24:27], v[164:167], v[188:191], v[24:27]
	v_mfma_f32_16x16x32_bf16 v[12:15], v[156:159], v[196:199], v[12:15]
	v_mfma_f32_16x16x32_bf16 v[8:11], v[164:167], v[196:199], v[8:11]
	s_setprio 0
	s_barrier
	s_add_u32 s20, s28, 0xb0000
	s_addc_u32 s21, s29, 0
	s_add_i32 s60, s52, s40
	s_mov_b32 m0, s60
	s_nop 0
	global_load_lds_dwordx4 v130, s[20:21]
	s_add_i32 m0, s60, 0x2000
	s_nop 0
	global_load_lds_dwordx4 v134, s[20:21]
	s_waitcnt vmcnt(6)
	s_barrier
	s_setprio 1
	v_mfma_f32_16x16x32_bf16 v[52:55], v[200:203], v[168:171], v[52:55]
	v_mfma_f32_16x16x32_bf16 v[48:51], v[208:211], v[168:171], v[48:51]
	v_mfma_f32_16x16x32_bf16 v[36:39], v[200:203], v[176:179], v[36:39]
	v_mfma_f32_16x16x32_bf16 v[32:35], v[208:211], v[176:179], v[32:35]
	v_mfma_f32_16x16x32_bf16 v[20:23], v[200:203], v[184:187], v[20:23]
	v_mfma_f32_16x16x32_bf16 v[16:19], v[208:211], v[184:187], v[16:19]
	v_mfma_f32_16x16x32_bf16 v[4:7], v[200:203], v[192:195], v[4:7]
	v_mfma_f32_16x16x32_bf16 v[0:3], v[208:211], v[192:195], v[0:3]
	v_mfma_f32_16x16x32_bf16 v[52:55], v[204:207], v[172:175], v[52:55]
	v_mfma_f32_16x16x32_bf16 v[48:51], v[212:215], v[172:175], v[48:51]
	v_mfma_f32_16x16x32_bf16 v[36:39], v[204:207], v[180:183], v[36:39]
	v_mfma_f32_16x16x32_bf16 v[32:35], v[212:215], v[180:183], v[32:35]
	v_mfma_f32_16x16x32_bf16 v[20:23], v[204:207], v[188:191], v[20:23]
	v_mfma_f32_16x16x32_bf16 v[16:19], v[212:215], v[188:191], v[16:19]
	v_mfma_f32_16x16x32_bf16 v[4:7], v[204:207], v[196:199], v[4:7]
	v_mfma_f32_16x16x32_bf16 v[0:3], v[212:215], v[196:199], v[0:3]
	s_setprio 0
	s_add_i32 s60, 0, 0x18000
	v_add_u32_e32 v155, s60, v149
	s_barrier
	ds_read_b128 v[144:147], v155
	ds_read_b128 v[156:159], v155 offset:1024
	ds_read_b128 v[160:163], v155 offset:2048
	ds_read_b128 v[164:167], v155 offset:3072
	s_add_u32 s20, s30, 0xb0000
	s_addc_u32 s21, s31, 0
	s_mov_b32 m0, s43
	ds_read_b128 v[168:171], v152 offset:32768
	ds_read_b128 v[172:175], v152 offset:33792
	ds_read_b128 v[176:179], v152 offset:34816
	ds_read_b128 v[180:183], v152 offset:35840
	ds_read_b128 v[184:187], v152 offset:36864
	ds_read_b128 v[188:191], v152 offset:37888
	ds_read_b128 v[192:195], v152 offset:38912
	ds_read_b128 v[196:199], v152 offset:39936
	global_load_lds_dwordx4 v128, s[20:21]
	s_mov_b32 m0, s44
	s_nop 0
	global_load_lds_dwordx4 v132, s[20:21]
	s_waitcnt lgkmcnt(8)
	s_barrier
	s_waitcnt lgkmcnt(0)
	s_setprio 1
	s_waitcnt lgkmcnt(0)
	v_mfma_f32_16x16x32_bf16 v[124:127], v[144:147], v[168:171], v[124:127]
	v_mfma_f32_16x16x32_bf16 v[120:123], v[160:163], v[168:171], v[120:123]
	v_mfma_f32_16x16x32_bf16 v[108:111], v[144:147], v[176:179], v[108:111]
	v_mfma_f32_16x16x32_bf16 v[104:107], v[160:163], v[176:179], v[104:107]
	v_mfma_f32_16x16x32_bf16 v[92:95], v[144:147], v[184:187], v[92:95]
	v_mfma_f32_16x16x32_bf16 v[88:91], v[160:163], v[184:187], v[88:91]
	v_mfma_f32_16x16x32_bf16 v[76:79], v[144:147], v[192:195], v[76:79]
	v_mfma_f32_16x16x32_bf16 v[72:75], v[160:163], v[192:195], v[72:75]
	v_mfma_f32_16x16x32_bf16 v[124:127], v[156:159], v[172:175], v[124:127]
	v_mfma_f32_16x16x32_bf16 v[120:123], v[164:167], v[172:175], v[120:123]
	v_mfma_f32_16x16x32_bf16 v[108:111], v[156:159], v[180:183], v[108:111]
	v_mfma_f32_16x16x32_bf16 v[104:107], v[164:167], v[180:183], v[104:107]
	v_mfma_f32_16x16x32_bf16 v[92:95], v[156:159], v[188:191], v[92:95]
	v_mfma_f32_16x16x32_bf16 v[88:91], v[164:167], v[188:191], v[88:91]
	v_mfma_f32_16x16x32_bf16 v[76:79], v[156:159], v[196:199], v[76:79]
	v_mfma_f32_16x16x32_bf16 v[72:75], v[164:167], v[196:199], v[72:75]
	s_setprio 0
	s_barrier
	s_add_i32 s30, 0, 0x1c000
	s_add_i32 s20, s60, s40
	v_add_u32_e32 v155, s30, v149
	s_mov_b32 m0, s20
	ds_read_b128 v[200:203], v155
	ds_read_b128 v[204:207], v155 offset:1024
	ds_read_b128 v[208:211], v155 offset:2048
	ds_read_b128 v[212:215], v155 offset:3072
	global_load_lds_dwordx4 v130, s[80:81]
	s_add_i32 m0, s20, 0x2000
	s_nop 0
	global_load_lds_dwordx4 v134, s[80:81]
	s_barrier
	s_waitcnt lgkmcnt(0)
	s_setprio 1
	s_waitcnt lgkmcnt(0)
	v_mfma_f32_16x16x32_bf16 v[116:119], v[200:203], v[168:171], v[116:119]
	v_mfma_f32_16x16x32_bf16 v[112:115], v[208:211], v[168:171], v[112:115]
	v_mfma_f32_16x16x32_bf16 v[100:103], v[200:203], v[176:179], v[100:103]
	v_mfma_f32_16x16x32_bf16 v[96:99], v[208:211], v[176:179], v[96:99]
	v_mfma_f32_16x16x32_bf16 v[84:87], v[200:203], v[184:187], v[84:87]
	v_mfma_f32_16x16x32_bf16 v[80:83], v[208:211], v[184:187], v[80:83]
	v_mfma_f32_16x16x32_bf16 v[68:71], v[200:203], v[192:195], v[68:71]
	v_mfma_f32_16x16x32_bf16 v[64:67], v[208:211], v[192:195], v[64:67]
	v_mfma_f32_16x16x32_bf16 v[116:119], v[204:207], v[172:175], v[116:119]
	v_mfma_f32_16x16x32_bf16 v[112:115], v[212:215], v[172:175], v[112:115]
	v_mfma_f32_16x16x32_bf16 v[100:103], v[204:207], v[180:183], v[100:103]
	v_mfma_f32_16x16x32_bf16 v[96:99], v[212:215], v[180:183], v[96:99]
	v_mfma_f32_16x16x32_bf16 v[84:87], v[204:207], v[188:191], v[84:87]
	v_mfma_f32_16x16x32_bf16 v[80:83], v[212:215], v[188:191], v[80:83]
	v_mfma_f32_16x16x32_bf16 v[68:71], v[204:207], v[196:199], v[68:71]
	v_mfma_f32_16x16x32_bf16 v[64:67], v[212:215], v[196:199], v[64:67]
	s_setprio 0
	s_mov_b32 m0, s46
	s_barrier
	ds_read_b128 v[168:171], v152 offset:49152
	ds_read_b128 v[172:175], v152 offset:50176
	ds_read_b128 v[176:179], v152 offset:51200
	ds_read_b128 v[180:183], v152 offset:52224
	ds_read_b128 v[184:187], v152 offset:53248
	ds_read_b128 v[188:191], v152 offset:54272
	ds_read_b128 v[192:195], v152 offset:55296
	ds_read_b128 v[196:199], v152 offset:56320
	global_load_lds_dwordx4 v128, s[82:83]
	s_mov_b32 m0, s47
	s_nop 0
	global_load_lds_dwordx4 v132, s[82:83]
	s_barrier
	s_waitcnt lgkmcnt(0)
	s_setprio 1
	s_waitcnt lgkmcnt(0)
	v_mfma_f32_16x16x32_bf16 v[60:63], v[144:147], v[168:171], v[60:63]
	v_mfma_f32_16x16x32_bf16 v[56:59], v[160:163], v[168:171], v[56:59]
	v_mfma_f32_16x16x32_bf16 v[44:47], v[144:147], v[176:179], v[44:47]
	v_mfma_f32_16x16x32_bf16 v[40:43], v[160:163], v[176:179], v[40:43]
	v_mfma_f32_16x16x32_bf16 v[28:31], v[144:147], v[184:187], v[28:31]
	v_mfma_f32_16x16x32_bf16 v[24:27], v[160:163], v[184:187], v[24:27]
	v_mfma_f32_16x16x32_bf16 v[12:15], v[144:147], v[192:195], v[12:15]
	v_mfma_f32_16x16x32_bf16 v[8:11], v[160:163], v[192:195], v[8:11]
	v_mfma_f32_16x16x32_bf16 v[60:63], v[156:159], v[172:175], v[60:63]
	v_mfma_f32_16x16x32_bf16 v[56:59], v[164:167], v[172:175], v[56:59]
	v_mfma_f32_16x16x32_bf16 v[44:47], v[156:159], v[180:183], v[44:47]
	v_mfma_f32_16x16x32_bf16 v[40:43], v[164:167], v[180:183], v[40:43]
	v_mfma_f32_16x16x32_bf16 v[28:31], v[156:159], v[188:191], v[28:31]
	v_mfma_f32_16x16x32_bf16 v[24:27], v[164:167], v[188:191], v[24:27]
	v_mfma_f32_16x16x32_bf16 v[12:15], v[156:159], v[196:199], v[12:15]
	v_mfma_f32_16x16x32_bf16 v[8:11], v[164:167], v[196:199], v[8:11]
	s_setprio 0
	s_barrier
	s_add_u32 s20, s28, 0xb0080
	s_addc_u32 s21, s29, 0
	s_add_i32 s28, s30, s40
	s_mov_b32 m0, s28
	s_nop 0
	global_load_lds_dwordx4 v130, s[20:21]
	s_add_i32 m0, s28, 0x2000
	s_nop 0
	global_load_lds_dwordx4 v134, s[20:21]
	s_waitcnt vmcnt(6)
	s_barrier
	s_setprio 1
	v_mfma_f32_16x16x32_bf16 v[52:55], v[200:203], v[168:171], v[52:55]
	v_mfma_f32_16x16x32_bf16 v[48:51], v[208:211], v[168:171], v[48:51]
	v_mfma_f32_16x16x32_bf16 v[36:39], v[200:203], v[176:179], v[36:39]
	v_mfma_f32_16x16x32_bf16 v[32:35], v[208:211], v[176:179], v[32:35]
	v_mfma_f32_16x16x32_bf16 v[20:23], v[200:203], v[184:187], v[20:23]
	v_mfma_f32_16x16x32_bf16 v[16:19], v[208:211], v[184:187], v[16:19]
	v_mfma_f32_16x16x32_bf16 v[4:7], v[200:203], v[192:195], v[4:7]
	v_mfma_f32_16x16x32_bf16 v[0:3], v[208:211], v[192:195], v[0:3]
	v_mfma_f32_16x16x32_bf16 v[52:55], v[204:207], v[172:175], v[52:55]
	v_mfma_f32_16x16x32_bf16 v[48:51], v[212:215], v[172:175], v[48:51]
	v_mfma_f32_16x16x32_bf16 v[36:39], v[204:207], v[180:183], v[36:39]
	v_mfma_f32_16x16x32_bf16 v[32:35], v[212:215], v[180:183], v[32:35]
	v_mfma_f32_16x16x32_bf16 v[20:23], v[204:207], v[188:191], v[20:23]
	v_mfma_f32_16x16x32_bf16 v[16:19], v[212:215], v[188:191], v[16:19]
	v_mfma_f32_16x16x32_bf16 v[4:7], v[204:207], v[196:199], v[4:7]
	v_mfma_f32_16x16x32_bf16 v[0:3], v[212:215], v[196:199], v[0:3]
	s_setprio 0
	s_add_i32 s59, s59, 2
	s_add_u32 s57, s57, 0x100
	s_addc_u32 s58, s58, 0
	s_cmp_gt_u32 s59, 41
	s_mov_b64 s[20:21], s[26:27]
	s_barrier
	s_cbranch_scc0 .LBB0_248
	s_cmpk_gt_u32 s35, 0xff
	s_cbranch_scc1 .Lg248_nox
	s_barrier
.Lg248_nox:
	v_lshl_add_u32 v146, s56, 8, v148
	v_ashrrev_i32_e32 v147, 31, v146
	v_lshl_or_b32 v144, s12, 8, v150
	v_lshlrev_b64 v[156:157], 11, v[146:147]
	v_ashrrev_i32_e32 v145, 31, v144
	v_lshl_add_u64 v[156:157], s[14:15], 0, v[156:157]
	v_lshl_add_u64 v[166:167], v[144:145], 1, v[156:157]
	global_load_dwordx4 v[158:161], v[166:167], off
	global_load_dwordx4 v[162:165], v[166:167], off offset:256
	v_and_b32_e32 v156, 64, v154
	v_xor_b32_e32 v155, 16, v154
	v_add_u32_e32 v156, 64, v156
	v_xor_b32_e32 v157, 32, v154
	v_cmp_lt_i32_e32 vcc, v155, v156
	s_lshl_b32 s20, s12, 2
	s_ashr_i32 s21, s20, 31
	v_cndmask_b32_e32 v155, v154, v155, vcc
	v_cmp_lt_i32_e32 vcc, v157, v156
	v_lshlrev_b32_e32 v156, 2, v155
	s_waitcnt vmcnt(0)
	v_lshlrev_b32_e32 v168, 16, v158
	v_and_b32_e32 v169, 0xffff0000, v158
	v_lshlrev_b32_e32 v158, 16, v159
	v_and_b32_e32 v159, 0xffff0000, v159
	v_lshlrev_b32_e32 v172, 16, v162
	v_and_b32_e32 v173, 0xffff0000, v162
	v_lshlrev_b32_e32 v162, 16, v163
	v_and_b32_e32 v163, 0xffff0000, v163
	v_cndmask_b32_e32 v157, v154, v157, vcc
	v_lshlrev_b32_e32 v170, 16, v160
	v_and_b32_e32 v171, 0xffff0000, v160
	v_lshlrev_b32_e32 v160, 16, v161
	v_and_b32_e32 v161, 0xffff0000, v161
	v_lshlrev_b32_e32 v174, 16, v164
	v_and_b32_e32 v175, 0xffff0000, v164
	v_lshlrev_b32_e32 v164, 16, v165
	v_and_b32_e32 v165, 0xffff0000, v165
	v_pk_fma_f32 v[126:127], v[126:127], 0.5, v[158:159] op_sel_hi:[1,0,1]
	v_pk_fma_f32 v[124:125], v[124:125], 0.5, v[168:169] op_sel_hi:[1,0,1]
	v_pk_fma_f32 v[118:119], v[118:119], 0.5, v[162:163] op_sel_hi:[1,0,1]
	v_pk_fma_f32 v[116:117], v[116:117], 0.5, v[172:173] op_sel_hi:[1,0,1]
	v_lshlrev_b32_e32 v155, 2, v157
	v_pk_fma_f32 v[122:123], v[122:123], 0.5, v[160:161] op_sel_hi:[1,0,1]
	v_pk_fma_f32 v[120:121], v[120:121], 0.5, v[170:171] op_sel_hi:[1,0,1]
	v_pk_fma_f32 v[158:159], v[114:115], 0.5, v[164:165] op_sel_hi:[1,0,1]
	v_pk_fma_f32 v[160:161], v[112:113], 0.5, v[174:175] op_sel_hi:[1,0,1]
	v_mul_f32_e32 v114, v125, v125
	v_mul_f32_e32 v115, v127, v127
	v_mul_f32_e32 v157, v117, v117
	v_mul_f32_e32 v162, v119, v119
	v_cvt_pk_bf16_f32 v112, v124, v125
	v_mul_f32_e32 v125, v121, v121
	v_mul_f32_e32 v163, v161, v161
	v_fmac_f32_e32 v114, v124, v124
	v_fmac_f32_e32 v115, v126, v126
	v_fmac_f32_e32 v157, v116, v116
	v_fmac_f32_e32 v162, v118, v118
	v_cvt_pk_bf16_f32 v113, v126, v127
	v_mul_f32_e32 v127, v123, v123
	v_mul_f32_e32 v164, v159, v159
	v_fmac_f32_e32 v125, v120, v120
	v_fmac_f32_e32 v163, v160, v160
	v_add_f32_e32 v114, v114, v115
	v_add_f32_e32 v115, v157, v162
	v_fmac_f32_e32 v127, v122, v122
	v_fmac_f32_e32 v164, v158, v158
	v_add_f32_e32 v114, v125, v114
	v_add_f32_e32 v115, v163, v115
	v_add_f32_e32 v114, v127, v114
	v_add_f32_e32 v115, v164, v115
	v_add_f32_e32 v124, v114, v115
	ds_bpermute_b32 v125, v156, v124
	v_cvt_pk_bf16_f32 v114, v120, v121
	v_cvt_pk_bf16_f32 v115, v122, v123
	global_store_dwordx4 v[166:167], v[112:115], off
	s_waitcnt lgkmcnt(0)
	s_nop 0
	v_add_f32_e32 v112, v124, v125
	ds_bpermute_b32 v113, v155, v112
	v_cvt_pk_bf16_f32 v114, v116, v117
	v_cvt_pk_bf16_f32 v115, v118, v119
	v_cvt_pk_bf16_f32 v116, v160, v161
	v_cvt_pk_bf16_f32 v117, v158, v159
	global_store_dwordx4 v[166:167], v[114:117], off offset:256
	s_and_saveexec_b64 s[26:27], s[4:5]
	s_cbranch_execz .LBB0_251
	v_lshlrev_b64 v[114:115], 6, v[146:147]
	v_lshl_add_u64 v[114:115], s[16:17], 0, v[114:115]
	v_lshl_add_u64 v[114:115], s[20:21], 2, v[114:115]
	s_lshl_b32 s12, s45, 2
	v_lshl_add_u64 v[114:115], v[114:115], 0, s[12:13]
	s_waitcnt lgkmcnt(0)
	v_add_f32_e32 v112, v112, v113
	global_store_dword v[114:115], v112, off

.LBB0_265:
	s_waitcnt vmcnt(0)
	s_cmpk_gt_u32 s35, 0xff
	s_cbranch_scc1 .LBB0_267
.LBB0_267:
	s_barrier

.LBB0_350:
	s_andn2_b64 vcc, exec, s[4:5]
	s_cbranch_vccnz .LBB0_451
	s_waitcnt vmcnt(3)
	v_ashrrev_i32_e32 v1, 31, v153
	v_lshrrev_b32_e32 v1, 26, v1
	v_add_u32_e32 v1, v153, v1
	s_waitcnt vmcnt(1)
	v_ashrrev_i32_e32 v8, 6, v1
	v_bfe_i32 v1, v153, 27, 1
	v_lshlrev_b32_e32 v0, 4, v153
	v_lshrrev_b32_e32 v1, 22, v1
	v_add_u32_e32 v1, v0, v1
	v_and_b32_e32 v1, 0xfffffc00, v1
	v_sub_u32_e32 v1, v0, v1
	v_lshrrev_b32_e32 v2, 4, v1
	v_bitop3_b32 v1, v2, v1, 32 bitop3:0x6c
	v_ashrrev_i32_e32 v3, 31, v1
	v_lshrrev_b32_e32 v3, 26, v3
	v_add_u32_e32 v3, v1, v3
	v_lshlrev_b32_e32 v2, 3, v8
	v_ashrrev_i32_e32 v9, 6, v3
	v_and_b32_e32 v3, 0xc0, v3
	v_and_b32_e32 v2, -16, v2
	v_sub_u32_e32 v1, v1, v3
	v_mov_b32_e32 v3, 1
	v_add_u32_e32 v2, v9, v2
	v_ashrrev_i16_sdwa v1, v3, sext(v1) dst_sel:DWORD dst_unused:UNUSED_PAD src0_sel:DWORD src1_sel:BYTE_0
	v_lshlrev_b32_e32 v4, 5, v8
	v_bfe_i32 v10, v1, 0, 16
	v_lshlrev_b32_e32 v1, 1, v2
	v_lshrrev_b32_e32 v5, 2, v2
	v_and_b32_e32 v6, 3, v9
	s_mov_b32 s5, 0x1fffe0
	v_and_b32_e32 v4, 32, v4
	v_and_b32_e32 v1, 24, v1
	v_and_b32_e32 v5, 4, v5
	v_and_or_b32 v6, v2, s5, v6
	v_or3_b32 v1, v6, v5, v1
	v_add_lshl_u32 v4, v4, v10, 1
	v_add_u32_e32 v0, 0x2000, v0
	v_lshl_add_u32 v144, v1, 11, v4
	v_ashrrev_i32_e32 v1, 31, v0
	v_lshrrev_b32_e32 v1, 22, v1
	v_add_u32_e32 v1, v0, v1
	v_ashrrev_i32_e32 v11, 10, v1
	v_mul_i32_i24_e32 v1, 0x400, v11
	v_sub_u32_e32 v0, v0, v1
	v_lshrrev_b32_e32 v1, 4, v0
	v_bitop3_b32 v0, v1, v0, 32 bitop3:0x6c
	s_waitcnt vmcnt(0)
	v_lshl_add_u32 v142, v2, 11, v4
	v_ashrrev_i32_e32 v2, 31, v0
	v_lshrrev_b32_e32 v2, 26, v2
	v_add_u32_e32 v2, v0, v2
	v_lshlrev_b32_e32 v1, 3, v11
	v_ashrrev_i32_e32 v12, 6, v2
	v_and_b32_e32 v2, 0xc0, v2
	v_and_b32_e32 v1, -16, v1
	v_sub_u32_e32 v0, v0, v2
	s_ashr_i32 s4, s45, 6
	v_add_u32_e32 v1, v12, v1
	v_ashrrev_i16_sdwa v0, v3, sext(v0) dst_sel:DWORD dst_unused:UNUSED_PAD src0_sel:DWORD src1_sel:BYTE_0
	v_and_b32_e32 v3, 3, v12
	v_and_or_b32 v3, v1, s5, v3
	s_ashr_i32 s5, s45, 8
	s_lshl_b32 s46, s4, 10
	s_add_u32 s47, s26, 0x3800000
	s_addc_u32 s48, s27, 0
	s_add_u32 s49, s26, 0x1080000
	s_addc_u32 s50, s27, 0
	s_ashr_i32 s7, s6, 31
	s_ashr_i32 s37, s36, 31
	s_lshl_b64 s[8:9], s[6:7], 19
	s_lshl_b64 s[10:11], s[36:37], 19
	s_add_u32 s38, s49, s10
	v_lshlrev_b32_e32 v4, 5, v11
	v_bfe_i32 v13, v0, 0, 16
	v_lshlrev_b32_e32 v0, 1, v1
	v_lshrrev_b32_e32 v2, 2, v1
	s_addc_u32 s39, s50, s11
	s_add_i32 s37, s46, 0
	v_and_b32_e32 v4, 32, v4
	v_and_b32_e32 v0, 24, v0
	v_and_b32_e32 v2, 4, v2
	s_add_i32 m0, s37, 0x10000
	v_or3_b32 v0, v3, v2, v0
	v_add_lshl_u32 v2, v4, v13, 1
	global_load_lds_dwordx4 v144, s[38:39]
	s_add_i32 m0, s37, 0x12000
	v_lshl_add_u32 v148, v0, 11, v2
	s_add_u32 s8, s47, s8
	global_load_lds_dwordx4 v148, s[38:39]
	s_addc_u32 s9, s48, s9
	s_mov_b32 m0, s37
	s_add_i32 s51, s37, 0x2000
	v_lshl_add_u32 v146, v1, 11, v2
	global_load_lds_dwordx4 v142, s[8:9]
	s_mov_b32 m0, s51
	s_add_u32 s10, s38, 0x40000
	global_load_lds_dwordx4 v146, s[8:9]
	s_addc_u32 s11, s39, 0
	s_add_i32 m0, s37, 0x14000
	v_mov_b32_e32 v151, 0
	global_load_lds_dwordx4 v144, s[10:11]
	s_add_i32 m0, s37, 0x16000
	v_mov_b32_e32 v145, v151
	global_load_lds_dwordx4 v148, s[10:11]
	s_add_u32 s10, s8, 0x40000
	s_addc_u32 s11, s9, 0
	s_add_i32 s52, s37, 0x4000
	s_mov_b32 m0, s52
	s_add_i32 s53, s37, 0x6000
	global_load_lds_dwordx4 v142, s[10:11]
	s_mov_b32 m0, s53
	v_mov_b32_e32 v149, v151
	global_load_lds_dwordx4 v146, s[10:11]
	v_mov_b32_e32 v143, v151
	v_mov_b32_e32 v147, v151
	s_mov_b32 s7, 0
	v_lshl_add_u64 v[6:7], s[38:39], 0, v[144:145]
	v_lshl_add_u64 v[4:5], s[38:39], 0, v[148:149]
	v_lshl_add_u64 v[2:3], s[8:9], 0, v[142:143]
	v_lshl_add_u64 v[0:1], s[8:9], 0, v[146:147]
	s_cmp_lg_u32 s5, 1
	s_movk_i32 s54, 0x4000
	s_cbranch_scc1 .LBB0_353
.LBB0_353:
	s_mov_b64 s[10:11], 0x80
	s_and_b32 s4, s4, 3
	s_add_i32 m0, s37, 0x18000
	v_lshl_add_u64 v[6:7], v[6:7], 0, s[10:11]
	s_lshl_b32 s14, s5, 13
	s_lshl_b32 s18, s4, 5
	s_lshl_b32 s15, s4, 12
	s_waitcnt vmcnt(4)
	s_barrier
	global_load_lds_dwordx4 v[6:7], off
	v_lshl_add_u64 v[4:5], v[4:5], 0, s[10:11]
	s_add_i32 m0, s37, 0x1a000
	s_add_i32 s55, s37, 0x8000
	s_add_i32 s56, s37, 0xa000
	global_load_lds_dwordx4 v[4:5], off
	v_lshl_add_u64 v[2:3], v[2:3], 0, s[10:11]
	s_mov_b32 m0, s55
	s_add_u32 s12, s38, 0x40080
	global_load_lds_dwordx4 v[2:3], off
	v_lshl_add_u64 v[0:1], v[0:1], 0, s[10:11]
	s_mov_b32 m0, s56
	s_addc_u32 s13, s39, 0
	global_load_lds_dwordx4 v[0:1], off
	s_add_i32 m0, s37, 0x1c000
	v_lshl_add_u64 v[0:1], s[12:13], 0, v[144:145]
	global_load_lds_dwordx4 v[0:1], off
	v_lshl_add_u64 v[0:1], s[12:13], 0, v[148:149]
	s_add_i32 m0, s37, 0x1e000
	v_mov_b32_e32 v159, v151
	global_load_lds_dwordx4 v[0:1], off
	v_and_b32_e32 v0, 15, v153
	v_lshl_or_b32 v178, s5, 6, v0
	v_lshrrev_b32_e32 v1, 1, v153
	s_lshl_b32 s5, s5, 8
	v_and_b32_e32 v152, 24, v1
	s_add_i32 s5, s5, 0
	v_lshlrev_b32_e32 v1, 1, v152
	s_add_i32 s5, s5, 0x20000
	v_lshl_or_b32 v1, v0, 6, v1
	v_lshlrev_b32_e32 v0, 2, v0
	s_add_u32 s12, s26, 0xf800000
	v_and_b32_e32 v2, 32, v0
	s_addc_u32 s13, s27, 0
	v_bitop3_b32 v3, v1, s14, v2 bitop3:0xde
	s_add_u32 s14, s26, 0xe000000
	v_bitop3_b32 v179, s15, v1, v2 bitop3:0xf6
	s_addc_u32 s15, s27, 0
	s_cmp_lt_u32 s4, 2
	s_cselect_b64 s[16:17], -1, 0
	s_lshl_b32 s57, s4, 6
	s_lshl_b32 s4, s4, 7
	s_add_u32 s4, s26, s4
	v_add_u32_e32 v180, s5, v0
	s_addc_u32 s5, s27, 0
	s_add_u32 s19, s4, 0xd3fff00
	s_addc_u32 s20, s5, 0
	s_add_u32 s21, s4, 0xc800000
	v_lshlrev_b32_e32 v150, 2, v152
	s_addc_u32 s30, s5, 0
	v_lshl_add_u64 v[0:1], s[26:27], 0, v[150:151]
	s_mov_b64 s[4:5], 0x2800000
	v_lshl_add_u64 v[154:155], v[0:1], 0, s[4:5]
	s_mov_b64 s[4:5], 0x2900000
	v_lshl_add_u64 v[156:157], v[0:1], 0, s[4:5]
	v_lshlrev_b32_e32 v0, 14, v8
	v_and_b32_e32 v0, 0xffff8000, v0
	v_lshl_add_u32 v0, v9, 11, v0
	v_and_b32_e32 v1, 1, v8
	v_lshl_or_b32 v0, v1, 6, v0
	s_add_u32 s58, s26, 0x9800000
	v_lshl_add_u32 v158, v10, 1, v0
	v_lshlrev_b32_e32 v0, 14, v11
	s_addc_u32 s59, s27, 0
	v_and_b32_e32 v0, 0xffff8000, v0
	s_waitcnt vmcnt(6)
	s_and_b64 s[4:5], s[16:17], exec
	v_lshl_add_u32 v0, v12, 11, v0
	v_and_b32_e32 v1, 1, v11
	s_cselect_b32 s60, s30, s20
	s_cselect_b32 s61, s21, s19
	v_lshl_or_b32 v0, v1, 6, v0
	s_add_i32 s63, 0, 0x10000
	s_add_i32 s64, 0, 0x14000
	v_lshl_add_u32 v160, v13, 1, v0
	v_mov_b32_e32 v161, v151
	v_mov_b64_e32 v[162:163], 0x6c0
	v_mov_b64_e32 v[164:165], 0x6bf
	s_movk_i32 s62, 0xd9
	v_add_u32_e32 v181, s63, v179
	v_add_u32_e32 v182, 0, v3
	v_add_u32_e32 v183, s64, v179
	s_lshl_b32 s65, s18, 1
	s_movk_i32 s66, 0x3f80
	s_movk_i32 s67, 0x3f70
	s_movk_i32 s68, 0x3f60
	s_movk_i32 s69, 0x3f50
	v_mov_b32_e32 v184, 0x1fcf
	v_mov_b32_e32 v185, 0x7cf
	v_mov_b32_e32 v186, 0x1fdf
	v_mov_b32_e32 v187, 0x7df
	v_mov_b32_e32 v188, 0x1fef
	v_mov_b32_e32 v189, 0x7ef
	v_mov_b32_e32 v190, 0x1fff
	v_mov_b32_e32 v191, 0x7ff
	s_barrier
	s_branch .LBB0_356

.LBB0_358:
	s_ashr_i32 s21, s20, 31
	v_cmp_lt_i64_e32 vcc, s[30:31], v[162:163]
	s_lshl_b64 s[30:31], s[20:21], 19
	s_add_u32 s30, s47, s30
	s_addc_u32 s31, s48, s31
	s_and_b64 s[34:35], vcc, exec
	s_cselect_b32 s21, s31, s9
	s_cselect_b32 s71, s30, s8
	s_ashr_i32 s19, s18, 31
	s_lshl_b64 s[34:35], s[18:19], 19
	s_add_u32 s34, s49, s34
	s_addc_u32 s35, s50, s35
	s_and_b64 s[40:41], vcc, exec
	s_cselect_b32 s19, s35, s39
	s_cselect_b32 s72, s34, s38
	s_add_u32 s8, s8, 0x40080
	s_addc_u32 s9, s9, 0
	s_add_u32 s73, s38, 0x100
	v_mov_b32_e32 v0, 0
	s_addc_u32 s74, s39, 0
	s_mov_b32 s75, -2
	v_mov_b32_e32 v1, v0
	v_mov_b32_e32 v2, v0
	v_mov_b32_e32 v3, v0
	v_mov_b32_e32 v8, v0
	v_mov_b32_e32 v9, v0
	v_mov_b32_e32 v10, v0
	v_mov_b32_e32 v11, v0
	v_mov_b32_e32 v16, v0
	v_mov_b32_e32 v17, v0
	v_mov_b32_e32 v18, v0
	v_mov_b32_e32 v19, v0
	v_mov_b32_e32 v24, v0
	v_mov_b32_e32 v25, v0
	v_mov_b32_e32 v26, v0
	v_mov_b32_e32 v27, v0
	v_mov_b32_e32 v32, v0
	v_mov_b32_e32 v33, v0
	v_mov_b32_e32 v34, v0
	v_mov_b32_e32 v35, v0
	v_mov_b32_e32 v40, v0
	v_mov_b32_e32 v41, v0
	v_mov_b32_e32 v42, v0
	v_mov_b32_e32 v43, v0
	v_mov_b32_e32 v48, v0
	v_mov_b32_e32 v49, v0
	v_mov_b32_e32 v50, v0
	v_mov_b32_e32 v51, v0
	v_mov_b32_e32 v56, v0
	v_mov_b32_e32 v57, v0
	v_mov_b32_e32 v58, v0
	v_mov_b32_e32 v59, v0
	v_mov_b32_e32 v4, v0
	v_mov_b32_e32 v5, v0
	v_mov_b32_e32 v6, v0
	v_mov_b32_e32 v7, v0
	v_mov_b32_e32 v12, v0
	v_mov_b32_e32 v13, v0
	v_mov_b32_e32 v14, v0
	v_mov_b32_e32 v15, v0
	v_mov_b32_e32 v20, v0
	v_mov_b32_e32 v21, v0
	v_mov_b32_e32 v22, v0
	v_mov_b32_e32 v23, v0
	v_mov_b32_e32 v28, v0
	v_mov_b32_e32 v29, v0
	v_mov_b32_e32 v30, v0
	v_mov_b32_e32 v31, v0
	v_mov_b32_e32 v36, v0
	v_mov_b32_e32 v37, v0
	v_mov_b32_e32 v38, v0
	v_mov_b32_e32 v39, v0
	v_mov_b32_e32 v44, v0
	v_mov_b32_e32 v45, v0
	v_mov_b32_e32 v46, v0
	v_mov_b32_e32 v47, v0
	v_mov_b32_e32 v52, v0
	v_mov_b32_e32 v53, v0
	v_mov_b32_e32 v54, v0
	v_mov_b32_e32 v55, v0
	v_mov_b32_e32 v60, v0
	v_mov_b32_e32 v61, v0
	v_mov_b32_e32 v62, v0
	v_mov_b32_e32 v63, v0
	v_mov_b32_e32 v64, v0
	v_mov_b32_e32 v65, v0
	v_mov_b32_e32 v66, v0
	v_mov_b32_e32 v67, v0
	v_mov_b32_e32 v72, v0
	v_mov_b32_e32 v73, v0
	v_mov_b32_e32 v74, v0
	v_mov_b32_e32 v75, v0
	v_mov_b32_e32 v80, v0
	v_mov_b32_e32 v81, v0
	v_mov_b32_e32 v82, v0
	v_mov_b32_e32 v83, v0
	v_mov_b32_e32 v88, v0
	v_mov_b32_e32 v89, v0
	v_mov_b32_e32 v90, v0
	v_mov_b32_e32 v91, v0
	v_mov_b32_e32 v96, v0
	v_mov_b32_e32 v97, v0
	v_mov_b32_e32 v98, v0
	v_mov_b32_e32 v99, v0
	v_mov_b32_e32 v104, v0
	v_mov_b32_e32 v105, v0
	v_mov_b32_e32 v106, v0
	v_mov_b32_e32 v107, v0
	v_mov_b32_e32 v112, v0
	v_mov_b32_e32 v113, v0
	v_mov_b32_e32 v114, v0
	v_mov_b32_e32 v115, v0
	v_mov_b32_e32 v120, v0
	v_mov_b32_e32 v121, v0
	v_mov_b32_e32 v122, v0
	v_mov_b32_e32 v123, v0
	v_mov_b32_e32 v68, v0
	v_mov_b32_e32 v69, v0
	v_mov_b32_e32 v70, v0
	v_mov_b32_e32 v71, v0
	v_mov_b32_e32 v76, v0
	v_mov_b32_e32 v77, v0
	v_mov_b32_e32 v78, v0
	v_mov_b32_e32 v79, v0
	v_mov_b32_e32 v84, v0
	v_mov_b32_e32 v85, v0
	v_mov_b32_e32 v86, v0
	v_mov_b32_e32 v87, v0
	v_mov_b32_e32 v92, v0
	v_mov_b32_e32 v93, v0
	v_mov_b32_e32 v94, v0
	v_mov_b32_e32 v95, v0
	v_mov_b32_e32 v100, v0
	v_mov_b32_e32 v101, v0
	v_mov_b32_e32 v102, v0
	v_mov_b32_e32 v103, v0
	v_mov_b32_e32 v108, v0
	v_mov_b32_e32 v109, v0
	v_mov_b32_e32 v110, v0
	v_mov_b32_e32 v111, v0
	v_mov_b32_e32 v116, v0
	v_mov_b32_e32 v117, v0
	v_mov_b32_e32 v118, v0
	v_mov_b32_e32 v119, v0
	v_mov_b32_e32 v124, v0
	v_mov_b32_e32 v125, v0
	v_mov_b32_e32 v126, v0
	v_mov_b32_e32 v127, v0
	s_cmpk_lt_u32 s45, 0x100
	s_cbranch_scc1 .Lg359_noy
	s_barrier
.Lg359_noy:
.LBB0_359:
	ds_read_b128 v[128:131], v181
	ds_read_b128 v[132:135], v181 offset:1024
	ds_read_b128 v[136:139], v181 offset:2048
	ds_read_b128 v[166:169], v181 offset:3072
	s_add_u32 s38, s8, 0xfffc0080
	s_addc_u32 s39, s9, -1
	s_cmp_eq_u32 s75, 12
	s_cselect_b32 s41, s21, s39
	s_cselect_b32 s40, s71, s38
	s_cselect_b32 s39, s19, s74
	s_cselect_b32 s38, s72, s73
	s_add_i32 m0, s37, 0xc000
	ds_read_b128 v[170:173], v182
	ds_read_b128 v[174:177], v182 offset:1024
	ds_read_b128 v[192:195], v182 offset:2048
	ds_read_b128 v[196:199], v182 offset:3072
	ds_read_b128 v[200:203], v182 offset:4096
	ds_read_b128 v[204:207], v182 offset:5120
	ds_read_b128 v[208:211], v182 offset:6144
	ds_read_b128 v[212:215], v182 offset:7168
	global_load_lds_dwordx4 v158, s[8:9]
	s_add_i32 m0, s37, 0xe000
	s_nop 0
	global_load_lds_dwordx4 v160, s[8:9]
	s_waitcnt lgkmcnt(8)
	s_barrier
	s_waitcnt lgkmcnt(0)
	s_setprio 1
	s_waitcnt lgkmcnt(0)
	v_mfma_f32_16x16x32_bf16 v[124:127], v[128:131], v[170:173], v[124:127]
	v_mfma_f32_16x16x32_bf16 v[116:119], v[136:139], v[170:173], v[116:119]
	v_mfma_f32_16x16x32_bf16 v[108:111], v[128:131], v[192:195], v[108:111]
	v_mfma_f32_16x16x32_bf16 v[100:103], v[136:139], v[192:195], v[100:103]
	v_mfma_f32_16x16x32_bf16 v[92:95], v[128:131], v[200:203], v[92:95]
	v_mfma_f32_16x16x32_bf16 v[84:87], v[136:139], v[200:203], v[84:87]
	v_mfma_f32_16x16x32_bf16 v[76:79], v[128:131], v[208:211], v[76:79]
	v_mfma_f32_16x16x32_bf16 v[68:71], v[136:139], v[208:211], v[68:71]
	v_mfma_f32_16x16x32_bf16 v[124:127], v[132:135], v[174:177], v[124:127]
	v_mfma_f32_16x16x32_bf16 v[116:119], v[166:169], v[174:177], v[116:119]
	v_mfma_f32_16x16x32_bf16 v[108:111], v[132:135], v[196:199], v[108:111]
	v_mfma_f32_16x16x32_bf16 v[100:103], v[166:169], v[196:199], v[100:103]
	v_mfma_f32_16x16x32_bf16 v[92:95], v[132:135], v[204:207], v[92:95]
	v_mfma_f32_16x16x32_bf16 v[84:87], v[166:169], v[204:207], v[84:87]
	v_mfma_f32_16x16x32_bf16 v[76:79], v[132:135], v[212:215], v[76:79]
	v_mfma_f32_16x16x32_bf16 v[68:71], v[166:169], v[212:215], v[68:71]
	s_setprio 0
	s_barrier
	s_add_i32 s76, s63, s46
	s_add_u32 s80, s38, 0x80
	s_addc_u32 s81, s39, 0
	s_mov_b32 m0, s76
	ds_read_b128 v[216:219], v183
	ds_read_b128 v[220:223], v183 offset:1024
	ds_read_b128 v[224:227], v183 offset:2048
	ds_read_b128 v[228:231], v183 offset:3072
	global_load_lds_dwordx4 v144, s[38:39]
	s_add_i32 m0, s76, 0x2000
	s_nop 0
	global_load_lds_dwordx4 v148, s[38:39]
	s_barrier
	s_waitcnt lgkmcnt(0)
	s_setprio 1
	s_waitcnt lgkmcnt(0)
	v_mfma_f32_16x16x32_bf16 v[120:123], v[216:219], v[170:173], v[120:123]
	v_mfma_f32_16x16x32_bf16 v[112:115], v[224:227], v[170:173], v[112:115]
	v_mfma_f32_16x16x32_bf16 v[104:107], v[216:219], v[192:195], v[104:107]
	v_mfma_f32_16x16x32_bf16 v[96:99], v[224:227], v[192:195], v[96:99]
	v_mfma_f32_16x16x32_bf16 v[88:91], v[216:219], v[200:203], v[88:91]
	v_mfma_f32_16x16x32_bf16 v[80:83], v[224:227], v[200:203], v[80:83]
	v_mfma_f32_16x16x32_bf16 v[72:75], v[216:219], v[208:211], v[72:75]
	v_mfma_f32_16x16x32_bf16 v[64:67], v[224:227], v[208:211], v[64:67]
	v_mfma_f32_16x16x32_bf16 v[120:123], v[220:223], v[174:177], v[120:123]
	v_mfma_f32_16x16x32_bf16 v[112:115], v[228:231], v[174:177], v[112:115]
	v_mfma_f32_16x16x32_bf16 v[104:107], v[220:223], v[196:199], v[104:107]
	v_mfma_f32_16x16x32_bf16 v[96:99], v[228:231], v[196:199], v[96:99]
	v_mfma_f32_16x16x32_bf16 v[88:91], v[220:223], v[204:207], v[88:91]
	v_mfma_f32_16x16x32_bf16 v[80:83], v[228:231], v[204:207], v[80:83]
	v_mfma_f32_16x16x32_bf16 v[72:75], v[220:223], v[212:215], v[72:75]
	v_mfma_f32_16x16x32_bf16 v[64:67], v[228:231], v[212:215], v[64:67]
	s_setprio 0
	s_mov_b32 m0, s37
	s_add_u32 s82, s40, 0x80
	s_addc_u32 s83, s41, 0
	s_barrier
	ds_read_b128 v[170:173], v182 offset:16384
	ds_read_b128 v[174:177], v182 offset:17408
	ds_read_b128 v[192:195], v182 offset:18432
	ds_read_b128 v[196:199], v182 offset:19456
	ds_read_b128 v[200:203], v182 offset:20480
	ds_read_b128 v[204:207], v182 offset:21504
	ds_read_b128 v[208:211], v182 offset:22528
	ds_read_b128 v[212:215], v182 offset:23552
	global_load_lds_dwordx4 v142, s[40:41]
	s_mov_b32 m0, s51
	s_nop 0
	global_load_lds_dwordx4 v146, s[40:41]
	s_barrier
	s_waitcnt lgkmcnt(0)
	s_setprio 1
	s_waitcnt lgkmcnt(0)
	v_mfma_f32_16x16x32_bf16 v[60:63], v[128:131], v[170:173], v[60:63]
	v_mfma_f32_16x16x32_bf16 v[52:55], v[136:139], v[170:173], v[52:55]
	v_mfma_f32_16x16x32_bf16 v[44:47], v[128:131], v[192:195], v[44:47]
	v_mfma_f32_16x16x32_bf16 v[36:39], v[136:139], v[192:195], v[36:39]
	v_mfma_f32_16x16x32_bf16 v[28:31], v[128:131], v[200:203], v[28:31]
	v_mfma_f32_16x16x32_bf16 v[20:23], v[136:139], v[200:203], v[20:23]
	v_mfma_f32_16x16x32_bf16 v[12:15], v[128:131], v[208:211], v[12:15]
	v_mfma_f32_16x16x32_bf16 v[4:7], v[136:139], v[208:211], v[4:7]
	v_mfma_f32_16x16x32_bf16 v[60:63], v[132:135], v[174:177], v[60:63]
	v_mfma_f32_16x16x32_bf16 v[52:55], v[166:169], v[174:177], v[52:55]
	v_mfma_f32_16x16x32_bf16 v[44:47], v[132:135], v[196:199], v[44:47]
	v_mfma_f32_16x16x32_bf16 v[36:39], v[166:169], v[196:199], v[36:39]
	v_mfma_f32_16x16x32_bf16 v[28:31], v[132:135], v[204:207], v[28:31]
	v_mfma_f32_16x16x32_bf16 v[20:23], v[166:169], v[204:207], v[20:23]
	v_mfma_f32_16x16x32_bf16 v[12:15], v[132:135], v[212:215], v[12:15]
	v_mfma_f32_16x16x32_bf16 v[4:7], v[166:169], v[212:215], v[4:7]
	s_setprio 0
	s_barrier
	s_add_u32 s76, s38, 0x40000
	s_addc_u32 s77, s39, 0
	s_add_i32 s78, s64, s46
	s_mov_b32 m0, s78
	s_nop 0
	global_load_lds_dwordx4 v144, s[76:77]
	s_add_i32 m0, s78, 0x2000
	s_nop 0
	global_load_lds_dwordx4 v148, s[76:77]
	s_waitcnt vmcnt(6)
	s_barrier
	s_setprio 1
	v_mfma_f32_16x16x32_bf16 v[56:59], v[216:219], v[170:173], v[56:59]
	v_mfma_f32_16x16x32_bf16 v[48:51], v[224:227], v[170:173], v[48:51]
	v_mfma_f32_16x16x32_bf16 v[40:43], v[216:219], v[192:195], v[40:43]
	v_mfma_f32_16x16x32_bf16 v[32:35], v[224:227], v[192:195], v[32:35]
	v_mfma_f32_16x16x32_bf16 v[24:27], v[216:219], v[200:203], v[24:27]
	v_mfma_f32_16x16x32_bf16 v[16:19], v[224:227], v[200:203], v[16:19]
	v_mfma_f32_16x16x32_bf16 v[8:11], v[216:219], v[208:211], v[8:11]
	v_mfma_f32_16x16x32_bf16 v[0:3], v[224:227], v[208:211], v[0:3]
	v_mfma_f32_16x16x32_bf16 v[56:59], v[220:223], v[174:177], v[56:59]
	v_mfma_f32_16x16x32_bf16 v[48:51], v[228:231], v[174:177], v[48:51]
	v_mfma_f32_16x16x32_bf16 v[40:43], v[220:223], v[196:199], v[40:43]
	v_mfma_f32_16x16x32_bf16 v[32:35], v[228:231], v[196:199], v[32:35]
	v_mfma_f32_16x16x32_bf16 v[24:27], v[220:223], v[204:207], v[24:27]
	v_mfma_f32_16x16x32_bf16 v[16:19], v[228:231], v[204:207], v[16:19]
	v_mfma_f32_16x16x32_bf16 v[8:11], v[220:223], v[212:215], v[8:11]
	v_mfma_f32_16x16x32_bf16 v[0:3], v[228:231], v[212:215], v[0:3]
	s_setprio 0
	s_add_i32 s76, 0, 0x18000
	v_add_u32_e32 v150, s76, v179
	s_barrier
	ds_read_b128 v[128:131], v150
	ds_read_b128 v[132:135], v150 offset:1024
	ds_read_b128 v[136:139], v150 offset:2048
	ds_read_b128 v[166:169], v150 offset:3072
	s_add_u32 s40, s40, 0x40000
	s_addc_u32 s41, s41, 0
	s_mov_b32 m0, s52
	ds_read_b128 v[170:173], v182 offset:32768
	ds_read_b128 v[174:177], v182 offset:33792
	ds_read_b128 v[192:195], v182 offset:34816
	ds_read_b128 v[196:199], v182 offset:35840
	ds_read_b128 v[200:203], v182 offset:36864
	ds_read_b128 v[204:207], v182 offset:37888
	ds_read_b128 v[208:211], v182 offset:38912
	ds_read_b128 v[212:215], v182 offset:39936
	global_load_lds_dwordx4 v142, s[40:41]
	s_mov_b32 m0, s53
	s_nop 0
	global_load_lds_dwordx4 v146, s[40:41]
	s_waitcnt lgkmcnt(8)
	s_barrier
	s_waitcnt lgkmcnt(0)
	s_setprio 1
	s_waitcnt lgkmcnt(0)
	v_mfma_f32_16x16x32_bf16 v[124:127], v[128:131], v[170:173], v[124:127]
	v_mfma_f32_16x16x32_bf16 v[116:119], v[136:139], v[170:173], v[116:119]
	v_mfma_f32_16x16x32_bf16 v[108:111], v[128:131], v[192:195], v[108:111]
	v_mfma_f32_16x16x32_bf16 v[100:103], v[136:139], v[192:195], v[100:103]
	v_mfma_f32_16x16x32_bf16 v[92:95], v[128:131], v[200:203], v[92:95]
	v_mfma_f32_16x16x32_bf16 v[84:87], v[136:139], v[200:203], v[84:87]
	v_mfma_f32_16x16x32_bf16 v[76:79], v[128:131], v[208:211], v[76:79]
	v_mfma_f32_16x16x32_bf16 v[68:71], v[136:139], v[208:211], v[68:71]
	v_mfma_f32_16x16x32_bf16 v[124:127], v[132:135], v[174:177], v[124:127]
	v_mfma_f32_16x16x32_bf16 v[116:119], v[166:169], v[174:177], v[116:119]
	v_mfma_f32_16x16x32_bf16 v[108:111], v[132:135], v[196:199], v[108:111]
	v_mfma_f32_16x16x32_bf16 v[100:103], v[166:169], v[196:199], v[100:103]
	v_mfma_f32_16x16x32_bf16 v[92:95], v[132:135], v[204:207], v[92:95]
	v_mfma_f32_16x16x32_bf16 v[84:87], v[166:169], v[204:207], v[84:87]
	v_mfma_f32_16x16x32_bf16 v[76:79], v[132:135], v[212:215], v[76:79]
	v_mfma_f32_16x16x32_bf16 v[68:71], v[166:169], v[212:215], v[68:71]
	s_setprio 0
	s_barrier
	s_add_i32 s40, 0, 0x1c000
	s_add_i32 s41, s76, s46
	v_add_u32_e32 v150, s40, v179
	s_mov_b32 m0, s41
	ds_read_b128 v[216:219], v150
	ds_read_b128 v[220:223], v150 offset:1024
	ds_read_b128 v[224:227], v150 offset:2048
	ds_read_b128 v[228:231], v150 offset:3072
	global_load_lds_dwordx4 v144, s[80:81]
	s_add_i32 m0, s41, 0x2000
	s_nop 0
	global_load_lds_dwordx4 v148, s[80:81]
	s_barrier
	s_waitcnt lgkmcnt(0)
	s_setprio 1
	s_waitcnt lgkmcnt(0)
	v_mfma_f32_16x16x32_bf16 v[120:123], v[216:219], v[170:173], v[120:123]
	v_mfma_f32_16x16x32_bf16 v[112:115], v[224:227], v[170:173], v[112:115]
	v_mfma_f32_16x16x32_bf16 v[104:107], v[216:219], v[192:195], v[104:107]
	v_mfma_f32_16x16x32_bf16 v[96:99], v[224:227], v[192:195], v[96:99]
	v_mfma_f32_16x16x32_bf16 v[88:91], v[216:219], v[200:203], v[88:91]
	v_mfma_f32_16x16x32_bf16 v[80:83], v[224:227], v[200:203], v[80:83]
	v_mfma_f32_16x16x32_bf16 v[72:75], v[216:219], v[208:211], v[72:75]
	v_mfma_f32_16x16x32_bf16 v[64:67], v[224:227], v[208:211], v[64:67]
	v_mfma_f32_16x16x32_bf16 v[120:123], v[220:223], v[174:177], v[120:123]
	v_mfma_f32_16x16x32_bf16 v[112:115], v[228:231], v[174:177], v[112:115]
	v_mfma_f32_16x16x32_bf16 v[104:107], v[220:223], v[196:199], v[104:107]
	v_mfma_f32_16x16x32_bf16 v[96:99], v[228:231], v[196:199], v[96:99]
	v_mfma_f32_16x16x32_bf16 v[88:91], v[220:223], v[204:207], v[88:91]
	v_mfma_f32_16x16x32_bf16 v[80:83], v[228:231], v[204:207], v[80:83]
	v_mfma_f32_16x16x32_bf16 v[72:75], v[220:223], v[212:215], v[72:75]
	v_mfma_f32_16x16x32_bf16 v[64:67], v[228:231], v[212:215], v[64:67]
	s_setprio 0
	s_mov_b32 m0, s55
	s_barrier
	ds_read_b128 v[170:173], v182 offset:49152
	ds_read_b128 v[174:177], v182 offset:50176
	ds_read_b128 v[192:195], v182 offset:51200
	ds_read_b128 v[196:199], v182 offset:52224
	ds_read_b128 v[200:203], v182 offset:53248
	ds_read_b128 v[204:207], v182 offset:54272
	ds_read_b128 v[208:211], v182 offset:55296
	ds_read_b128 v[212:215], v182 offset:56320
	global_load_lds_dwordx4 v142, s[82:83]
	s_mov_b32 m0, s56
	s_nop 0
	global_load_lds_dwordx4 v146, s[82:83]
	s_barrier
	s_waitcnt lgkmcnt(0)
	s_setprio 1
	s_waitcnt lgkmcnt(0)
	v_mfma_f32_16x16x32_bf16 v[60:63], v[128:131], v[170:173], v[60:63]
	v_mfma_f32_16x16x32_bf16 v[52:55], v[136:139], v[170:173], v[52:55]
	v_mfma_f32_16x16x32_bf16 v[44:47], v[128:131], v[192:195], v[44:47]
	v_mfma_f32_16x16x32_bf16 v[36:39], v[136:139], v[192:195], v[36:39]
	v_mfma_f32_16x16x32_bf16 v[28:31], v[128:131], v[200:203], v[28:31]
	v_mfma_f32_16x16x32_bf16 v[20:23], v[136:139], v[200:203], v[20:23]
	v_mfma_f32_16x16x32_bf16 v[12:15], v[128:131], v[208:211], v[12:15]
	v_mfma_f32_16x16x32_bf16 v[4:7], v[136:139], v[208:211], v[4:7]
	v_mfma_f32_16x16x32_bf16 v[60:63], v[132:135], v[174:177], v[60:63]
	v_mfma_f32_16x16x32_bf16 v[52:55], v[166:169], v[174:177], v[52:55]
	v_mfma_f32_16x16x32_bf16 v[44:47], v[132:135], v[196:199], v[44:47]
	v_mfma_f32_16x16x32_bf16 v[36:39], v[166:169], v[196:199], v[36:39]
	v_mfma_f32_16x16x32_bf16 v[28:31], v[132:135], v[204:207], v[28:31]
	v_mfma_f32_16x16x32_bf16 v[20:23], v[166:169], v[204:207], v[20:23]
	v_mfma_f32_16x16x32_bf16 v[12:15], v[132:135], v[212:215], v[12:15]
	v_mfma_f32_16x16x32_bf16 v[4:7], v[166:169], v[212:215], v[4:7]
	s_setprio 0
	s_barrier
	s_add_u32 s38, s38, 0x40080
	s_addc_u32 s39, s39, 0
	s_add_i32 s40, s40, s46
	s_mov_b32 m0, s40
	s_nop 0
	global_load_lds_dwordx4 v144, s[38:39]
	s_add_i32 m0, s40, 0x2000
	s_nop 0
	global_load_lds_dwordx4 v148, s[38:39]
	s_waitcnt vmcnt(6)
	s_barrier
	s_setprio 1
	v_mfma_f32_16x16x32_bf16 v[56:59], v[216:219], v[170:173], v[56:59]
	v_mfma_f32_16x16x32_bf16 v[48:51], v[224:227], v[170:173], v[48:51]
	v_mfma_f32_16x16x32_bf16 v[40:43], v[216:219], v[192:195], v[40:43]
	v_mfma_f32_16x16x32_bf16 v[32:35], v[224:227], v[192:195], v[32:35]
	v_mfma_f32_16x16x32_bf16 v[24:27], v[216:219], v[200:203], v[24:27]
	v_mfma_f32_16x16x32_bf16 v[16:19], v[224:227], v[200:203], v[16:19]
	v_mfma_f32_16x16x32_bf16 v[8:11], v[216:219], v[208:211], v[8:11]
	v_mfma_f32_16x16x32_bf16 v[0:3], v[224:227], v[208:211], v[0:3]
	v_mfma_f32_16x16x32_bf16 v[56:59], v[220:223], v[174:177], v[56:59]
	v_mfma_f32_16x16x32_bf16 v[48:51], v[228:231], v[174:177], v[48:51]
	v_mfma_f32_16x16x32_bf16 v[40:43], v[220:223], v[196:199], v[40:43]
	v_mfma_f32_16x16x32_bf16 v[32:35], v[228:231], v[196:199], v[32:35]
	v_mfma_f32_16x16x32_bf16 v[24:27], v[220:223], v[204:207], v[24:27]
	v_mfma_f32_16x16x32_bf16 v[16:19], v[228:231], v[204:207], v[16:19]
	v_mfma_f32_16x16x32_bf16 v[8:11], v[220:223], v[212:215], v[8:11]
	v_mfma_f32_16x16x32_bf16 v[0:3], v[228:231], v[212:215], v[0:3]
	s_setprio 0
	s_add_i32 s75, s75, 2
	s_add_u32 s8, s8, 0x100
	s_addc_u32 s9, s9, 0
	s_add_u32 s73, s73, 0x100
	s_addc_u32 s74, s74, 0
	s_cmp_gt_u32 s75, 13
	s_barrier
	s_cbranch_scc0 .LBB0_359
	s_cmpk_gt_u32 s45, 0xff
	s_cbranch_scc1 .Lg359_nox
	s_barrier
.Lg359_nox:
	s_lshl_b32 s19, s7, 10
	v_lshl_add_u32 v166, s6, 8, v178
	s_cmp_gt_i32 s36, 2
	s_mov_b64 s[6:7], -1
	s_cbranch_scc0 .LBB0_373
	s_cmp_gt_u32 s36, 8
	s_cbranch_scc1 .LBB0_372
	s_cmp_lt_i32 s36, 4
	s_cbranch_scc1 .LBB0_406
	s_cmp_lg_u32 s36, 4
	s_mov_b64 s[8:9], -1
	s_cbranch_scc0 .LBB0_369
	s_lshl_b32 s6, s36, 9
	s_add_u32 s21, s26, s6
	s_addc_u32 s38, s27, 0
	s_cmp_gt_u32 s36, 6
	s_cbranch_scc0 .LBB0_366
	s_add_u32 s6, s21, 0x13fff200
	s_addc_u32 s7, s38, 0
	s_mov_b64 s[8:9], 0

.LBB0_448:
	s_waitcnt vmcnt(0)
	s_cmpk_gt_u32 s45, 0xff
	s_cbranch_scc1 .LBB0_450
.LBB0_450:
	s_barrier

.LBB0_778:
	s_or_b64 exec, exec, s[4:5]
	s_waitcnt lgkmcnt(0)
	s_barrier
	s_load_dwordx2 s[4:5], s[0:1], 0xa8
	v_mov_b32_e32 v8, v240
	s_waitcnt lgkmcnt(0)
	v_mov_b32_e32 v0, s4
	v_mov_b32_e32 v1, s5
	s_nop 0
	v_readfirstlane_b32 s6, v0
	v_mov_b32_e32 v0, s2
	v_readfirstlane_b32 s7, v1
	v_readfirstlane_b32 s33, v0
	v_mov_b32_e32 v0, s24
	s_cmpk_gt_i32 s33, 0x2ff
	v_readfirstlane_b32 s36, v0
	v_readfirstlane_b32 s37, v8
	s_cbranch_scc1 .LBB0_806
	v_lshlrev_b32_e32 v0, 4, v8
	v_add_u32_e32 v1, 0x2000, v0
	v_ashrrev_i32_e32 v2, 31, v1
	v_lshrrev_b32_e32 v2, 22, v2
	v_add_u32_e32 v2, v1, v2
	v_ashrrev_i32_e32 v9, 10, v2
	v_mul_i32_i24_e32 v2, 0x400, v9
	v_sub_u32_e32 v1, v1, v2
	v_lshrrev_b32_e32 v2, 4, v1
	v_bitop3_b32 v1, v2, v1, 32 bitop3:0x6c
	v_ashrrev_i32_e32 v2, 31, v1
	v_lshrrev_b32_e32 v2, 26, v2
	v_add_u32_e32 v2, v1, v2
	v_lshlrev_b32_e32 v3, 3, v9
	v_ashrrev_i32_e32 v10, 6, v2
	v_and_b32_e32 v3, -16, v3
	v_add_u32_e32 v3, v10, v3
	v_and_b32_e32 v4, 3, v10
	s_mov_b32 s4, 0x1fffe0
	v_lshrrev_b32_e32 v5, 2, v3
	v_lshlrev_b32_e32 v6, 1, v3
	v_and_b32_e32 v2, 0xc0, v2
	v_and_or_b32 v4, v3, s4, v4
	v_and_b32_e32 v5, 4, v5
	v_and_b32_e32 v6, 24, v6
	v_sub_u32_e32 v1, v1, v2
	v_mov_b32_e32 v2, 1
	v_or3_b32 v4, v4, v5, v6
	v_lshlrev_b32_e32 v5, 5, v9
	v_ashrrev_i16_sdwa v1, v2, sext(v1) dst_sel:DWORD dst_unused:UNUSED_PAD src0_sel:DWORD src1_sel:BYTE_0
	v_and_b32_e32 v5, 32, v5
	v_bfe_i32 v11, v1, 0, 16
	v_add_lshl_u32 v1, v5, v11, 1
	v_lshl_add_u32 v128, v4, 11, v1
	v_lshl_add_u32 v130, v3, 11, v1
	v_bfe_i32 v1, v8, 27, 1
	v_lshrrev_b32_e32 v1, 22, v1
	v_add_u32_e32 v1, v0, v1
	v_and_b32_e32 v1, 0xfffffc00, v1
	v_sub_u32_e32 v0, v0, v1
	v_lshrrev_b32_e32 v1, 4, v0
	v_ashrrev_i32_e32 v3, 31, v8
	v_bitop3_b32 v0, v1, v0, 32 bitop3:0x6c
	v_lshrrev_b32_e32 v3, 26, v3
	v_ashrrev_i32_e32 v1, 31, v0
	v_add_u32_e32 v3, v8, v3
	s_add_u32 s38, s6, 0x17600000
	v_lshrrev_b32_e32 v1, 26, v1
	v_ashrrev_i32_e32 v13, 6, v3
	s_addc_u32 s39, s7, 0
	v_add_u32_e32 v1, v0, v1
	v_lshlrev_b32_e32 v3, 3, v13
	s_add_u32 s40, s6, 0x1580000
	v_ashrrev_i32_e32 v12, 6, v1
	v_and_b32_e32 v3, -16, v3
	s_addc_u32 s41, s7, 0
	v_add_u32_e32 v3, v12, v3
	v_and_b32_e32 v4, 3, v12
	s_ashr_i32 s43, s33, 31
	v_and_or_b32 v4, v3, s4, v4
	s_lshr_b32 s4, s43, 29
	s_add_i32 s4, s33, s4
	s_ashr_i32 s14, s37, 6
	s_ashr_i32 s8, s4, 3
	s_and_b32 s4, s4, -8
	s_ashr_i32 s5, s37, 8
	s_lshl_b32 s42, s14, 10
	s_sub_i32 s4, s33, s4
	s_cmp_lt_i32 s4, 0
	s_movk_i32 s44, 0x61
	s_cselect_b32 s9, s44, 0x60
	s_mul_i32 s4, s4, s9
	s_add_i32 s4, s4, s8
	s_ashr_i32 s8, s4, 31
	s_lshr_b32 s8, s8, 27
	s_add_i32 s8, s4, s8
	s_ashr_i32 s9, s8, 5
	s_and_b32 s8, s8, 0xffe0
	s_sub_i32 s8, s4, s8
	s_bfe_i32 s4, s8, 0x80000
	s_bfe_u32 s4, s4, 0x3000c
	s_add_i32 s10, s8, s4
	s_bfe_i32 s4, s10, 0x80000
	s_and_b32 s10, s10, 0xf8
	s_sub_i32 s8, s8, s10
	s_lshl_b32 s9, s9, 3
	s_sext_i32_i16 s4, s4
	s_sext_i32_i8 s8, s8
	v_lshrrev_b32_e32 v5, 2, v3
	v_lshlrev_b32_e32 v6, 1, v3
	v_and_b32_e32 v1, 0xc0, v1
	s_lshr_b32 s4, s4, 3
	s_add_i32 s8, s9, s8
	v_and_b32_e32 v5, 4, v5
	v_and_b32_e32 v6, 24, v6
	v_sub_u32_e32 v0, v0, v1
	s_ashr_i32 s9, s8, 31
	s_bfe_i64 s[12:13], s[4:5], 0x100000
	v_or3_b32 v4, v4, v5, v6
	v_lshlrev_b32_e32 v5, 5, v13
	v_ashrrev_i16_sdwa v0, v2, sext(v0) dst_sel:DWORD dst_unused:UNUSED_PAD src0_sel:DWORD src1_sel:BYTE_0
	s_lshl_b64 s[10:11], s[8:9], 19
	s_lshl_b64 s[12:13], s[12:13], 19
	v_and_b32_e32 v5, 32, v5
	v_bfe_i32 v14, v0, 0, 16
	s_add_u32 s30, s40, s12
	v_add_lshl_u32 v0, v5, v14, 1
	s_addc_u32 s31, s41, s13
	s_add_i32 s45, s42, 0
	v_lshl_add_u32 v132, v4, 11, v0
	s_add_i32 m0, s45, 0x10000
	v_lshl_add_u32 v134, v3, 11, v0
	global_load_lds_dwordx4 v132, s[30:31]
	s_add_i32 m0, s45, 0x12000
	s_add_u32 s28, s38, s10
	global_load_lds_dwordx4 v128, s[30:31]
	s_addc_u32 s29, s39, s11
	s_mov_b32 m0, s45
	s_add_i32 s46, s45, 0x2000
	global_load_lds_dwordx4 v134, s[28:29]
	s_mov_b32 m0, s46
	s_add_u32 s10, s30, 0x40000
	global_load_lds_dwordx4 v130, s[28:29]
	s_addc_u32 s11, s31, 0
	s_add_i32 m0, s45, 0x14000
	v_mov_b32_e32 v133, 0
	global_load_lds_dwordx4 v132, s[10:11]
	s_add_i32 m0, s45, 0x16000
	v_mov_b32_e32 v129, v133
	global_load_lds_dwordx4 v128, s[10:11]
	s_add_u32 s10, s28, 0x40000
	s_addc_u32 s11, s29, 0
	s_add_i32 s47, s45, 0x4000
	s_mov_b32 m0, s47
	s_add_i32 s48, s45, 0x6000
	global_load_lds_dwordx4 v134, s[10:11]
	s_mov_b32 m0, s48
	v_mov_b32_e32 v135, v133
	global_load_lds_dwordx4 v130, s[10:11]
	v_mov_b32_e32 v131, v133
	s_mov_b32 s9, 0
	v_lshl_add_u64 v[6:7], s[30:31], 0, v[132:133]
	v_lshl_add_u64 v[4:5], s[30:31], 0, v[128:129]
	v_lshl_add_u64 v[2:3], s[28:29], 0, v[134:135]
	s_cmp_lg_u32 s5, 1
	v_lshl_add_u64 v[0:1], s[28:29], 0, v[130:131]
	s_cbranch_scc1 .LBB0_781
.LBB0_781:
	s_add_u32 s10, s6, 0x3800000
	s_addc_u32 s11, s7, 0
	s_add_u32 s12, s6, 0x3000000
	s_addc_u32 s13, s7, 0
	s_and_b32 s49, s14, 3
	s_mov_b64 s[14:15], 0x80
	s_add_i32 m0, s45, 0x18000
	v_lshl_add_u64 v[6:7], v[6:7], 0, s[14:15]
	s_lshl_b32 s16, s5, 13
	s_lshl_b32 s17, s49, 12
	s_waitcnt vmcnt(4)
	s_barrier
	global_load_lds_dwordx4 v[6:7], off
	v_lshl_add_u64 v[4:5], v[4:5], 0, s[14:15]
	s_add_i32 m0, s45, 0x1a000
	s_add_i32 s50, s45, 0x8000
	s_add_i32 s51, s45, 0xa000
	global_load_lds_dwordx4 v[4:5], off
	v_lshl_add_u64 v[2:3], v[2:3], 0, s[14:15]
	s_mov_b32 m0, s50
	s_add_u32 s6, s30, 0x40080
	global_load_lds_dwordx4 v[2:3], off
	v_lshl_add_u64 v[0:1], v[0:1], 0, s[14:15]
	s_mov_b32 m0, s51
	s_addc_u32 s7, s31, 0
	global_load_lds_dwordx4 v[0:1], off
	s_add_i32 m0, s45, 0x1c000
	v_lshl_add_u64 v[0:1], s[6:7], 0, v[132:133]
	global_load_lds_dwordx4 v[0:1], off
	v_lshl_add_u64 v[0:1], s[6:7], 0, v[128:129]
	s_add_i32 m0, s45, 0x1e000
	s_sext_i32_i8 s56, s4
	global_load_lds_dwordx4 v[0:1], off
	v_bfe_u32 v0, v8, 4, 2
	v_and_b32_e32 v1, 15, v8
	v_lshlrev_b32_e32 v3, 4, v0
	v_lshl_or_b32 v148, s5, 6, v1
	v_lshlrev_b32_e32 v2, 3, v0
	v_lshl_or_b32 v1, v1, 6, v3
	v_lshlrev_b32_e32 v3, 2, v8
	v_cmp_eq_u32_e64 s[4:5], 0, v0
	v_lshlrev_b32_e32 v0, 14, v13
	v_and_b32_e32 v3, 32, v3
	v_and_b32_e32 v0, 0xffff8000, v0
	v_bitop3_b32 v4, v1, s16, v3 bitop3:0xde
	v_bitop3_b32 v149, s17, v1, v3 bitop3:0xf6
	v_lshl_add_u32 v0, v12, 11, v0
	v_and_b32_e32 v1, 1, v13
	v_lshl_or_b32 v0, v1, 6, v0
	v_lshl_add_u32 v136, v14, 1, v0
	v_lshlrev_b32_e32 v0, 14, v9
	v_and_b32_e32 v0, 0xffff8000, v0
	s_waitcnt vmcnt(6)
	v_lshl_add_u32 v0, v10, 11, v0
	v_and_b32_e32 v1, 1, v9
	v_lshl_or_b32 v0, v1, 6, v0
	s_add_i32 s53, 0, 0x10000
	s_add_i32 s54, 0, 0x14000
	v_lshl_or_b32 v150, s49, 5, v2
	s_ashr_i32 s52, s36, 31
	v_mov_b32_e32 v137, v133
	v_lshl_add_u32 v138, v11, 1, v0
	v_mov_b32_e32 v139, v133
	v_mov_b64_e32 v[140:141], 0x300
	v_mov_b64_e32 v[142:143], 0x2ff
	v_add_u32_e32 v151, s53, v149
	v_add_u32_e32 v152, 0, v4
	v_add_u32_e32 v153, s54, v149
	v_mbcnt_hi_u32_b32 v154, -1, v241
	s_mov_b32 s55, 0
	s_barrier
	s_branch .LBB0_783

.LBB0_785:
	s_ashr_i32 s19, s18, 31
	v_cmp_lt_i64_e32 vcc, s[20:21], v[140:141]
	s_lshl_b64 s[20:21], s[18:19], 19
	s_add_u32 s20, s38, s20
	s_addc_u32 s21, s39, s21
	s_and_b64 s[26:27], vcc, exec
	s_cselect_b32 s19, s21, s29
	s_cselect_b32 s57, s20, s28
	s_ashr_i32 s17, s16, 31
	s_lshl_b64 s[26:27], s[16:17], 19
	s_add_u32 s26, s40, s26
	s_addc_u32 s27, s41, s27
	s_and_b64 s[34:35], vcc, exec
	s_cselect_b32 s17, s27, s31
	s_cselect_b32 s58, s26, s30
	s_add_u32 s28, s28, 0x40080
	s_addc_u32 s29, s29, 0
	s_add_u32 s59, s30, 0x100
	v_mov_b32_e32 v0, 0
	s_addc_u32 s60, s31, 0
	s_mov_b32 s61, -2
	s_waitcnt lgkmcnt(0)
	v_mov_b32_e32 v1, v0
	v_mov_b32_e32 v2, v0
	v_mov_b32_e32 v3, v0
	v_mov_b32_e32 v4, v0
	v_mov_b32_e32 v5, v0
	v_mov_b32_e32 v6, v0
	v_mov_b32_e32 v7, v0
	v_mov_b32_e32 v16, v0
	v_mov_b32_e32 v17, v0
	v_mov_b32_e32 v18, v0
	v_mov_b32_e32 v19, v0
	v_mov_b32_e32 v20, v0
	v_mov_b32_e32 v21, v0
	v_mov_b32_e32 v22, v0
	v_mov_b32_e32 v23, v0
	v_mov_b32_e32 v32, v0
	v_mov_b32_e32 v33, v0
	v_mov_b32_e32 v34, v0
	v_mov_b32_e32 v35, v0
	v_mov_b32_e32 v36, v0
	v_mov_b32_e32 v37, v0
	v_mov_b32_e32 v38, v0
	v_mov_b32_e32 v39, v0
	v_mov_b32_e32 v48, v0
	v_mov_b32_e32 v49, v0
	v_mov_b32_e32 v50, v0
	v_mov_b32_e32 v51, v0
	v_mov_b32_e32 v52, v0
	v_mov_b32_e32 v53, v0
	v_mov_b32_e32 v54, v0
	v_mov_b32_e32 v55, v0
	v_mov_b32_e32 v8, v0
	v_mov_b32_e32 v9, v0
	v_mov_b32_e32 v10, v0
	v_mov_b32_e32 v11, v0
	v_mov_b32_e32 v12, v0
	v_mov_b32_e32 v13, v0
	v_mov_b32_e32 v14, v0
	v_mov_b32_e32 v15, v0
	v_mov_b32_e32 v24, v0
	v_mov_b32_e32 v25, v0
	v_mov_b32_e32 v26, v0
	v_mov_b32_e32 v27, v0
	v_mov_b32_e32 v28, v0
	v_mov_b32_e32 v29, v0
	v_mov_b32_e32 v30, v0
	v_mov_b32_e32 v31, v0
	v_mov_b32_e32 v40, v0
	v_mov_b32_e32 v41, v0
	v_mov_b32_e32 v42, v0
	v_mov_b32_e32 v43, v0
	v_mov_b32_e32 v44, v0
	v_mov_b32_e32 v45, v0
	v_mov_b32_e32 v46, v0
	v_mov_b32_e32 v47, v0
	v_mov_b32_e32 v56, v0
	v_mov_b32_e32 v57, v0
	v_mov_b32_e32 v58, v0
	v_mov_b32_e32 v59, v0
	v_mov_b32_e32 v60, v0
	v_mov_b32_e32 v61, v0
	v_mov_b32_e32 v62, v0
	v_mov_b32_e32 v63, v0
	v_mov_b32_e32 v64, v0
	v_mov_b32_e32 v65, v0
	v_mov_b32_e32 v66, v0
	v_mov_b32_e32 v67, v0
	v_mov_b32_e32 v68, v0
	v_mov_b32_e32 v69, v0
	v_mov_b32_e32 v70, v0
	v_mov_b32_e32 v71, v0
	v_mov_b32_e32 v80, v0
	v_mov_b32_e32 v81, v0
	v_mov_b32_e32 v82, v0
	v_mov_b32_e32 v83, v0
	v_mov_b32_e32 v84, v0
	v_mov_b32_e32 v85, v0
	v_mov_b32_e32 v86, v0
	v_mov_b32_e32 v87, v0
	v_mov_b32_e32 v96, v0
	v_mov_b32_e32 v97, v0
	v_mov_b32_e32 v98, v0
	v_mov_b32_e32 v99, v0
	v_mov_b32_e32 v100, v0
	v_mov_b32_e32 v101, v0
	v_mov_b32_e32 v102, v0
	v_mov_b32_e32 v103, v0
	v_mov_b32_e32 v112, v0
	v_mov_b32_e32 v113, v0
	v_mov_b32_e32 v114, v0
	v_mov_b32_e32 v115, v0
	v_mov_b32_e32 v116, v0
	v_mov_b32_e32 v117, v0
	v_mov_b32_e32 v118, v0
	v_mov_b32_e32 v119, v0
	v_mov_b32_e32 v72, v0
	v_mov_b32_e32 v73, v0
	v_mov_b32_e32 v74, v0
	v_mov_b32_e32 v75, v0
	v_mov_b32_e32 v76, v0
	v_mov_b32_e32 v77, v0
	v_mov_b32_e32 v78, v0
	v_mov_b32_e32 v79, v0
	v_mov_b32_e32 v88, v0
	v_mov_b32_e32 v89, v0
	v_mov_b32_e32 v90, v0
	v_mov_b32_e32 v91, v0
	v_mov_b32_e32 v92, v0
	v_mov_b32_e32 v93, v0
	v_mov_b32_e32 v94, v0
	v_mov_b32_e32 v95, v0
	v_mov_b32_e32 v104, v0
	v_mov_b32_e32 v105, v0
	v_mov_b32_e32 v106, v0
	v_mov_b32_e32 v107, v0
	v_mov_b32_e32 v108, v0
	v_mov_b32_e32 v109, v0
	v_mov_b32_e32 v110, v0
	v_mov_b32_e32 v111, v0
	v_mov_b32_e32 v120, v0
	v_mov_b32_e32 v121, v0
	v_mov_b32_e32 v122, v0
	v_mov_b32_e32 v123, v0
	v_mov_b32_e32 v124, v0
	v_mov_b32_e32 v125, v0
	v_mov_b32_e32 v126, v0
	v_mov_b32_e32 v127, v0
	s_cmpk_lt_u32 s37, 0x100
	s_cbranch_scc1 .Lg786_noy
	s_barrier
.Lg786_noy:
.LBB0_786:
	ds_read_b128 v[144:147], v151
	ds_read_b128 v[156:159], v151 offset:1024
	ds_read_b128 v[160:163], v151 offset:2048
	ds_read_b128 v[164:167], v151 offset:3072
	s_add_u32 s30, s28, 0xfffc0080
	s_addc_u32 s31, s29, -1
	s_cmp_eq_u32 s61, 12
	s_cselect_b32 s35, s19, s31
	s_cselect_b32 s34, s57, s30
	s_cselect_b32 s31, s17, s60
	s_cselect_b32 s30, s58, s59
	s_add_i32 m0, s45, 0xc000
	ds_read_b128 v[168:171], v152
	ds_read_b128 v[172:175], v152 offset:1024
	ds_read_b128 v[176:179], v152 offset:2048
	ds_read_b128 v[180:183], v152 offset:3072
	ds_read_b128 v[184:187], v152 offset:4096
	ds_read_b128 v[188:191], v152 offset:5120
	ds_read_b128 v[192:195], v152 offset:6144
	ds_read_b128 v[196:199], v152 offset:7168
	global_load_lds_dwordx4 v136, s[28:29]
	s_add_i32 m0, s45, 0xe000
	s_nop 0
	global_load_lds_dwordx4 v138, s[28:29]
	s_waitcnt lgkmcnt(8)
	s_barrier
	s_waitcnt lgkmcnt(0)
	s_setprio 1
	s_waitcnt lgkmcnt(0)
	v_mfma_f32_16x16x32_bf16 v[124:127], v[144:147], v[168:171], v[124:127]
	v_mfma_f32_16x16x32_bf16 v[120:123], v[160:163], v[168:171], v[120:123]
	v_mfma_f32_16x16x32_bf16 v[108:111], v[144:147], v[176:179], v[108:111]
	v_mfma_f32_16x16x32_bf16 v[104:107], v[160:163], v[176:179], v[104:107]
	v_mfma_f32_16x16x32_bf16 v[92:95], v[144:147], v[184:187], v[92:95]
	v_mfma_f32_16x16x32_bf16 v[88:91], v[160:163], v[184:187], v[88:91]
	v_mfma_f32_16x16x32_bf16 v[76:79], v[144:147], v[192:195], v[76:79]
	v_mfma_f32_16x16x32_bf16 v[72:75], v[160:163], v[192:195], v[72:75]
	v_mfma_f32_16x16x32_bf16 v[124:127], v[156:159], v[172:175], v[124:127]
	v_mfma_f32_16x16x32_bf16 v[120:123], v[164:167], v[172:175], v[120:123]
	v_mfma_f32_16x16x32_bf16 v[108:111], v[156:159], v[180:183], v[108:111]
	v_mfma_f32_16x16x32_bf16 v[104:107], v[164:167], v[180:183], v[104:107]
	v_mfma_f32_16x16x32_bf16 v[92:95], v[156:159], v[188:191], v[92:95]
	v_mfma_f32_16x16x32_bf16 v[88:91], v[164:167], v[188:191], v[88:91]
	v_mfma_f32_16x16x32_bf16 v[76:79], v[156:159], v[196:199], v[76:79]
	v_mfma_f32_16x16x32_bf16 v[72:75], v[164:167], v[196:199], v[72:75]
	s_setprio 0
	s_barrier
	s_add_i32 s62, s53, s42
	s_add_u32 s80, s30, 0x80
	s_addc_u32 s81, s31, 0
	s_mov_b32 m0, s62
	ds_read_b128 v[200:203], v153
	ds_read_b128 v[204:207], v153 offset:1024
	ds_read_b128 v[208:211], v153 offset:2048
	ds_read_b128 v[212:215], v153 offset:3072
	global_load_lds_dwordx4 v132, s[30:31]
	s_add_i32 m0, s62, 0x2000
	s_nop 0
	global_load_lds_dwordx4 v128, s[30:31]
	s_barrier
	s_waitcnt lgkmcnt(0)
	s_setprio 1
	s_waitcnt lgkmcnt(0)
	v_mfma_f32_16x16x32_bf16 v[116:119], v[200:203], v[168:171], v[116:119]
	v_mfma_f32_16x16x32_bf16 v[112:115], v[208:211], v[168:171], v[112:115]
	v_mfma_f32_16x16x32_bf16 v[100:103], v[200:203], v[176:179], v[100:103]
	v_mfma_f32_16x16x32_bf16 v[96:99], v[208:211], v[176:179], v[96:99]
	v_mfma_f32_16x16x32_bf16 v[84:87], v[200:203], v[184:187], v[84:87]
	v_mfma_f32_16x16x32_bf16 v[80:83], v[208:211], v[184:187], v[80:83]
	v_mfma_f32_16x16x32_bf16 v[68:71], v[200:203], v[192:195], v[68:71]
	v_mfma_f32_16x16x32_bf16 v[64:67], v[208:211], v[192:195], v[64:67]
	v_mfma_f32_16x16x32_bf16 v[116:119], v[204:207], v[172:175], v[116:119]
	v_mfma_f32_16x16x32_bf16 v[112:115], v[212:215], v[172:175], v[112:115]
	v_mfma_f32_16x16x32_bf16 v[100:103], v[204:207], v[180:183], v[100:103]
	v_mfma_f32_16x16x32_bf16 v[96:99], v[212:215], v[180:183], v[96:99]
	v_mfma_f32_16x16x32_bf16 v[84:87], v[204:207], v[188:191], v[84:87]
	v_mfma_f32_16x16x32_bf16 v[80:83], v[212:215], v[188:191], v[80:83]
	v_mfma_f32_16x16x32_bf16 v[68:71], v[204:207], v[196:199], v[68:71]
	v_mfma_f32_16x16x32_bf16 v[64:67], v[212:215], v[196:199], v[64:67]
	s_setprio 0
	s_mov_b32 m0, s45
	s_add_u32 s82, s34, 0x80
	s_addc_u32 s83, s35, 0
	s_barrier
	ds_read_b128 v[168:171], v152 offset:16384
	ds_read_b128 v[172:175], v152 offset:17408
	ds_read_b128 v[176:179], v152 offset:18432
	ds_read_b128 v[180:183], v152 offset:19456
	ds_read_b128 v[184:187], v152 offset:20480
	ds_read_b128 v[188:191], v152 offset:21504
	ds_read_b128 v[192:195], v152 offset:22528
	ds_read_b128 v[196:199], v152 offset:23552
	global_load_lds_dwordx4 v134, s[34:35]
	s_mov_b32 m0, s46
	s_nop 0
	global_load_lds_dwordx4 v130, s[34:35]
	s_barrier
	s_waitcnt lgkmcnt(0)
	s_setprio 1
	s_waitcnt lgkmcnt(0)
	v_mfma_f32_16x16x32_bf16 v[60:63], v[144:147], v[168:171], v[60:63]
	v_mfma_f32_16x16x32_bf16 v[56:59], v[160:163], v[168:171], v[56:59]
	v_mfma_f32_16x16x32_bf16 v[44:47], v[144:147], v[176:179], v[44:47]
	v_mfma_f32_16x16x32_bf16 v[40:43], v[160:163], v[176:179], v[40:43]
	v_mfma_f32_16x16x32_bf16 v[28:31], v[144:147], v[184:187], v[28:31]
	v_mfma_f32_16x16x32_bf16 v[24:27], v[160:163], v[184:187], v[24:27]
	v_mfma_f32_16x16x32_bf16 v[12:15], v[144:147], v[192:195], v[12:15]
	v_mfma_f32_16x16x32_bf16 v[8:11], v[160:163], v[192:195], v[8:11]
	v_mfma_f32_16x16x32_bf16 v[60:63], v[156:159], v[172:175], v[60:63]
	v_mfma_f32_16x16x32_bf16 v[56:59], v[164:167], v[172:175], v[56:59]
	v_mfma_f32_16x16x32_bf16 v[44:47], v[156:159], v[180:183], v[44:47]
	v_mfma_f32_16x16x32_bf16 v[40:43], v[164:167], v[180:183], v[40:43]
	v_mfma_f32_16x16x32_bf16 v[28:31], v[156:159], v[188:191], v[28:31]
	v_mfma_f32_16x16x32_bf16 v[24:27], v[164:167], v[188:191], v[24:27]
	v_mfma_f32_16x16x32_bf16 v[12:15], v[156:159], v[196:199], v[12:15]
	v_mfma_f32_16x16x32_bf16 v[8:11], v[164:167], v[196:199], v[8:11]
	s_setprio 0
	s_barrier
	s_add_u32 s62, s30, 0x40000
	s_addc_u32 s63, s31, 0
	s_add_i32 s64, s54, s42
	s_mov_b32 m0, s64
	s_nop 0
	global_load_lds_dwordx4 v132, s[62:63]
	s_add_i32 m0, s64, 0x2000
	s_nop 0
	global_load_lds_dwordx4 v128, s[62:63]
	s_waitcnt vmcnt(6)
	s_barrier
	s_setprio 1
	v_mfma_f32_16x16x32_bf16 v[52:55], v[200:203], v[168:171], v[52:55]
	v_mfma_f32_16x16x32_bf16 v[48:51], v[208:211], v[168:171], v[48:51]
	v_mfma_f32_16x16x32_bf16 v[36:39], v[200:203], v[176:179], v[36:39]
	v_mfma_f32_16x16x32_bf16 v[32:35], v[208:211], v[176:179], v[32:35]
	v_mfma_f32_16x16x32_bf16 v[20:23], v[200:203], v[184:187], v[20:23]
	v_mfma_f32_16x16x32_bf16 v[16:19], v[208:211], v[184:187], v[16:19]
	v_mfma_f32_16x16x32_bf16 v[4:7], v[200:203], v[192:195], v[4:7]
	v_mfma_f32_16x16x32_bf16 v[0:3], v[208:211], v[192:195], v[0:3]
	v_mfma_f32_16x16x32_bf16 v[52:55], v[204:207], v[172:175], v[52:55]
	v_mfma_f32_16x16x32_bf16 v[48:51], v[212:215], v[172:175], v[48:51]
	v_mfma_f32_16x16x32_bf16 v[36:39], v[204:207], v[180:183], v[36:39]
	v_mfma_f32_16x16x32_bf16 v[32:35], v[212:215], v[180:183], v[32:35]
	v_mfma_f32_16x16x32_bf16 v[20:23], v[204:207], v[188:191], v[20:23]
	v_mfma_f32_16x16x32_bf16 v[16:19], v[212:215], v[188:191], v[16:19]
	v_mfma_f32_16x16x32_bf16 v[4:7], v[204:207], v[196:199], v[4:7]
	v_mfma_f32_16x16x32_bf16 v[0:3], v[212:215], v[196:199], v[0:3]
	s_setprio 0
	s_add_i32 s62, 0, 0x18000
	v_add_u32_e32 v155, s62, v149
	s_barrier
	ds_read_b128 v[144:147], v155
	ds_read_b128 v[156:159], v155 offset:1024
	ds_read_b128 v[160:163], v155 offset:2048
	ds_read_b128 v[164:167], v155 offset:3072
	s_add_u32 s34, s34, 0x40000
	s_addc_u32 s35, s35, 0
	s_mov_b32 m0, s47
	ds_read_b128 v[168:171], v152 offset:32768
	ds_read_b128 v[172:175], v152 offset:33792
	ds_read_b128 v[176:179], v152 offset:34816
	ds_read_b128 v[180:183], v152 offset:35840
	ds_read_b128 v[184:187], v152 offset:36864
	ds_read_b128 v[188:191], v152 offset:37888
	ds_read_b128 v[192:195], v152 offset:38912
	ds_read_b128 v[196:199], v152 offset:39936
	global_load_lds_dwordx4 v134, s[34:35]
	s_mov_b32 m0, s48
	s_nop 0
	global_load_lds_dwordx4 v130, s[34:35]
	s_waitcnt lgkmcnt(8)
	s_barrier
	s_waitcnt lgkmcnt(0)
	s_setprio 1
	s_waitcnt lgkmcnt(0)
	v_mfma_f32_16x16x32_bf16 v[124:127], v[144:147], v[168:171], v[124:127]
	v_mfma_f32_16x16x32_bf16 v[120:123], v[160:163], v[168:171], v[120:123]
	v_mfma_f32_16x16x32_bf16 v[108:111], v[144:147], v[176:179], v[108:111]
	v_mfma_f32_16x16x32_bf16 v[104:107], v[160:163], v[176:179], v[104:107]
	v_mfma_f32_16x16x32_bf16 v[92:95], v[144:147], v[184:187], v[92:95]
	v_mfma_f32_16x16x32_bf16 v[88:91], v[160:163], v[184:187], v[88:91]
	v_mfma_f32_16x16x32_bf16 v[76:79], v[144:147], v[192:195], v[76:79]
	v_mfma_f32_16x16x32_bf16 v[72:75], v[160:163], v[192:195], v[72:75]
	v_mfma_f32_16x16x32_bf16 v[124:127], v[156:159], v[172:175], v[124:127]
	v_mfma_f32_16x16x32_bf16 v[120:123], v[164:167], v[172:175], v[120:123]
	v_mfma_f32_16x16x32_bf16 v[108:111], v[156:159], v[180:183], v[108:111]
	v_mfma_f32_16x16x32_bf16 v[104:107], v[164:167], v[180:183], v[104:107]
	v_mfma_f32_16x16x32_bf16 v[92:95], v[156:159], v[188:191], v[92:95]
	v_mfma_f32_16x16x32_bf16 v[88:91], v[164:167], v[188:191], v[88:91]
	v_mfma_f32_16x16x32_bf16 v[76:79], v[156:159], v[196:199], v[76:79]
	v_mfma_f32_16x16x32_bf16 v[72:75], v[164:167], v[196:199], v[72:75]
	s_setprio 0
	s_barrier
	s_add_i32 s34, 0, 0x1c000
	s_add_i32 s35, s62, s42
	v_add_u32_e32 v155, s34, v149
	s_mov_b32 m0, s35
	ds_read_b128 v[200:203], v155
	ds_read_b128 v[204:207], v155 offset:1024
	ds_read_b128 v[208:211], v155 offset:2048
	ds_read_b128 v[212:215], v155 offset:3072
	global_load_lds_dwordx4 v132, s[80:81]
	s_add_i32 m0, s35, 0x2000
	s_nop 0
	global_load_lds_dwordx4 v128, s[80:81]
	s_barrier
	s_waitcnt lgkmcnt(0)
	s_setprio 1
	s_waitcnt lgkmcnt(0)
	v_mfma_f32_16x16x32_bf16 v[116:119], v[200:203], v[168:171], v[116:119]
	v_mfma_f32_16x16x32_bf16 v[112:115], v[208:211], v[168:171], v[112:115]
	v_mfma_f32_16x16x32_bf16 v[100:103], v[200:203], v[176:179], v[100:103]
	v_mfma_f32_16x16x32_bf16 v[96:99], v[208:211], v[176:179], v[96:99]
	v_mfma_f32_16x16x32_bf16 v[84:87], v[200:203], v[184:187], v[84:87]
	v_mfma_f32_16x16x32_bf16 v[80:83], v[208:211], v[184:187], v[80:83]
	v_mfma_f32_16x16x32_bf16 v[68:71], v[200:203], v[192:195], v[68:71]
	v_mfma_f32_16x16x32_bf16 v[64:67], v[208:211], v[192:195], v[64:67]
	v_mfma_f32_16x16x32_bf16 v[116:119], v[204:207], v[172:175], v[116:119]
	v_mfma_f32_16x16x32_bf16 v[112:115], v[212:215], v[172:175], v[112:115]
	v_mfma_f32_16x16x32_bf16 v[100:103], v[204:207], v[180:183], v[100:103]
	v_mfma_f32_16x16x32_bf16 v[96:99], v[212:215], v[180:183], v[96:99]
	v_mfma_f32_16x16x32_bf16 v[84:87], v[204:207], v[188:191], v[84:87]
	v_mfma_f32_16x16x32_bf16 v[80:83], v[212:215], v[188:191], v[80:83]
	v_mfma_f32_16x16x32_bf16 v[68:71], v[204:207], v[196:199], v[68:71]
	v_mfma_f32_16x16x32_bf16 v[64:67], v[212:215], v[196:199], v[64:67]
	s_setprio 0
	s_mov_b32 m0, s50
	s_barrier
	ds_read_b128 v[168:171], v152 offset:49152
	ds_read_b128 v[172:175], v152 offset:50176
	ds_read_b128 v[176:179], v152 offset:51200
	ds_read_b128 v[180:183], v152 offset:52224
	ds_read_b128 v[184:187], v152 offset:53248
	ds_read_b128 v[188:191], v152 offset:54272
	ds_read_b128 v[192:195], v152 offset:55296
	ds_read_b128 v[196:199], v152 offset:56320
	global_load_lds_dwordx4 v134, s[82:83]
	s_mov_b32 m0, s51
	s_nop 0
	global_load_lds_dwordx4 v130, s[82:83]
	s_barrier
	s_waitcnt lgkmcnt(0)
	s_setprio 1
	s_waitcnt lgkmcnt(0)
	v_mfma_f32_16x16x32_bf16 v[60:63], v[144:147], v[168:171], v[60:63]
	v_mfma_f32_16x16x32_bf16 v[56:59], v[160:163], v[168:171], v[56:59]
	v_mfma_f32_16x16x32_bf16 v[44:47], v[144:147], v[176:179], v[44:47]
	v_mfma_f32_16x16x32_bf16 v[40:43], v[160:163], v[176:179], v[40:43]
	v_mfma_f32_16x16x32_bf16 v[28:31], v[144:147], v[184:187], v[28:31]
	v_mfma_f32_16x16x32_bf16 v[24:27], v[160:163], v[184:187], v[24:27]
	v_mfma_f32_16x16x32_bf16 v[12:15], v[144:147], v[192:195], v[12:15]
	v_mfma_f32_16x16x32_bf16 v[8:11], v[160:163], v[192:195], v[8:11]
	v_mfma_f32_16x16x32_bf16 v[60:63], v[156:159], v[172:175], v[60:63]
	v_mfma_f32_16x16x32_bf16 v[56:59], v[164:167], v[172:175], v[56:59]
	v_mfma_f32_16x16x32_bf16 v[44:47], v[156:159], v[180:183], v[44:47]
	v_mfma_f32_16x16x32_bf16 v[40:43], v[164:167], v[180:183], v[40:43]
	v_mfma_f32_16x16x32_bf16 v[28:31], v[156:159], v[188:191], v[28:31]
	v_mfma_f32_16x16x32_bf16 v[24:27], v[164:167], v[188:191], v[24:27]
	v_mfma_f32_16x16x32_bf16 v[12:15], v[156:159], v[196:199], v[12:15]
	v_mfma_f32_16x16x32_bf16 v[8:11], v[164:167], v[196:199], v[8:11]
	s_setprio 0
	s_barrier
	s_add_u32 s30, s30, 0x40080
	s_addc_u32 s31, s31, 0
	s_add_i32 s34, s34, s42
	s_mov_b32 m0, s34
	s_nop 0
	global_load_lds_dwordx4 v132, s[30:31]
	s_add_i32 m0, s34, 0x2000
	s_nop 0
	global_load_lds_dwordx4 v128, s[30:31]
	s_waitcnt vmcnt(6)
	s_barrier
	s_setprio 1
	v_mfma_f32_16x16x32_bf16 v[52:55], v[200:203], v[168:171], v[52:55]
	v_mfma_f32_16x16x32_bf16 v[48:51], v[208:211], v[168:171], v[48:51]
	v_mfma_f32_16x16x32_bf16 v[36:39], v[200:203], v[176:179], v[36:39]
	v_mfma_f32_16x16x32_bf16 v[32:35], v[208:211], v[176:179], v[32:35]
	v_mfma_f32_16x16x32_bf16 v[20:23], v[200:203], v[184:187], v[20:23]
	v_mfma_f32_16x16x32_bf16 v[16:19], v[208:211], v[184:187], v[16:19]
	v_mfma_f32_16x16x32_bf16 v[4:7], v[200:203], v[192:195], v[4:7]
	v_mfma_f32_16x16x32_bf16 v[0:3], v[208:211], v[192:195], v[0:3]
	v_mfma_f32_16x16x32_bf16 v[52:55], v[204:207], v[172:175], v[52:55]
	v_mfma_f32_16x16x32_bf16 v[48:51], v[212:215], v[172:175], v[48:51]
	v_mfma_f32_16x16x32_bf16 v[36:39], v[204:207], v[180:183], v[36:39]
	v_mfma_f32_16x16x32_bf16 v[32:35], v[212:215], v[180:183], v[32:35]
	v_mfma_f32_16x16x32_bf16 v[20:23], v[204:207], v[188:191], v[20:23]
	v_mfma_f32_16x16x32_bf16 v[16:19], v[212:215], v[188:191], v[16:19]
	v_mfma_f32_16x16x32_bf16 v[4:7], v[204:207], v[196:199], v[4:7]
	v_mfma_f32_16x16x32_bf16 v[0:3], v[212:215], v[196:199], v[0:3]
	s_setprio 0
	s_add_i32 s61, s61, 2
	s_add_u32 s28, s28, 0x100
	s_addc_u32 s29, s29, 0
	s_add_u32 s59, s59, 0x100
	s_addc_u32 s60, s60, 0
	s_cmp_gt_u32 s61, 13
	s_barrier
	s_cbranch_scc0 .LBB0_786
	s_cmpk_gt_u32 s37, 0xff
	s_cbranch_scc1 .Lg786_nox
	s_barrier
.Lg786_nox:
	v_lshl_add_u32 v146, s8, 8, v148
	v_ashrrev_i32_e32 v147, 31, v146
	v_lshl_or_b32 v144, s56, 8, v150
	v_lshlrev_b64 v[156:157], 11, v[146:147]
	v_ashrrev_i32_e32 v145, 31, v144
	v_lshl_add_u64 v[156:157], s[10:11], 0, v[156:157]
	v_lshl_add_u64 v[166:167], v[144:145], 1, v[156:157]
	global_load_dwordx4 v[158:161], v[166:167], off
	global_load_dwordx4 v[162:165], v[166:167], off offset:256
	v_and_b32_e32 v156, 64, v154
	v_xor_b32_e32 v155, 16, v154
	v_add_u32_e32 v156, 64, v156
	v_xor_b32_e32 v157, 32, v154
	v_cmp_lt_i32_e32 vcc, v155, v156
	s_lshl_b32 s28, s56, 2
	s_ashr_i32 s29, s28, 31
	v_cndmask_b32_e32 v155, v154, v155, vcc
	v_cmp_lt_i32_e32 vcc, v157, v156
	v_lshlrev_b32_e32 v156, 2, v155
	s_waitcnt vmcnt(0)
	v_lshlrev_b32_e32 v168, 16, v158
	v_and_b32_e32 v169, 0xffff0000, v158
	v_lshlrev_b32_e32 v158, 16, v159
	v_and_b32_e32 v159, 0xffff0000, v159
	v_lshlrev_b32_e32 v172, 16, v162
	v_and_b32_e32 v173, 0xffff0000, v162
	v_lshlrev_b32_e32 v162, 16, v163
	v_and_b32_e32 v163, 0xffff0000, v163
	v_cndmask_b32_e32 v157, v154, v157, vcc
	v_lshlrev_b32_e32 v170, 16, v160
	v_and_b32_e32 v171, 0xffff0000, v160
	v_lshlrev_b32_e32 v160, 16, v161
	v_and_b32_e32 v161, 0xffff0000, v161
	v_lshlrev_b32_e32 v174, 16, v164
	v_and_b32_e32 v175, 0xffff0000, v164
	v_lshlrev_b32_e32 v164, 16, v165
	v_and_b32_e32 v165, 0xffff0000, v165
	v_pk_add_f32 v[126:127], v[126:127], v[158:159]
	v_pk_add_f32 v[124:125], v[124:125], v[168:169]
	v_pk_add_f32 v[118:119], v[118:119], v[162:163]
	v_pk_add_f32 v[116:117], v[116:117], v[172:173]
	v_lshlrev_b32_e32 v155, 2, v157
	v_pk_add_f32 v[122:123], v[122:123], v[160:161]
	v_pk_add_f32 v[120:121], v[120:121], v[170:171]
	v_pk_add_f32 v[158:159], v[114:115], v[164:165]
	v_pk_add_f32 v[160:161], v[112:113], v[174:175]
	v_mul_f32_e32 v114, v125, v125
	v_mul_f32_e32 v115, v127, v127
	v_mul_f32_e32 v157, v117, v117
	v_mul_f32_e32 v162, v119, v119
	v_cvt_pk_bf16_f32 v112, v124, v125
	v_mul_f32_e32 v125, v121, v121
	v_mul_f32_e32 v163, v161, v161
	v_fmac_f32_e32 v114, v124, v124
	v_fmac_f32_e32 v115, v126, v126
	v_fmac_f32_e32 v157, v116, v116
	v_fmac_f32_e32 v162, v118, v118
	v_cvt_pk_bf16_f32 v113, v126, v127
	v_mul_f32_e32 v127, v123, v123
	v_mul_f32_e32 v164, v159, v159
	v_fmac_f32_e32 v125, v120, v120
	v_fmac_f32_e32 v163, v160, v160
	v_add_f32_e32 v114, v114, v115
	v_add_f32_e32 v115, v157, v162
	v_fmac_f32_e32 v127, v122, v122
	v_fmac_f32_e32 v164, v158, v158
	v_add_f32_e32 v114, v125, v114
	v_add_f32_e32 v115, v163, v115
	v_add_f32_e32 v114, v127, v114
	v_add_f32_e32 v115, v164, v115
	v_add_f32_e32 v124, v114, v115
	ds_bpermute_b32 v125, v156, v124
	v_cvt_pk_bf16_f32 v114, v120, v121
	v_cvt_pk_bf16_f32 v115, v122, v123
	global_store_dwordx4 v[166:167], v[112:115], off
	s_waitcnt lgkmcnt(0)
	s_nop 0
	v_add_f32_e32 v112, v124, v125
	ds_bpermute_b32 v113, v155, v112
	v_cvt_pk_bf16_f32 v114, v116, v117
	v_cvt_pk_bf16_f32 v115, v118, v119
	v_cvt_pk_bf16_f32 v116, v160, v161
	v_cvt_pk_bf16_f32 v117, v158, v159
	global_store_dwordx4 v[166:167], v[114:117], off offset:256
	s_and_saveexec_b64 s[30:31], s[4:5]
	s_cbranch_execz .LBB0_789
	v_lshlrev_b64 v[114:115], 6, v[146:147]
	v_lshl_add_u64 v[114:115], s[12:13], 0, v[114:115]
	v_lshl_add_u64 v[114:115], s[28:29], 2, v[114:115]
	s_lshl_b32 s8, s49, 2
	v_lshl_add_u64 v[114:115], v[114:115], 0, s[8:9]
	s_waitcnt lgkmcnt(0)
	v_add_f32_e32 v112, v112, v113
	global_store_dword v[114:115], v112, off

.LBB0_803:
	s_waitcnt vmcnt(0)
	s_cmpk_gt_u32 s37, 0xff
	s_cbranch_scc1 .LBB0_805
.LBB0_805:
	s_barrier
	s_load_dwordx2 s[4:5], s[0:1], 0xa8

.LBB0_886:
	s_cmpk_gt_i32 s33, 0x107f
	v_readfirstlane_b32 s30, v145
	s_waitcnt lgkmcnt(0)
	s_barrier
	s_cbranch_scc1 .LBB0_898
	s_waitcnt vmcnt(3)
	v_lshlrev_b32_e32 v0, 4, v145
	v_add_u32_e32 v1, 0x2000, v0
	v_ashrrev_i32_e32 v2, 31, v1
	v_lshrrev_b32_e32 v2, 22, v2
	v_add_u32_e32 v2, v1, v2
	s_waitcnt vmcnt(1)
	v_ashrrev_i32_e32 v8, 10, v2
	v_mul_i32_i24_e32 v2, 0x400, v8
	v_sub_u32_e32 v1, v1, v2
	v_lshrrev_b32_e32 v2, 4, v1
	v_bitop3_b32 v1, v2, v1, 32 bitop3:0x6c
	v_ashrrev_i32_e32 v2, 31, v1
	v_lshrrev_b32_e32 v2, 26, v2
	v_add_u32_e32 v2, v1, v2
	v_lshlrev_b32_e32 v3, 3, v8
	v_ashrrev_i32_e32 v9, 6, v2
	v_and_b32_e32 v3, -16, v3
	v_add_u32_e32 v3, v9, v3
	v_and_b32_e32 v4, 3, v9
	s_mov_b32 s4, 0x1fffe0
	v_lshrrev_b32_e32 v5, 2, v3
	v_lshlrev_b32_e32 v6, 1, v3
	v_and_b32_e32 v2, 0xc0, v2
	v_and_or_b32 v4, v3, s4, v4
	v_and_b32_e32 v5, 4, v5
	v_and_b32_e32 v6, 24, v6
	v_sub_u32_e32 v1, v1, v2
	v_mov_b32_e32 v2, 1
	v_or3_b32 v4, v4, v5, v6
	v_lshlrev_b32_e32 v5, 5, v8
	v_ashrrev_i16_sdwa v1, v2, sext(v1) dst_sel:DWORD dst_unused:UNUSED_PAD src0_sel:DWORD src1_sel:BYTE_0
	v_and_b32_e32 v5, 32, v5
	v_bfe_i32 v10, v1, 0, 16
	v_add_lshl_u32 v1, v5, v10, 1
	v_lshl_add_u32 v128, v4, 11, v1
	v_lshl_add_u32 v130, v3, 11, v1
	v_bfe_i32 v1, v145, 27, 1
	v_lshrrev_b32_e32 v1, 22, v1
	v_add_u32_e32 v1, v0, v1
	v_and_b32_e32 v1, 0xfffffc00, v1
	v_sub_u32_e32 v0, v0, v1
	v_lshrrev_b32_e32 v1, 4, v0
	v_ashrrev_i32_e32 v3, 31, v145
	v_bitop3_b32 v0, v1, v0, 32 bitop3:0x6c
	v_lshrrev_b32_e32 v3, 26, v3
	s_ashr_i32 s6, s30, 6
	v_ashrrev_i32_e32 v1, 31, v0
	v_add_u32_e32 v3, v145, v3
	s_ashr_i32 s5, s30, 8
	s_lshl_b32 s31, s6, 10
	v_lshrrev_b32_e32 v1, 26, v1
	s_waitcnt vmcnt(0)
	v_ashrrev_i32_e32 v12, 6, v3
	s_add_u32 s37, s45, 0x3800000
	v_add_u32_e32 v1, v0, v1
	v_lshlrev_b32_e32 v3, 3, v12
	s_addc_u32 s38, s46, 0
	v_ashrrev_i32_e32 v11, 6, v1
	v_and_b32_e32 v3, -16, v3
	s_add_u32 s39, s45, 0x1780000
	v_add_u32_e32 v3, v11, v3
	v_and_b32_e32 v4, 3, v11
	s_addc_u32 s40, s46, 0
	v_and_or_b32 v4, v3, s4, v4
	s_ashr_i32 s4, s33, 31
	s_lshr_b32 s4, s4, 29
	s_add_i32 s4, s33, s4
	s_ashr_i32 s7, s4, 3
	s_and_b32 s4, s4, -8
	s_sub_i32 s4, s33, s4
	s_cmp_lt_i32 s4, 0
	s_movk_i32 s41, 0x211
	s_cselect_b32 s8, s41, 0x210
	s_mul_i32 s4, s4, s8
	s_add_i32 s4, s4, s7
	s_mul_hi_i32 s7, s4, 0x2e8ba2e9
	s_lshr_b32 s8, s7, 31
	s_ashr_i32 s7, s7, 5
	s_add_i32 s7, s7, s8
	s_lshl_b32 s8, s7, 3
	s_mulk_i32 s7, 0xb0
	s_sub_i32 s7, s4, s7
	s_bfe_u32 s4, s7, 0x3001c
	s_add_i32 s9, s7, s4
	s_sext_i32_i16 s4, s9
	s_and_b32 s9, s9, 0xfff8
	s_sub_i32 s7, s7, s9
	s_sext_i32_i16 s7, s7
	v_lshrrev_b32_e32 v5, 2, v3
	v_lshlrev_b32_e32 v6, 1, v3
	v_and_b32_e32 v1, 0xc0, v1
	s_lshr_b32 s4, s4, 3
	s_add_i32 s18, s8, s7
	v_and_b32_e32 v5, 4, v5
	v_and_b32_e32 v6, 24, v6
	v_sub_u32_e32 v0, v0, v1
	s_ashr_i32 s19, s18, 31
	s_bfe_i64 s[10:11], s[4:5], 0x100000
	v_or3_b32 v4, v4, v5, v6
	v_lshlrev_b32_e32 v5, 5, v12
	v_ashrrev_i16_sdwa v0, v2, sext(v0) dst_sel:DWORD dst_unused:UNUSED_PAD src0_sel:DWORD src1_sel:BYTE_0
	s_lshl_b64 s[8:9], s[18:19], 19
	s_lshl_b64 s[10:11], s[10:11], 19
	v_and_b32_e32 v5, 32, v5
	v_bfe_i32 v13, v0, 0, 16
	s_add_u32 s26, s39, s10
	v_add_lshl_u32 v0, v5, v13, 1
	s_addc_u32 s27, s40, s11
	s_add_i32 s19, s31, 0
	v_lshl_add_u32 v132, v4, 11, v0
	s_add_i32 m0, s19, 0x10000
	v_lshl_add_u32 v134, v3, 11, v0
	global_load_lds_dwordx4 v132, s[26:27]
	s_add_i32 m0, s19, 0x12000
	s_add_u32 s20, s37, s8
	global_load_lds_dwordx4 v128, s[26:27]
	s_addc_u32 s21, s38, s9
	s_mov_b32 m0, s19
	s_add_i32 s42, s19, 0x2000
	global_load_lds_dwordx4 v134, s[20:21]
	s_mov_b32 m0, s42
	s_add_u32 s8, s26, 0x40000
	global_load_lds_dwordx4 v130, s[20:21]
	s_addc_u32 s9, s27, 0
	s_add_i32 m0, s19, 0x14000
	v_mov_b32_e32 v133, 0
	global_load_lds_dwordx4 v132, s[8:9]
	s_add_i32 m0, s19, 0x16000
	v_mov_b32_e32 v129, v133
	global_load_lds_dwordx4 v128, s[8:9]
	s_add_u32 s8, s20, 0x40000
	s_addc_u32 s9, s21, 0
	s_add_i32 s43, s19, 0x4000
	s_mov_b32 m0, s43
	s_add_i32 s44, s19, 0x6000
	global_load_lds_dwordx4 v134, s[8:9]
	s_mov_b32 m0, s44
	v_mov_b32_e32 v135, v133
	global_load_lds_dwordx4 v130, s[8:9]
	v_mov_b32_e32 v131, v133
	s_mov_b32 s51, 0
	v_lshl_add_u64 v[6:7], s[26:27], 0, v[132:133]
	v_lshl_add_u64 v[4:5], s[26:27], 0, v[128:129]
	v_lshl_add_u64 v[2:3], s[20:21], 0, v[134:135]
	s_cmp_lg_u32 s5, 1
	v_lshl_add_u64 v[0:1], s[20:21], 0, v[130:131]
	s_cbranch_scc1 .LBB0_889
.LBB0_889:
	s_lshl_b32 s6, s6, 5
	s_and_b32 s13, s6, 0x60
	s_lshl_b32 s12, s5, 13
	s_lshl_b32 s14, s13, 7
	s_add_u32 s6, s45, 0x9800000
	s_mov_b64 s[8:9], 0x80
	s_addc_u32 s7, s46, 0
	s_add_i32 m0, s19, 0x18000
	v_lshl_add_u64 v[6:7], v[6:7], 0, s[8:9]
	s_waitcnt vmcnt(4)
	s_barrier
	global_load_lds_dwordx4 v[6:7], off
	v_lshl_add_u64 v[4:5], v[4:5], 0, s[8:9]
	s_add_i32 m0, s19, 0x1a000
	s_add_i32 s45, s19, 0x8000
	s_add_i32 s46, s19, 0xa000
	global_load_lds_dwordx4 v[4:5], off
	v_lshl_add_u64 v[2:3], v[2:3], 0, s[8:9]
	s_mov_b32 m0, s45
	s_add_u32 s10, s26, 0x40080
	global_load_lds_dwordx4 v[2:3], off
	v_lshl_add_u64 v[0:1], v[0:1], 0, s[8:9]
	s_mov_b32 m0, s46
	s_addc_u32 s11, s27, 0
	global_load_lds_dwordx4 v[0:1], off
	s_add_i32 m0, s19, 0x1c000
	v_lshl_add_u64 v[0:1], s[10:11], 0, v[132:133]
	global_load_lds_dwordx4 v[0:1], off
	v_lshl_add_u64 v[0:1], s[10:11], 0, v[128:129]
	s_add_i32 m0, s19, 0x1e000
	s_sext_i32_i16 s52, s4
	global_load_lds_dwordx4 v[0:1], off
	v_lshrrev_b32_e32 v1, 1, v145
	v_and_b32_e32 v1, 24, v1
	s_lshl_b32 s4, s5, 8
	v_and_b32_e32 v0, 15, v145
	v_lshlrev_b32_e32 v2, 1, v1
	s_add_i32 s4, s4, 0
	v_lshl_or_b32 v144, s5, 6, v0
	v_lshl_or_b32 v2, v0, 6, v2
	v_lshlrev_b32_e32 v0, 2, v0
	s_add_i32 s4, s4, 0x20000
	v_and_b32_e32 v3, 32, v0
	v_add_u32_e32 v146, s4, v0
	v_lshlrev_b32_e32 v0, 14, v12
	v_and_b32_e32 v0, 0xffff8000, v0
	v_or_b32_e32 v147, s13, v1
	v_lshl_add_u32 v0, v11, 11, v0
	v_and_b32_e32 v1, 1, v12
	v_lshl_or_b32 v0, v1, 6, v0
	v_lshl_add_u32 v136, v13, 1, v0
	v_lshlrev_b32_e32 v0, 14, v8
	v_and_b32_e32 v0, 0xffff8000, v0
	s_waitcnt vmcnt(6)
	v_lshl_add_u32 v0, v9, 11, v0
	v_and_b32_e32 v1, 1, v8
	v_bitop3_b32 v4, v2, s12, v3 bitop3:0xde
	v_bitop3_b32 v145, s14, v2, v3 bitop3:0xf6
	v_lshl_or_b32 v0, v1, 6, v0
	s_add_i32 s47, 0, 0x10000
	s_add_i32 s48, 0, 0x14000
	v_mov_b32_e32 v137, v133
	v_lshl_add_u32 v138, v10, 1, v0
	v_mov_b32_e32 v139, v133
	v_mov_b64_e32 v[140:141], 0x1080
	v_mov_b64_e32 v[142:143], 0x107f
	v_add_u32_e32 v148, s47, v145
	v_add_u32_e32 v149, 0, v4
	v_add_u32_e32 v150, s48, v145
	s_movk_i32 s49, 0x1600
	s_barrier

.LBB0_892:
	s_ashr_i32 s13, s12, 31
	v_cmp_lt_i64_e32 vcc, s[14:15], v[140:141]
	s_lshl_b64 s[14:15], s[12:13], 19
	s_add_u32 s14, s37, s14
	s_addc_u32 s15, s38, s15
	s_and_b64 s[16:17], vcc, exec
	s_cselect_b32 s13, s15, s21
	s_cselect_b32 s53, s14, s20
	s_ashr_i32 s11, s10, 31
	s_lshl_b64 s[16:17], s[10:11], 19
	s_add_u32 s16, s39, s16
	s_addc_u32 s17, s40, s17
	s_and_b64 s[28:29], vcc, exec
	s_cselect_b32 s11, s17, s27
	s_cselect_b32 s54, s16, s26
	s_add_u32 s20, s20, 0x40080
	s_addc_u32 s21, s21, 0
	s_add_u32 s55, s26, 0x100
	v_mov_b32_e32 v0, 0
	s_addc_u32 s56, s27, 0
	s_mov_b32 s57, -2
	v_mov_b32_e32 v1, v0
	v_mov_b32_e32 v2, v0
	v_mov_b32_e32 v3, v0
	v_mov_b32_e32 v4, v0
	v_mov_b32_e32 v5, v0
	v_mov_b32_e32 v6, v0
	v_mov_b32_e32 v7, v0
	v_mov_b32_e32 v16, v0
	v_mov_b32_e32 v17, v0
	v_mov_b32_e32 v18, v0
	v_mov_b32_e32 v19, v0
	v_mov_b32_e32 v20, v0
	v_mov_b32_e32 v21, v0
	v_mov_b32_e32 v22, v0
	v_mov_b32_e32 v23, v0
	v_mov_b32_e32 v32, v0
	v_mov_b32_e32 v33, v0
	v_mov_b32_e32 v34, v0
	v_mov_b32_e32 v35, v0
	v_mov_b32_e32 v36, v0
	v_mov_b32_e32 v37, v0
	v_mov_b32_e32 v38, v0
	v_mov_b32_e32 v39, v0
	v_mov_b32_e32 v48, v0
	v_mov_b32_e32 v49, v0
	v_mov_b32_e32 v50, v0
	v_mov_b32_e32 v51, v0
	v_mov_b32_e32 v52, v0
	v_mov_b32_e32 v53, v0
	v_mov_b32_e32 v54, v0
	v_mov_b32_e32 v55, v0
	v_mov_b32_e32 v8, v0
	v_mov_b32_e32 v9, v0
	v_mov_b32_e32 v10, v0
	v_mov_b32_e32 v11, v0
	v_mov_b32_e32 v12, v0
	v_mov_b32_e32 v13, v0
	v_mov_b32_e32 v14, v0
	v_mov_b32_e32 v15, v0
	v_mov_b32_e32 v24, v0
	v_mov_b32_e32 v25, v0
	v_mov_b32_e32 v26, v0
	v_mov_b32_e32 v27, v0
	v_mov_b32_e32 v28, v0
	v_mov_b32_e32 v29, v0
	v_mov_b32_e32 v30, v0
	v_mov_b32_e32 v31, v0
	v_mov_b32_e32 v40, v0
	v_mov_b32_e32 v41, v0
	v_mov_b32_e32 v42, v0
	v_mov_b32_e32 v43, v0
	v_mov_b32_e32 v44, v0
	v_mov_b32_e32 v45, v0
	v_mov_b32_e32 v46, v0
	v_mov_b32_e32 v47, v0
	v_mov_b32_e32 v56, v0
	v_mov_b32_e32 v57, v0
	v_mov_b32_e32 v58, v0
	v_mov_b32_e32 v59, v0
	v_mov_b32_e32 v60, v0
	v_mov_b32_e32 v61, v0
	v_mov_b32_e32 v62, v0
	v_mov_b32_e32 v63, v0
	v_mov_b32_e32 v64, v0
	v_mov_b32_e32 v65, v0
	v_mov_b32_e32 v66, v0
	v_mov_b32_e32 v67, v0
	v_mov_b32_e32 v68, v0
	v_mov_b32_e32 v69, v0
	v_mov_b32_e32 v70, v0
	v_mov_b32_e32 v71, v0
	v_mov_b32_e32 v80, v0
	v_mov_b32_e32 v81, v0
	v_mov_b32_e32 v82, v0
	v_mov_b32_e32 v83, v0
	v_mov_b32_e32 v84, v0
	v_mov_b32_e32 v85, v0
	v_mov_b32_e32 v86, v0
	v_mov_b32_e32 v87, v0
	v_mov_b32_e32 v96, v0
	v_mov_b32_e32 v97, v0
	v_mov_b32_e32 v98, v0
	v_mov_b32_e32 v99, v0
	v_mov_b32_e32 v100, v0
	v_mov_b32_e32 v101, v0
	v_mov_b32_e32 v102, v0
	v_mov_b32_e32 v103, v0
	v_mov_b32_e32 v112, v0
	v_mov_b32_e32 v113, v0
	v_mov_b32_e32 v114, v0
	v_mov_b32_e32 v115, v0
	v_mov_b32_e32 v116, v0
	v_mov_b32_e32 v117, v0
	v_mov_b32_e32 v118, v0
	v_mov_b32_e32 v119, v0
	v_mov_b32_e32 v72, v0
	v_mov_b32_e32 v73, v0
	v_mov_b32_e32 v74, v0
	v_mov_b32_e32 v75, v0
	v_mov_b32_e32 v76, v0
	v_mov_b32_e32 v77, v0
	v_mov_b32_e32 v78, v0
	v_mov_b32_e32 v79, v0
	v_mov_b32_e32 v88, v0
	v_mov_b32_e32 v89, v0
	v_mov_b32_e32 v90, v0
	v_mov_b32_e32 v91, v0
	v_mov_b32_e32 v92, v0
	v_mov_b32_e32 v93, v0
	v_mov_b32_e32 v94, v0
	v_mov_b32_e32 v95, v0
	v_mov_b32_e32 v104, v0
	v_mov_b32_e32 v105, v0
	v_mov_b32_e32 v106, v0
	v_mov_b32_e32 v107, v0
	v_mov_b32_e32 v108, v0
	v_mov_b32_e32 v109, v0
	v_mov_b32_e32 v110, v0
	v_mov_b32_e32 v111, v0
	v_mov_b32_e32 v120, v0
	v_mov_b32_e32 v121, v0
	v_mov_b32_e32 v122, v0
	v_mov_b32_e32 v123, v0
	v_mov_b32_e32 v124, v0
	v_mov_b32_e32 v125, v0
	v_mov_b32_e32 v126, v0
	v_mov_b32_e32 v127, v0
	s_cmpk_lt_u32 s30, 0x100
	s_cbranch_scc1 .Lg893_noy
	s_barrier
.Lg893_noy:
.LBB0_893:
	ds_read_b128 v[152:155], v148
	ds_read_b128 v[156:159], v148 offset:1024
	ds_read_b128 v[160:163], v148 offset:2048
	ds_read_b128 v[164:167], v148 offset:3072
	s_add_u32 s26, s20, 0xfffc0080
	s_addc_u32 s27, s21, -1
	s_cmp_eq_u32 s57, 12
	s_cselect_b32 s29, s13, s27
	s_cselect_b32 s28, s53, s26
	s_cselect_b32 s27, s11, s56
	s_cselect_b32 s26, s54, s55
	s_add_i32 m0, s19, 0xc000
	ds_read_b128 v[168:171], v149
	ds_read_b128 v[172:175], v149 offset:1024
	ds_read_b128 v[176:179], v149 offset:2048
	ds_read_b128 v[180:183], v149 offset:3072
	ds_read_b128 v[184:187], v149 offset:4096
	ds_read_b128 v[188:191], v149 offset:5120
	ds_read_b128 v[192:195], v149 offset:6144
	ds_read_b128 v[196:199], v149 offset:7168
	global_load_lds_dwordx4 v136, s[20:21]
	s_add_i32 m0, s19, 0xe000
	s_nop 0
	global_load_lds_dwordx4 v138, s[20:21]
	s_waitcnt lgkmcnt(8)
	s_barrier
	s_waitcnt lgkmcnt(0)
	s_setprio 1
	s_waitcnt lgkmcnt(0)
	v_mfma_f32_16x16x32_bf16 v[124:127], v[152:155], v[168:171], v[124:127]
	v_mfma_f32_16x16x32_bf16 v[120:123], v[160:163], v[168:171], v[120:123]
	v_mfma_f32_16x16x32_bf16 v[108:111], v[152:155], v[176:179], v[108:111]
	v_mfma_f32_16x16x32_bf16 v[104:107], v[160:163], v[176:179], v[104:107]
	v_mfma_f32_16x16x32_bf16 v[92:95], v[152:155], v[184:187], v[92:95]
	v_mfma_f32_16x16x32_bf16 v[88:91], v[160:163], v[184:187], v[88:91]
	v_mfma_f32_16x16x32_bf16 v[76:79], v[152:155], v[192:195], v[76:79]
	v_mfma_f32_16x16x32_bf16 v[72:75], v[160:163], v[192:195], v[72:75]
	v_mfma_f32_16x16x32_bf16 v[124:127], v[156:159], v[172:175], v[124:127]
	v_mfma_f32_16x16x32_bf16 v[120:123], v[164:167], v[172:175], v[120:123]
	v_mfma_f32_16x16x32_bf16 v[108:111], v[156:159], v[180:183], v[108:111]
	v_mfma_f32_16x16x32_bf16 v[104:107], v[164:167], v[180:183], v[104:107]
	v_mfma_f32_16x16x32_bf16 v[92:95], v[156:159], v[188:191], v[92:95]
	v_mfma_f32_16x16x32_bf16 v[88:91], v[164:167], v[188:191], v[88:91]
	v_mfma_f32_16x16x32_bf16 v[76:79], v[156:159], v[196:199], v[76:79]
	v_mfma_f32_16x16x32_bf16 v[72:75], v[164:167], v[196:199], v[72:75]
	s_setprio 0
	s_barrier
	s_add_i32 s58, s47, s31
	s_add_u32 s80, s26, 0x80
	s_addc_u32 s81, s27, 0
	s_mov_b32 m0, s58
	ds_read_b128 v[200:203], v150
	ds_read_b128 v[204:207], v150 offset:1024
	ds_read_b128 v[208:211], v150 offset:2048
	ds_read_b128 v[212:215], v150 offset:3072
	global_load_lds_dwordx4 v132, s[26:27]
	s_add_i32 m0, s58, 0x2000
	s_nop 0
	global_load_lds_dwordx4 v128, s[26:27]
	s_barrier
	s_waitcnt lgkmcnt(0)
	s_setprio 1
	s_waitcnt lgkmcnt(0)
	v_mfma_f32_16x16x32_bf16 v[116:119], v[200:203], v[168:171], v[116:119]
	v_mfma_f32_16x16x32_bf16 v[112:115], v[208:211], v[168:171], v[112:115]
	v_mfma_f32_16x16x32_bf16 v[100:103], v[200:203], v[176:179], v[100:103]
	v_mfma_f32_16x16x32_bf16 v[96:99], v[208:211], v[176:179], v[96:99]
	v_mfma_f32_16x16x32_bf16 v[84:87], v[200:203], v[184:187], v[84:87]
	v_mfma_f32_16x16x32_bf16 v[80:83], v[208:211], v[184:187], v[80:83]
	v_mfma_f32_16x16x32_bf16 v[68:71], v[200:203], v[192:195], v[68:71]
	v_mfma_f32_16x16x32_bf16 v[64:67], v[208:211], v[192:195], v[64:67]
	v_mfma_f32_16x16x32_bf16 v[116:119], v[204:207], v[172:175], v[116:119]
	v_mfma_f32_16x16x32_bf16 v[112:115], v[212:215], v[172:175], v[112:115]
	v_mfma_f32_16x16x32_bf16 v[100:103], v[204:207], v[180:183], v[100:103]
	v_mfma_f32_16x16x32_bf16 v[96:99], v[212:215], v[180:183], v[96:99]
	v_mfma_f32_16x16x32_bf16 v[84:87], v[204:207], v[188:191], v[84:87]
	v_mfma_f32_16x16x32_bf16 v[80:83], v[212:215], v[188:191], v[80:83]
	v_mfma_f32_16x16x32_bf16 v[68:71], v[204:207], v[196:199], v[68:71]
	v_mfma_f32_16x16x32_bf16 v[64:67], v[212:215], v[196:199], v[64:67]
	s_setprio 0
	s_mov_b32 m0, s19
	s_add_u32 s82, s28, 0x80
	s_addc_u32 s83, s29, 0
	s_barrier
	ds_read_b128 v[168:171], v149 offset:16384
	ds_read_b128 v[172:175], v149 offset:17408
	ds_read_b128 v[176:179], v149 offset:18432
	ds_read_b128 v[180:183], v149 offset:19456
	ds_read_b128 v[184:187], v149 offset:20480
	ds_read_b128 v[188:191], v149 offset:21504
	ds_read_b128 v[192:195], v149 offset:22528
	ds_read_b128 v[196:199], v149 offset:23552
	global_load_lds_dwordx4 v134, s[28:29]
	s_mov_b32 m0, s42
	s_nop 0
	global_load_lds_dwordx4 v130, s[28:29]
	s_barrier
	s_waitcnt lgkmcnt(0)
	s_setprio 1
	s_waitcnt lgkmcnt(0)
	v_mfma_f32_16x16x32_bf16 v[60:63], v[152:155], v[168:171], v[60:63]
	v_mfma_f32_16x16x32_bf16 v[56:59], v[160:163], v[168:171], v[56:59]
	v_mfma_f32_16x16x32_bf16 v[44:47], v[152:155], v[176:179], v[44:47]
	v_mfma_f32_16x16x32_bf16 v[40:43], v[160:163], v[176:179], v[40:43]
	v_mfma_f32_16x16x32_bf16 v[28:31], v[152:155], v[184:187], v[28:31]
	v_mfma_f32_16x16x32_bf16 v[24:27], v[160:163], v[184:187], v[24:27]
	v_mfma_f32_16x16x32_bf16 v[12:15], v[152:155], v[192:195], v[12:15]
	v_mfma_f32_16x16x32_bf16 v[8:11], v[160:163], v[192:195], v[8:11]
	v_mfma_f32_16x16x32_bf16 v[60:63], v[156:159], v[172:175], v[60:63]
	v_mfma_f32_16x16x32_bf16 v[56:59], v[164:167], v[172:175], v[56:59]
	v_mfma_f32_16x16x32_bf16 v[44:47], v[156:159], v[180:183], v[44:47]
	v_mfma_f32_16x16x32_bf16 v[40:43], v[164:167], v[180:183], v[40:43]
	v_mfma_f32_16x16x32_bf16 v[28:31], v[156:159], v[188:191], v[28:31]
	v_mfma_f32_16x16x32_bf16 v[24:27], v[164:167], v[188:191], v[24:27]
	v_mfma_f32_16x16x32_bf16 v[12:15], v[156:159], v[196:199], v[12:15]
	v_mfma_f32_16x16x32_bf16 v[8:11], v[164:167], v[196:199], v[8:11]
	s_setprio 0
	s_barrier
	s_add_u32 s58, s26, 0x40000
	s_addc_u32 s59, s27, 0
	s_add_i32 s60, s48, s31
	s_mov_b32 m0, s60
	s_nop 0
	global_load_lds_dwordx4 v132, s[58:59]
	s_add_i32 m0, s60, 0x2000
	s_nop 0
	global_load_lds_dwordx4 v128, s[58:59]
	s_waitcnt vmcnt(6)
	s_barrier
	s_setprio 1
	v_mfma_f32_16x16x32_bf16 v[52:55], v[200:203], v[168:171], v[52:55]
	v_mfma_f32_16x16x32_bf16 v[48:51], v[208:211], v[168:171], v[48:51]
	v_mfma_f32_16x16x32_bf16 v[36:39], v[200:203], v[176:179], v[36:39]
	v_mfma_f32_16x16x32_bf16 v[32:35], v[208:211], v[176:179], v[32:35]
	v_mfma_f32_16x16x32_bf16 v[20:23], v[200:203], v[184:187], v[20:23]
	v_mfma_f32_16x16x32_bf16 v[16:19], v[208:211], v[184:187], v[16:19]
	v_mfma_f32_16x16x32_bf16 v[4:7], v[200:203], v[192:195], v[4:7]
	v_mfma_f32_16x16x32_bf16 v[0:3], v[208:211], v[192:195], v[0:3]
	v_mfma_f32_16x16x32_bf16 v[52:55], v[204:207], v[172:175], v[52:55]
	v_mfma_f32_16x16x32_bf16 v[48:51], v[212:215], v[172:175], v[48:51]
	v_mfma_f32_16x16x32_bf16 v[36:39], v[204:207], v[180:183], v[36:39]
	v_mfma_f32_16x16x32_bf16 v[32:35], v[212:215], v[180:183], v[32:35]
	v_mfma_f32_16x16x32_bf16 v[20:23], v[204:207], v[188:191], v[20:23]
	v_mfma_f32_16x16x32_bf16 v[16:19], v[212:215], v[188:191], v[16:19]
	v_mfma_f32_16x16x32_bf16 v[4:7], v[204:207], v[196:199], v[4:7]
	v_mfma_f32_16x16x32_bf16 v[0:3], v[212:215], v[196:199], v[0:3]
	s_setprio 0
	s_add_i32 s58, 0, 0x18000
	v_add_u32_e32 v151, s58, v145
	s_barrier
	ds_read_b128 v[152:155], v151
	ds_read_b128 v[156:159], v151 offset:1024
	ds_read_b128 v[160:163], v151 offset:2048
	ds_read_b128 v[164:167], v151 offset:3072
	s_add_u32 s28, s28, 0x40000
	s_addc_u32 s29, s29, 0
	s_mov_b32 m0, s43
	ds_read_b128 v[168:171], v149 offset:32768
	ds_read_b128 v[172:175], v149 offset:33792
	ds_read_b128 v[176:179], v149 offset:34816
	ds_read_b128 v[180:183], v149 offset:35840
	ds_read_b128 v[184:187], v149 offset:36864
	ds_read_b128 v[188:191], v149 offset:37888
	ds_read_b128 v[192:195], v149 offset:38912
	ds_read_b128 v[196:199], v149 offset:39936
	global_load_lds_dwordx4 v134, s[28:29]
	s_mov_b32 m0, s44
	s_nop 0
	global_load_lds_dwordx4 v130, s[28:29]
	s_waitcnt lgkmcnt(8)
	s_barrier
	s_waitcnt lgkmcnt(0)
	s_setprio 1
	s_waitcnt lgkmcnt(0)
	v_mfma_f32_16x16x32_bf16 v[124:127], v[152:155], v[168:171], v[124:127]
	v_mfma_f32_16x16x32_bf16 v[120:123], v[160:163], v[168:171], v[120:123]
	v_mfma_f32_16x16x32_bf16 v[108:111], v[152:155], v[176:179], v[108:111]
	v_mfma_f32_16x16x32_bf16 v[104:107], v[160:163], v[176:179], v[104:107]
	v_mfma_f32_16x16x32_bf16 v[92:95], v[152:155], v[184:187], v[92:95]
	v_mfma_f32_16x16x32_bf16 v[88:91], v[160:163], v[184:187], v[88:91]
	v_mfma_f32_16x16x32_bf16 v[76:79], v[152:155], v[192:195], v[76:79]
	v_mfma_f32_16x16x32_bf16 v[72:75], v[160:163], v[192:195], v[72:75]
	v_mfma_f32_16x16x32_bf16 v[124:127], v[156:159], v[172:175], v[124:127]
	v_mfma_f32_16x16x32_bf16 v[120:123], v[164:167], v[172:175], v[120:123]
	v_mfma_f32_16x16x32_bf16 v[108:111], v[156:159], v[180:183], v[108:111]
	v_mfma_f32_16x16x32_bf16 v[104:107], v[164:167], v[180:183], v[104:107]
	v_mfma_f32_16x16x32_bf16 v[92:95], v[156:159], v[188:191], v[92:95]
	v_mfma_f32_16x16x32_bf16 v[88:91], v[164:167], v[188:191], v[88:91]
	v_mfma_f32_16x16x32_bf16 v[76:79], v[156:159], v[196:199], v[76:79]
	v_mfma_f32_16x16x32_bf16 v[72:75], v[164:167], v[196:199], v[72:75]
	s_setprio 0
	s_barrier
	s_add_i32 s28, 0, 0x1c000
	s_add_i32 s29, s58, s31
	v_add_u32_e32 v151, s28, v145
	s_mov_b32 m0, s29
	ds_read_b128 v[200:203], v151
	ds_read_b128 v[204:207], v151 offset:1024
	ds_read_b128 v[208:211], v151 offset:2048
	ds_read_b128 v[212:215], v151 offset:3072
	global_load_lds_dwordx4 v132, s[80:81]
	s_add_i32 m0, s29, 0x2000
	s_nop 0
	global_load_lds_dwordx4 v128, s[80:81]
	s_barrier
	s_waitcnt lgkmcnt(0)
	s_setprio 1
	s_waitcnt lgkmcnt(0)
	v_mfma_f32_16x16x32_bf16 v[116:119], v[200:203], v[168:171], v[116:119]
	v_mfma_f32_16x16x32_bf16 v[112:115], v[208:211], v[168:171], v[112:115]
	v_mfma_f32_16x16x32_bf16 v[100:103], v[200:203], v[176:179], v[100:103]
	v_mfma_f32_16x16x32_bf16 v[96:99], v[208:211], v[176:179], v[96:99]
	v_mfma_f32_16x16x32_bf16 v[84:87], v[200:203], v[184:187], v[84:87]
	v_mfma_f32_16x16x32_bf16 v[80:83], v[208:211], v[184:187], v[80:83]
	v_mfma_f32_16x16x32_bf16 v[68:71], v[200:203], v[192:195], v[68:71]
	v_mfma_f32_16x16x32_bf16 v[64:67], v[208:211], v[192:195], v[64:67]
	v_mfma_f32_16x16x32_bf16 v[116:119], v[204:207], v[172:175], v[116:119]
	v_mfma_f32_16x16x32_bf16 v[112:115], v[212:215], v[172:175], v[112:115]
	v_mfma_f32_16x16x32_bf16 v[100:103], v[204:207], v[180:183], v[100:103]
	v_mfma_f32_16x16x32_bf16 v[96:99], v[212:215], v[180:183], v[96:99]
	v_mfma_f32_16x16x32_bf16 v[84:87], v[204:207], v[188:191], v[84:87]
	v_mfma_f32_16x16x32_bf16 v[80:83], v[212:215], v[188:191], v[80:83]
	v_mfma_f32_16x16x32_bf16 v[68:71], v[204:207], v[196:199], v[68:71]
	v_mfma_f32_16x16x32_bf16 v[64:67], v[212:215], v[196:199], v[64:67]
	s_setprio 0
	s_mov_b32 m0, s45
	s_barrier
	ds_read_b128 v[168:171], v149 offset:49152
	ds_read_b128 v[172:175], v149 offset:50176
	ds_read_b128 v[176:179], v149 offset:51200
	ds_read_b128 v[180:183], v149 offset:52224
	ds_read_b128 v[184:187], v149 offset:53248
	ds_read_b128 v[188:191], v149 offset:54272
	ds_read_b128 v[192:195], v149 offset:55296
	ds_read_b128 v[196:199], v149 offset:56320
	global_load_lds_dwordx4 v134, s[82:83]
	s_mov_b32 m0, s46
	s_nop 0
	global_load_lds_dwordx4 v130, s[82:83]
	s_barrier
	s_waitcnt lgkmcnt(0)
	s_setprio 1
	s_waitcnt lgkmcnt(0)
	v_mfma_f32_16x16x32_bf16 v[60:63], v[152:155], v[168:171], v[60:63]
	v_mfma_f32_16x16x32_bf16 v[56:59], v[160:163], v[168:171], v[56:59]
	v_mfma_f32_16x16x32_bf16 v[44:47], v[152:155], v[176:179], v[44:47]
	v_mfma_f32_16x16x32_bf16 v[40:43], v[160:163], v[176:179], v[40:43]
	v_mfma_f32_16x16x32_bf16 v[28:31], v[152:155], v[184:187], v[28:31]
	v_mfma_f32_16x16x32_bf16 v[24:27], v[160:163], v[184:187], v[24:27]
	v_mfma_f32_16x16x32_bf16 v[12:15], v[152:155], v[192:195], v[12:15]
	v_mfma_f32_16x16x32_bf16 v[8:11], v[160:163], v[192:195], v[8:11]
	v_mfma_f32_16x16x32_bf16 v[60:63], v[156:159], v[172:175], v[60:63]
	v_mfma_f32_16x16x32_bf16 v[56:59], v[164:167], v[172:175], v[56:59]
	v_mfma_f32_16x16x32_bf16 v[44:47], v[156:159], v[180:183], v[44:47]
	v_mfma_f32_16x16x32_bf16 v[40:43], v[164:167], v[180:183], v[40:43]
	v_mfma_f32_16x16x32_bf16 v[28:31], v[156:159], v[188:191], v[28:31]
	v_mfma_f32_16x16x32_bf16 v[24:27], v[164:167], v[188:191], v[24:27]
	v_mfma_f32_16x16x32_bf16 v[12:15], v[156:159], v[196:199], v[12:15]
	v_mfma_f32_16x16x32_bf16 v[8:11], v[164:167], v[196:199], v[8:11]
	s_setprio 0
	s_barrier
	s_add_u32 s26, s26, 0x40080
	s_addc_u32 s27, s27, 0
	s_add_i32 s28, s28, s31
	s_mov_b32 m0, s28
	s_nop 0
	global_load_lds_dwordx4 v132, s[26:27]
	s_add_i32 m0, s28, 0x2000
	s_nop 0
	global_load_lds_dwordx4 v128, s[26:27]
	s_waitcnt vmcnt(6)
	s_barrier
	s_setprio 1
	v_mfma_f32_16x16x32_bf16 v[52:55], v[200:203], v[168:171], v[52:55]
	v_mfma_f32_16x16x32_bf16 v[48:51], v[208:211], v[168:171], v[48:51]
	v_mfma_f32_16x16x32_bf16 v[36:39], v[200:203], v[176:179], v[36:39]
	v_mfma_f32_16x16x32_bf16 v[32:35], v[208:211], v[176:179], v[32:35]
	v_mfma_f32_16x16x32_bf16 v[20:23], v[200:203], v[184:187], v[20:23]
	v_mfma_f32_16x16x32_bf16 v[16:19], v[208:211], v[184:187], v[16:19]
	v_mfma_f32_16x16x32_bf16 v[4:7], v[200:203], v[192:195], v[4:7]
	v_mfma_f32_16x16x32_bf16 v[0:3], v[208:211], v[192:195], v[0:3]
	v_mfma_f32_16x16x32_bf16 v[52:55], v[204:207], v[172:175], v[52:55]
	v_mfma_f32_16x16x32_bf16 v[48:51], v[212:215], v[172:175], v[48:51]
	v_mfma_f32_16x16x32_bf16 v[36:39], v[204:207], v[180:183], v[36:39]
	v_mfma_f32_16x16x32_bf16 v[32:35], v[212:215], v[180:183], v[32:35]
	v_mfma_f32_16x16x32_bf16 v[20:23], v[204:207], v[188:191], v[20:23]
	v_mfma_f32_16x16x32_bf16 v[16:19], v[212:215], v[188:191], v[16:19]
	v_mfma_f32_16x16x32_bf16 v[4:7], v[204:207], v[196:199], v[4:7]
	v_mfma_f32_16x16x32_bf16 v[0:3], v[212:215], v[196:199], v[0:3]
	s_setprio 0
	s_add_i32 s57, s57, 2
	s_add_u32 s20, s20, 0x100
	s_addc_u32 s21, s21, 0
	s_add_u32 s55, s55, 0x100
	s_addc_u32 s56, s56, 0
	s_cmp_gt_u32 s57, 13
	s_barrier
	s_cbranch_scc0 .LBB0_893
	s_cmpk_gt_u32 s30, 0xff
	s_cbranch_scc1 .Lg893_nox
	s_barrier
.Lg893_nox:
	v_lshl_add_u32 v152, s51, 10, v146
	ds_read2_b32 v[154:155], v152 offset1:16
	v_lshl_or_b32 v156, s52, 7, v147
	v_lshl_add_u32 v151, s18, 8, v144
	s_and_b64 vcc, exec, s[4:5]
	s_mov_b32 s52, s10
	s_waitcnt lgkmcnt(0)
	v_pk_mul_f32 v[124:125], v[124:125], v[154:155] op_sel_hi:[1,0]
	v_pk_mul_f32 v[126:127], v[126:127], v[154:155] op_sel_hi:[1,0]
	v_mul_f32_e32 v153, 0xbfb8aa3b, v124
	v_mul_f32_e32 v157, 0xbfb8aa3b, v125
	v_exp_f32_e32 v153, v153
	v_exp_f32_e32 v158, v157
	v_mul_f32_e32 v160, 0xbfb8aa3b, v127
	v_exp_f32_e32 v161, v160
	v_add_f32_e32 v153, 1.0, v153
	v_add_f32_e32 v159, 1.0, v158
	v_rcp_f32_e32 v158, v153
	v_mul_f32_e32 v153, 0xbfb8aa3b, v126
	v_exp_f32_e32 v153, v153
	v_rcp_f32_e32 v159, v159
	v_pk_mul_f32 v[116:117], v[116:117], v[154:155] op_sel_hi:[1,0]
	v_pk_mul_f32 v[120:121], v[120:121], v[154:155] op_sel_hi:[1,0]
	v_add_f32_e32 v153, 1.0, v153
	v_rcp_f32_e32 v160, v153
	v_add_f32_e32 v153, 1.0, v161
	v_rcp_f32_e32 v161, v153
	v_pk_mul_f32 v[124:125], v[124:125], v[158:159]
	v_pk_mul_f32 v[118:119], v[118:119], v[154:155] op_sel_hi:[1,0]
	v_pk_mul_f32 v[116:117], v[116:117], v[124:125]
	v_pk_mul_f32 v[124:125], v[126:127], v[160:161]
	v_mul_f32_e32 v126, 0xbfb8aa3b, v120
	v_exp_f32_e32 v126, v126
	v_pk_mul_f32 v[118:119], v[118:119], v[124:125]
	v_mul_f32_e32 v124, 0xbfb8aa3b, v121
	v_pk_mul_f32 v[122:123], v[122:123], v[154:155] op_sel_hi:[1,0]
	v_exp_f32_e32 v125, v124
	v_add_f32_e32 v124, 1.0, v126
	v_mul_f32_e32 v126, 0xbfb8aa3b, v122
	v_mul_f32_e32 v127, 0xbfb8aa3b, v123
	v_exp_f32_e32 v126, v126
	v_exp_f32_e32 v127, v127
	v_add_f32_e32 v125, 1.0, v125
	v_rcp_f32_e32 v124, v124
	v_rcp_f32_e32 v125, v125
	v_add_f32_e32 v126, 1.0, v126
	v_add_f32_e32 v127, 1.0, v127
	v_rcp_f32_e32 v126, v126
	v_rcp_f32_e32 v127, v127
	v_pk_mul_f32 v[112:113], v[112:113], v[154:155] op_sel_hi:[1,0]
	v_pk_mul_f32 v[120:121], v[120:121], v[124:125]
	v_pk_mul_f32 v[114:115], v[114:115], v[154:155] op_sel_hi:[1,0]
	v_pk_mul_f32 v[112:113], v[112:113], v[120:121]
	v_pk_mul_f32 v[120:121], v[122:123], v[126:127]
	v_mov_b32_e32 v122, v155
	v_pk_mul_f32 v[108:109], v[108:109], v[122:123] op_sel_hi:[1,0]
	v_ashrrev_i32_e32 v157, 31, v156
	v_mul_f32_e32 v123, 0xbfb8aa3b, v108
	v_exp_f32_e32 v123, v123
	v_pk_mul_f32 v[114:115], v[114:115], v[120:121]
	v_cvt_pk_bf16_f32 v116, v116, v117
	v_cvt_pk_bf16_f32 v117, v118, v119
	v_cvt_pk_bf16_f32 v118, v112, v113
	v_mov_b64_e32 v[112:113], s[6:7]
	v_cvt_pk_bf16_f32 v119, v114, v115
	v_mad_i64_i32 v[120:121], s[20:21], v151, s49, v[112:113]
	v_lshlrev_b64 v[114:115], 1, v[156:157]
	v_lshl_add_u64 v[120:121], v[120:121], 0, v[114:115]
	global_store_dwordx4 v[120:121], v[116:119], off nt
	v_pk_mul_f32 v[110:111], v[110:111], v[122:123] op_sel_hi:[1,0]
	v_pk_mul_f32 v[100:101], v[100:101], v[122:123] op_sel_hi:[1,0]
	v_mul_f32_e32 v116, 0xbfb8aa3b, v109
	v_exp_f32_e32 v117, v116
	v_mul_f32_e32 v118, 0xbfb8aa3b, v110
	v_mul_f32_e32 v119, 0xbfb8aa3b, v111
	v_exp_f32_e32 v118, v118
	v_exp_f32_e32 v119, v119
	v_add_f32_e32 v116, 1.0, v123
	v_add_f32_e32 v117, 1.0, v117
	v_rcp_f32_e32 v116, v116
	v_rcp_f32_e32 v117, v117
	v_add_f32_e32 v118, 1.0, v118
	v_add_f32_e32 v119, 1.0, v119
	v_rcp_f32_e32 v118, v118
	v_rcp_f32_e32 v119, v119
	v_pk_mul_f32 v[108:109], v[108:109], v[116:117]
	v_pk_mul_f32 v[104:105], v[104:105], v[122:123] op_sel_hi:[1,0]
	v_pk_mul_f32 v[100:101], v[100:101], v[108:109]
	v_pk_mul_f32 v[108:109], v[110:111], v[118:119]
	v_mul_f32_e32 v110, 0xbfb8aa3b, v104
	v_exp_f32_e32 v110, v110
	v_pk_mul_f32 v[102:103], v[102:103], v[122:123] op_sel_hi:[1,0]
	v_pk_mul_f32 v[106:107], v[106:107], v[122:123] op_sel_hi:[1,0]
	v_pk_mul_f32 v[102:103], v[102:103], v[108:109]
	v_mul_f32_e32 v108, 0xbfb8aa3b, v105
	v_exp_f32_e32 v109, v108
	v_add_f32_e32 v108, 1.0, v110
	v_mul_f32_e32 v110, 0xbfb8aa3b, v106
	v_mul_f32_e32 v111, 0xbfb8aa3b, v107
	v_exp_f32_e32 v110, v110
	v_exp_f32_e32 v111, v111
	v_add_f32_e32 v109, 1.0, v109
	v_rcp_f32_e32 v108, v108
	v_rcp_f32_e32 v109, v109
	v_add_f32_e32 v110, 1.0, v110
	v_add_f32_e32 v111, 1.0, v111
	v_rcp_f32_e32 v110, v110
	v_rcp_f32_e32 v111, v111
	v_pk_mul_f32 v[96:97], v[96:97], v[122:123] op_sel_hi:[1,0]
	v_pk_mul_f32 v[104:105], v[104:105], v[108:109]
	v_or_b32_e32 v108, 16, v151
	v_pk_mul_f32 v[104:105], v[96:97], v[104:105]
	v_pk_mul_f32 v[96:97], v[98:99], v[122:123] op_sel_hi:[1,0]
	v_pk_mul_f32 v[98:99], v[106:107], v[110:111]
	s_mov_b32 s18, s12
	v_pk_mul_f32 v[106:107], v[96:97], v[98:99]
	v_cvt_pk_bf16_f32 v96, v100, v101
	ds_read2_b32 v[100:101], v152 offset0:32 offset1:48
	v_cvt_pk_bf16_f32 v97, v102, v103
	v_mad_i64_i32 v[102:103], s[20:21], v108, s49, v[112:113]
	v_cvt_pk_bf16_f32 v98, v104, v105
	v_cvt_pk_bf16_f32 v99, v106, v107
	v_lshl_add_u64 v[102:103], v[102:103], 0, v[114:115]
	s_waitcnt lgkmcnt(0)
	v_pk_mul_f32 v[92:93], v[92:93], v[100:101] op_sel_hi:[1,0]
	global_store_dwordx4 v[102:103], v[96:99], off nt
	v_mul_f32_e32 v104, 0xbfb8aa3b, v92
	v_pk_mul_f32 v[94:95], v[94:95], v[100:101] op_sel_hi:[1,0]
	v_mul_f32_e32 v96, 0xbfb8aa3b, v93
	v_exp_f32_e32 v104, v104
	v_exp_f32_e32 v97, v96
	v_mul_f32_e32 v98, 0xbfb8aa3b, v94
	v_mul_f32_e32 v99, 0xbfb8aa3b, v95
	v_exp_f32_e32 v98, v98
	v_exp_f32_e32 v99, v99
	v_add_f32_e32 v96, 1.0, v104
	v_add_f32_e32 v97, 1.0, v97
	v_rcp_f32_e32 v96, v96
	v_rcp_f32_e32 v97, v97
	v_add_f32_e32 v98, 1.0, v98
	v_add_f32_e32 v99, 1.0, v99
	v_rcp_f32_e32 v98, v98
	v_rcp_f32_e32 v99, v99
	v_pk_mul_f32 v[84:85], v[84:85], v[100:101] op_sel_hi:[1,0]
	v_pk_mul_f32 v[92:93], v[92:93], v[96:97]
	v_pk_mul_f32 v[88:89], v[88:89], v[100:101] op_sel_hi:[1,0]
	v_pk_mul_f32 v[84:85], v[84:85], v[92:93]
	v_pk_mul_f32 v[92:93], v[94:95], v[98:99]
	v_mul_f32_e32 v94, 0xbfb8aa3b, v88
	v_exp_f32_e32 v94, v94
	v_pk_mul_f32 v[86:87], v[86:87], v[100:101] op_sel_hi:[1,0]
	v_pk_mul_f32 v[90:91], v[90:91], v[100:101] op_sel_hi:[1,0]
	v_pk_mul_f32 v[86:87], v[86:87], v[92:93]
	v_mul_f32_e32 v92, 0xbfb8aa3b, v89
	v_exp_f32_e32 v93, v92
	v_add_f32_e32 v92, 1.0, v94
	v_mul_f32_e32 v94, 0xbfb8aa3b, v90
	v_mul_f32_e32 v95, 0xbfb8aa3b, v91
	v_exp_f32_e32 v94, v94
	v_exp_f32_e32 v95, v95
	v_add_f32_e32 v93, 1.0, v93
	v_rcp_f32_e32 v92, v92
	v_rcp_f32_e32 v93, v93
	v_add_f32_e32 v94, 1.0, v94
	v_add_f32_e32 v95, 1.0, v95
	v_rcp_f32_e32 v94, v94
	v_rcp_f32_e32 v95, v95
	v_pk_mul_f32 v[80:81], v[80:81], v[100:101] op_sel_hi:[1,0]
	v_pk_mul_f32 v[88:89], v[88:89], v[92:93]
	v_or_b32_e32 v92, 32, v151
	v_pk_mul_f32 v[88:89], v[80:81], v[88:89]
	v_pk_mul_f32 v[80:81], v[82:83], v[100:101] op_sel_hi:[1,0]
	v_pk_mul_f32 v[82:83], v[90:91], v[94:95]
	s_mov_b64 s[26:27], s[16:17]
	v_pk_mul_f32 v[90:91], v[80:81], v[82:83]
	v_cvt_pk_bf16_f32 v81, v86, v87
	v_mov_b32_e32 v86, v101
	v_pk_mul_f32 v[76:77], v[76:77], v[86:87] op_sel_hi:[1,0]
	v_cvt_pk_bf16_f32 v80, v84, v85
	v_mul_f32_e32 v87, 0xbfb8aa3b, v76
	v_exp_f32_e32 v87, v87
	v_mad_i64_i32 v[84:85], s[20:21], v92, s49, v[112:113]
	v_cvt_pk_bf16_f32 v82, v88, v89
	v_cvt_pk_bf16_f32 v83, v90, v91
	v_lshl_add_u64 v[84:85], v[84:85], 0, v[114:115]
	global_store_dwordx4 v[84:85], v[80:83], off nt
	v_pk_mul_f32 v[78:79], v[78:79], v[86:87] op_sel_hi:[1,0]
	v_pk_mul_f32 v[68:69], v[68:69], v[86:87] op_sel_hi:[1,0]
	v_mul_f32_e32 v80, 0xbfb8aa3b, v77
	v_exp_f32_e32 v81, v80
	v_mul_f32_e32 v82, 0xbfb8aa3b, v78
	v_mul_f32_e32 v83, 0xbfb8aa3b, v79
	v_exp_f32_e32 v82, v82
	v_exp_f32_e32 v83, v83
	v_add_f32_e32 v80, 1.0, v87
	v_add_f32_e32 v81, 1.0, v81
	v_rcp_f32_e32 v80, v80
	v_rcp_f32_e32 v81, v81
	v_add_f32_e32 v82, 1.0, v82
	v_add_f32_e32 v83, 1.0, v83
	v_rcp_f32_e32 v82, v82
	v_rcp_f32_e32 v83, v83
	v_pk_mul_f32 v[76:77], v[76:77], v[80:81]
	v_pk_mul_f32 v[72:73], v[72:73], v[86:87] op_sel_hi:[1,0]
	v_pk_mul_f32 v[68:69], v[68:69], v[76:77]
	v_pk_mul_f32 v[76:77], v[78:79], v[82:83]
	v_mul_f32_e32 v78, 0xbfb8aa3b, v72
	v_exp_f32_e32 v78, v78
	v_pk_mul_f32 v[70:71], v[70:71], v[86:87] op_sel_hi:[1,0]
	v_pk_mul_f32 v[74:75], v[74:75], v[86:87] op_sel_hi:[1,0]
	v_pk_mul_f32 v[70:71], v[70:71], v[76:77]
	v_mul_f32_e32 v76, 0xbfb8aa3b, v73
	v_exp_f32_e32 v77, v76
	v_add_f32_e32 v76, 1.0, v78
	v_mul_f32_e32 v78, 0xbfb8aa3b, v74
	v_mul_f32_e32 v79, 0xbfb8aa3b, v75
	v_exp_f32_e32 v78, v78
	v_exp_f32_e32 v79, v79
	v_add_f32_e32 v77, 1.0, v77
	v_rcp_f32_e32 v76, v76
	v_rcp_f32_e32 v77, v77
	v_add_f32_e32 v78, 1.0, v78
	v_add_f32_e32 v79, 1.0, v79
	v_rcp_f32_e32 v78, v78
	v_rcp_f32_e32 v79, v79
	v_pk_mul_f32 v[64:65], v[64:65], v[86:87] op_sel_hi:[1,0]
	v_pk_mul_f32 v[72:73], v[72:73], v[76:77]
	v_or_b32_e32 v76, 48, v151
	v_pk_mul_f32 v[72:73], v[64:65], v[72:73]
	v_pk_mul_f32 v[64:65], v[66:67], v[86:87] op_sel_hi:[1,0]
	v_pk_mul_f32 v[66:67], v[74:75], v[78:79]
	s_mov_b32 s51, s50
	v_pk_mul_f32 v[74:75], v[64:65], v[66:67]
	v_cvt_pk_bf16_f32 v64, v68, v69
	ds_read2_b32 v[68:69], v152 offset0:128 offset1:144
	v_cvt_pk_bf16_f32 v65, v70, v71
	v_mad_i64_i32 v[70:71], s[20:21], v76, s49, v[112:113]
	v_cvt_pk_bf16_f32 v66, v72, v73
	v_cvt_pk_bf16_f32 v67, v74, v75
	v_lshl_add_u64 v[70:71], v[70:71], 0, v[114:115]
	s_waitcnt lgkmcnt(0)
	v_pk_mul_f32 v[60:61], v[60:61], v[68:69] op_sel_hi:[1,0]
	global_store_dwordx4 v[70:71], v[64:67], off nt
	v_pk_mul_f32 v[62:63], v[62:63], v[68:69] op_sel_hi:[1,0]
	v_pk_mul_f32 v[52:53], v[52:53], v[68:69] op_sel_hi:[1,0]
	v_mul_f32_e32 v64, 0xbfb8aa3b, v60
	v_mul_f32_e32 v65, 0xbfb8aa3b, v61
	v_exp_f32_e32 v64, v64
	v_exp_f32_e32 v65, v65
	v_mul_f32_e32 v66, 0xbfb8aa3b, v62
	v_mul_f32_e32 v67, 0xbfb8aa3b, v63
	v_exp_f32_e32 v66, v66
	v_exp_f32_e32 v67, v67
	v_add_f32_e32 v64, 1.0, v64
	v_add_f32_e32 v65, 1.0, v65
	v_rcp_f32_e32 v64, v64
	v_rcp_f32_e32 v65, v65
	v_add_f32_e32 v66, 1.0, v66
	v_add_f32_e32 v67, 1.0, v67
	v_rcp_f32_e32 v66, v66
	v_rcp_f32_e32 v67, v67
	v_pk_mul_f32 v[60:61], v[60:61], v[64:65]
	v_pk_mul_f32 v[56:57], v[56:57], v[68:69] op_sel_hi:[1,0]
	v_pk_mul_f32 v[52:53], v[52:53], v[60:61]
	v_pk_mul_f32 v[60:61], v[62:63], v[66:67]
	v_mul_f32_e32 v62, 0xbfb8aa3b, v56
	v_exp_f32_e32 v62, v62
	v_pk_mul_f32 v[54:55], v[54:55], v[68:69] op_sel_hi:[1,0]
	v_pk_mul_f32 v[58:59], v[58:59], v[68:69] op_sel_hi:[1,0]
	v_pk_mul_f32 v[54:55], v[54:55], v[60:61]
	v_mul_f32_e32 v60, 0xbfb8aa3b, v57
	v_exp_f32_e32 v61, v60
	v_add_f32_e32 v60, 1.0, v62
	v_mul_f32_e32 v62, 0xbfb8aa3b, v58
	v_mul_f32_e32 v63, 0xbfb8aa3b, v59
	v_exp_f32_e32 v62, v62
	v_exp_f32_e32 v63, v63
	v_add_f32_e32 v61, 1.0, v61
	v_rcp_f32_e32 v60, v60
	v_rcp_f32_e32 v61, v61
	v_add_f32_e32 v62, 1.0, v62
	v_add_f32_e32 v63, 1.0, v63
	v_rcp_f32_e32 v62, v62
	v_rcp_f32_e32 v63, v63
	v_pk_mul_f32 v[48:49], v[48:49], v[68:69] op_sel_hi:[1,0]
	v_pk_mul_f32 v[56:57], v[56:57], v[60:61]
	v_add_u32_e32 v70, 0x80, v151
	v_pk_mul_f32 v[56:57], v[48:49], v[56:57]
	v_pk_mul_f32 v[48:49], v[50:51], v[68:69] op_sel_hi:[1,0]
	v_pk_mul_f32 v[50:51], v[58:59], v[62:63]
	s_nop 0
	v_pk_mul_f32 v[58:59], v[48:49], v[50:51]
	v_cvt_pk_bf16_f32 v49, v54, v55
	v_mov_b32_e32 v54, v69
	v_pk_mul_f32 v[44:45], v[44:45], v[54:55] op_sel_hi:[1,0]
	v_cvt_pk_bf16_f32 v48, v52, v53
	v_mul_f32_e32 v55, 0xbfb8aa3b, v44
	v_exp_f32_e32 v55, v55
	v_mad_i64_i32 v[52:53], s[20:21], v70, s49, v[112:113]
	v_cvt_pk_bf16_f32 v50, v56, v57
	v_cvt_pk_bf16_f32 v51, v58, v59
	v_lshl_add_u64 v[52:53], v[52:53], 0, v[114:115]
	global_store_dwordx4 v[52:53], v[48:51], off nt
	v_pk_mul_f32 v[46:47], v[46:47], v[54:55] op_sel_hi:[1,0]
	v_pk_mul_f32 v[36:37], v[36:37], v[54:55] op_sel_hi:[1,0]
	v_mul_f32_e32 v48, 0xbfb8aa3b, v45
	v_exp_f32_e32 v49, v48
	v_mul_f32_e32 v50, 0xbfb8aa3b, v46
	v_mul_f32_e32 v51, 0xbfb8aa3b, v47
	v_exp_f32_e32 v50, v50
	v_exp_f32_e32 v51, v51
	v_add_f32_e32 v48, 1.0, v55
	v_add_f32_e32 v49, 1.0, v49
	v_rcp_f32_e32 v48, v48
	v_rcp_f32_e32 v49, v49
	v_add_f32_e32 v50, 1.0, v50
	v_add_f32_e32 v51, 1.0, v51
	v_rcp_f32_e32 v50, v50
	v_rcp_f32_e32 v51, v51
	v_pk_mul_f32 v[44:45], v[44:45], v[48:49]
	v_pk_mul_f32 v[40:41], v[40:41], v[54:55] op_sel_hi:[1,0]
	v_pk_mul_f32 v[36:37], v[36:37], v[44:45]
	v_pk_mul_f32 v[44:45], v[46:47], v[50:51]
	v_mul_f32_e32 v46, 0xbfb8aa3b, v40
	v_exp_f32_e32 v46, v46
	v_pk_mul_f32 v[38:39], v[38:39], v[54:55] op_sel_hi:[1,0]
	v_pk_mul_f32 v[42:43], v[42:43], v[54:55] op_sel_hi:[1,0]
	v_pk_mul_f32 v[38:39], v[38:39], v[44:45]
	v_mul_f32_e32 v44, 0xbfb8aa3b, v41
	v_exp_f32_e32 v45, v44
	v_add_f32_e32 v44, 1.0, v46
	v_mul_f32_e32 v46, 0xbfb8aa3b, v42
	v_mul_f32_e32 v47, 0xbfb8aa3b, v43
	v_exp_f32_e32 v46, v46
	v_exp_f32_e32 v47, v47
	v_add_f32_e32 v45, 1.0, v45
	v_rcp_f32_e32 v44, v44
	v_rcp_f32_e32 v45, v45
	v_add_f32_e32 v46, 1.0, v46
	v_add_f32_e32 v47, 1.0, v47
	v_rcp_f32_e32 v46, v46
	v_rcp_f32_e32 v47, v47
	v_pk_mul_f32 v[32:33], v[32:33], v[54:55] op_sel_hi:[1,0]
	v_pk_mul_f32 v[40:41], v[40:41], v[44:45]
	v_add_u32_e32 v44, 0x90, v151
	v_pk_mul_f32 v[40:41], v[32:33], v[40:41]
	v_pk_mul_f32 v[32:33], v[34:35], v[54:55] op_sel_hi:[1,0]
	v_pk_mul_f32 v[34:35], v[42:43], v[46:47]
	s_nop 0
	v_pk_mul_f32 v[42:43], v[32:33], v[34:35]
	v_cvt_pk_bf16_f32 v32, v36, v37
	ds_read2_b32 v[36:37], v152 offset0:160 offset1:176
	v_cvt_pk_bf16_f32 v33, v38, v39
	v_mad_i64_i32 v[38:39], s[20:21], v44, s49, v[112:113]
	v_cvt_pk_bf16_f32 v34, v40, v41
	v_cvt_pk_bf16_f32 v35, v42, v43
	v_lshl_add_u64 v[38:39], v[38:39], 0, v[114:115]
	s_waitcnt lgkmcnt(0)
	v_pk_mul_f32 v[28:29], v[28:29], v[36:37] op_sel_hi:[1,0]
	global_store_dwordx4 v[38:39], v[32:35], off nt
	v_mul_f32_e32 v40, 0xbfb8aa3b, v28
	v_pk_mul_f32 v[30:31], v[30:31], v[36:37] op_sel_hi:[1,0]
	v_mul_f32_e32 v32, 0xbfb8aa3b, v29
	v_exp_f32_e32 v40, v40
	v_exp_f32_e32 v33, v32
	v_mul_f32_e32 v34, 0xbfb8aa3b, v30
	v_mul_f32_e32 v35, 0xbfb8aa3b, v31
	v_exp_f32_e32 v34, v34
	v_exp_f32_e32 v35, v35
	v_add_f32_e32 v32, 1.0, v40
	v_add_f32_e32 v33, 1.0, v33
	v_rcp_f32_e32 v32, v32
	v_rcp_f32_e32 v33, v33
	v_add_f32_e32 v34, 1.0, v34
	v_add_f32_e32 v35, 1.0, v35
	v_rcp_f32_e32 v34, v34
	v_rcp_f32_e32 v35, v35
	v_pk_mul_f32 v[20:21], v[20:21], v[36:37] op_sel_hi:[1,0]
	v_pk_mul_f32 v[28:29], v[28:29], v[32:33]
	v_pk_mul_f32 v[24:25], v[24:25], v[36:37] op_sel_hi:[1,0]
	v_pk_mul_f32 v[20:21], v[20:21], v[28:29]
	v_pk_mul_f32 v[28:29], v[30:31], v[34:35]
	v_mul_f32_e32 v30, 0xbfb8aa3b, v24
	v_exp_f32_e32 v30, v30
	v_pk_mul_f32 v[22:23], v[22:23], v[36:37] op_sel_hi:[1,0]
	v_pk_mul_f32 v[26:27], v[26:27], v[36:37] op_sel_hi:[1,0]
	v_pk_mul_f32 v[22:23], v[22:23], v[28:29]
	v_mul_f32_e32 v28, 0xbfb8aa3b, v25
	v_exp_f32_e32 v29, v28
	v_add_f32_e32 v28, 1.0, v30
	v_mul_f32_e32 v30, 0xbfb8aa3b, v26
	v_mul_f32_e32 v31, 0xbfb8aa3b, v27
	v_exp_f32_e32 v30, v30
	v_exp_f32_e32 v31, v31
	v_add_f32_e32 v29, 1.0, v29
	v_rcp_f32_e32 v28, v28
	v_rcp_f32_e32 v29, v29
	v_add_f32_e32 v30, 1.0, v30
	v_add_f32_e32 v31, 1.0, v31
	v_rcp_f32_e32 v30, v30
	v_rcp_f32_e32 v31, v31
	v_pk_mul_f32 v[16:17], v[16:17], v[36:37] op_sel_hi:[1,0]
	v_pk_mul_f32 v[24:25], v[24:25], v[28:29]
	v_add_u32_e32 v28, 0xa0, v151
	v_pk_mul_f32 v[24:25], v[16:17], v[24:25]
	v_pk_mul_f32 v[16:17], v[18:19], v[36:37] op_sel_hi:[1,0]
	v_pk_mul_f32 v[18:19], v[26:27], v[30:31]
	s_nop 0
	v_pk_mul_f32 v[26:27], v[16:17], v[18:19]
	v_cvt_pk_bf16_f32 v17, v22, v23
	v_mov_b32_e32 v22, v37
	v_pk_mul_f32 v[12:13], v[12:13], v[22:23] op_sel_hi:[1,0]
	v_cvt_pk_bf16_f32 v16, v20, v21
	v_mul_f32_e32 v23, 0xbfb8aa3b, v12
	v_exp_f32_e32 v23, v23
	v_mad_i64_i32 v[20:21], s[20:21], v28, s49, v[112:113]
	v_cvt_pk_bf16_f32 v18, v24, v25
	v_cvt_pk_bf16_f32 v19, v26, v27
	v_lshl_add_u64 v[20:21], v[20:21], 0, v[114:115]
	global_store_dwordx4 v[20:21], v[16:19], off nt
	v_pk_mul_f32 v[14:15], v[14:15], v[22:23] op_sel_hi:[1,0]
	v_pk_mul_f32 v[4:5], v[4:5], v[22:23] op_sel_hi:[1,0]
	v_mul_f32_e32 v16, 0xbfb8aa3b, v13
	v_exp_f32_e32 v17, v16
	v_mul_f32_e32 v18, 0xbfb8aa3b, v14
	v_mul_f32_e32 v19, 0xbfb8aa3b, v15
	v_exp_f32_e32 v18, v18
	v_exp_f32_e32 v19, v19
	v_add_f32_e32 v16, 1.0, v23
	v_add_f32_e32 v17, 1.0, v17
	v_rcp_f32_e32 v16, v16
	v_rcp_f32_e32 v17, v17
	v_add_f32_e32 v18, 1.0, v18
	v_add_f32_e32 v19, 1.0, v19
	v_rcp_f32_e32 v18, v18
	v_rcp_f32_e32 v19, v19
	v_pk_mul_f32 v[12:13], v[12:13], v[16:17]
	v_pk_mul_f32 v[8:9], v[8:9], v[22:23] op_sel_hi:[1,0]
	v_pk_mul_f32 v[4:5], v[4:5], v[12:13]
	v_pk_mul_f32 v[12:13], v[14:15], v[18:19]
	v_mul_f32_e32 v14, 0xbfb8aa3b, v8
	v_exp_f32_e32 v14, v14
	v_pk_mul_f32 v[6:7], v[6:7], v[22:23] op_sel_hi:[1,0]
	v_pk_mul_f32 v[10:11], v[10:11], v[22:23] op_sel_hi:[1,0]
	v_pk_mul_f32 v[6:7], v[6:7], v[12:13]
	v_mul_f32_e32 v12, 0xbfb8aa3b, v9
	v_exp_f32_e32 v13, v12
	v_add_f32_e32 v12, 1.0, v14
	v_mul_f32_e32 v14, 0xbfb8aa3b, v10
	v_mul_f32_e32 v15, 0xbfb8aa3b, v11
	v_exp_f32_e32 v14, v14
	v_exp_f32_e32 v15, v15
	v_add_f32_e32 v13, 1.0, v13
	v_rcp_f32_e32 v12, v12
	v_rcp_f32_e32 v13, v13
	v_add_f32_e32 v14, 1.0, v14
	v_add_f32_e32 v15, 1.0, v15
	v_rcp_f32_e32 v14, v14
	v_rcp_f32_e32 v15, v15
	v_pk_mul_f32 v[0:1], v[0:1], v[22:23] op_sel_hi:[1,0]
	v_pk_mul_f32 v[8:9], v[8:9], v[12:13]
	v_add_u32_e32 v12, 0xb0, v151
	v_pk_mul_f32 v[8:9], v[0:1], v[8:9]
	v_pk_mul_f32 v[0:1], v[2:3], v[22:23] op_sel_hi:[1,0]
	v_pk_mul_f32 v[2:3], v[10:11], v[14:15]
	s_nop 0
	v_pk_mul_f32 v[10:11], v[0:1], v[2:3]
	v_cvt_pk_bf16_f32 v0, v4, v5
	v_mad_i64_i32 v[4:5], s[20:21], v12, s49, v[112:113]
	v_cvt_pk_bf16_f32 v1, v6, v7
	v_cvt_pk_bf16_f32 v2, v8, v9
	v_cvt_pk_bf16_f32 v3, v10, v11
	v_lshl_add_u64 v[4:5], v[4:5], 0, v[114:115]
	s_mov_b64 s[20:21], s[14:15]
	global_store_dwordx4 v[4:5], v[0:3], off nt
	s_cbranch_vccz .LBB0_890
	s_waitcnt vmcnt(0)
	s_cmpk_gt_u32 s30, 0xff
	s_cbranch_scc1 .LBB0_897

.LBB0_962:
	v_ashrrev_i32_e32 v1, 31, v240
	v_lshrrev_b32_e32 v1, 26, v1
	v_add_u32_e32 v1, v240, v1
	v_ashrrev_i32_e32 v8, 6, v1
	v_bfe_i32 v1, v240, 27, 1
	v_lshlrev_b32_e32 v0, 4, v240
	v_lshrrev_b32_e32 v1, 22, v1
	v_add_u32_e32 v1, v0, v1
	v_and_b32_e32 v1, 0xfffffc00, v1
	v_sub_u32_e32 v1, v0, v1
	v_lshrrev_b32_e32 v2, 4, v1
	v_bitop3_b32 v1, v2, v1, 32 bitop3:0x6c
	v_ashrrev_i32_e32 v3, 31, v1
	v_lshrrev_b32_e32 v3, 26, v3
	v_lshlrev_b32_e32 v2, 3, v8
	v_add_u32_e32 v3, v1, v3
	v_and_b32_e32 v2, -16, v2
	v_ashrrev_i32_e32 v10, 6, v3
	v_and_b32_e32 v3, 0xc0, v3
	v_add_u32_e32 v2, v10, v2
	v_lshlrev_b32_e32 v4, 5, v8
	v_sub_u32_e32 v1, v1, v3
	v_mov_b32_e32 v3, 1
	v_and_b32_e32 v9, 32, v4
	v_ashrrev_i16_sdwa v1, v3, sext(v1) dst_sel:DWORD dst_unused:UNUSED_PAD src0_sel:DWORD src1_sel:BYTE_0
	v_lshlrev_b32_e32 v4, 1, v2
	v_lshrrev_b32_e32 v5, 2, v2
	v_and_b32_e32 v6, 3, v10
	s_mov_b32 s6, 0xffffe0
	v_bfe_i32 v11, v1, 0, 16
	v_and_b32_e32 v4, 24, v4
	v_and_b32_e32 v5, 4, v5
	v_and_or_b32 v6, v2, s6, v6
	s_movk_i32 s2, 0xb00
	v_add_u32_e32 v1, v9, v11
	v_or3_b32 v4, v6, v5, v4
	v_mul_lo_u32 v2, v2, s2
	v_add_lshl_u32 v128, v1, v2, 1
	v_mul_u32_u24_e32 v2, 0xb00, v4
	v_add_u32_e32 v0, 0x2000, v0
	v_add_lshl_u32 v130, v2, v1, 1
	v_ashrrev_i32_e32 v1, 31, v0
	v_lshrrev_b32_e32 v1, 22, v1
	v_add_u32_e32 v1, v0, v1
	v_ashrrev_i32_e32 v12, 10, v1
	v_mul_i32_i24_e32 v1, 0x400, v12
	v_sub_u32_e32 v0, v0, v1
	v_lshrrev_b32_e32 v1, 4, v0
	v_bitop3_b32 v0, v1, v0, 32 bitop3:0x6c
	v_ashrrev_i32_e32 v2, 31, v0
	s_add_u32 s31, s4, 0x9800000
	v_lshrrev_b32_e32 v2, 26, v2
	s_addc_u32 s33, s5, 0
	v_lshlrev_b32_e32 v1, 3, v12
	v_add_u32_e32 v2, v0, v2
	s_add_u32 s34, s4, 0x2280000
	v_and_b32_e32 v1, -16, v1
	v_ashrrev_i32_e32 v13, 6, v2
	v_lshlrev_b32_e32 v4, 5, v12
	s_addc_u32 s35, s5, 0
	s_ashr_i32 s3, s30, 6
	v_add_u32_e32 v1, v13, v1
	v_and_b32_e32 v14, 32, v4
	v_and_b32_e32 v2, 0xc0, v2
	v_and_b32_e32 v4, 3, v13
	v_sub_u32_e32 v0, v0, v2
	v_and_or_b32 v4, v1, s6, v4
	s_ashr_i32 s6, s30, 8
	s_lshl_b32 s36, s3, 10
	s_mul_i32 s11, s10, 0x160000
	v_ashrrev_i16_sdwa v0, v3, sext(v0) dst_sel:DWORD dst_unused:UNUSED_PAD src0_sel:DWORD src1_sel:BYTE_0
	v_lshlrev_b32_e32 v2, 1, v1
	v_lshrrev_b32_e32 v3, 2, v1
	s_mul_hi_i32 s9, s10, 0x160000
	s_add_u32 s22, s34, s11
	v_bfe_i32 v15, v0, 0, 16
	v_and_b32_e32 v2, 24, v2
	v_and_b32_e32 v3, 4, v3
	s_addc_u32 s23, s35, s9
	s_add_i32 s37, s36, 0
	v_add_u32_e32 v0, v14, v15
	v_or3_b32 v2, v4, v3, v2
	v_mul_lo_u32 v1, v1, s2
	s_add_i32 m0, s37, 0x10000
	v_add_lshl_u32 v132, v0, v1, 1
	v_mul_u32_u24_e32 v1, 0xb00, v2
	s_mul_i32 s8, s53, 0x160000
	global_load_lds_dwordx4 v130, s[22:23]
	s_add_i32 m0, s37, 0x12000
	v_add_lshl_u32 v134, v1, v0, 1
	s_mul_hi_i32 s7, s53, 0x160000
	s_add_u32 s20, s31, s8
	global_load_lds_dwordx4 v134, s[22:23]
	s_addc_u32 s21, s33, s7
	s_mov_b32 m0, s37
	s_add_i32 s38, s37, 0x2000
	global_load_lds_dwordx4 v128, s[20:21]
	s_mov_b32 m0, s38
	s_add_u32 s8, s22, 0xb0000
	global_load_lds_dwordx4 v132, s[20:21]
	s_addc_u32 s9, s23, 0
	s_add_i32 m0, s37, 0x14000
	v_mov_b32_e32 v131, 0
	global_load_lds_dwordx4 v130, s[8:9]
	s_add_i32 m0, s37, 0x16000
	v_mov_b32_e32 v135, v131
	global_load_lds_dwordx4 v134, s[8:9]
	s_add_u32 s8, s20, 0xb0000
	s_addc_u32 s9, s21, 0
	s_add_i32 s39, s37, 0x4000
	s_mov_b32 m0, s39
	s_add_i32 s40, s37, 0x6000
	global_load_lds_dwordx4 v128, s[8:9]
	s_mov_b32 m0, s40
	v_mov_b32_e32 v129, v131
	global_load_lds_dwordx4 v132, s[8:9]
	s_load_dwordx2 s[8:9], s[0:1], 0xa0
	v_mov_b32_e32 v133, v131
	s_mov_b32 s11, 0
	v_lshl_add_u64 v[6:7], s[22:23], 0, v[130:131]
	v_lshl_add_u64 v[4:5], s[22:23], 0, v[134:135]
	v_lshl_add_u64 v[2:3], s[20:21], 0, v[128:129]
	s_cmp_lg_u32 s6, 1
	v_lshl_add_u64 v[0:1], s[20:21], 0, v[132:133]
	s_cbranch_scc1 .LBB0_964
.LBB0_964:
	s_add_u32 s12, s4, 0x3800000
	s_addc_u32 s13, s5, 0
	s_add_u32 s14, s4, 0x3300000
	s_addc_u32 s15, s5, 0
	s_add_u32 s16, s4, 0x3798b00
	s_mov_b64 s[18:19], 0x80
	s_addc_u32 s17, s5, 0
	s_and_b32 s41, s3, 3
	s_add_i32 m0, s37, 0x18000
	v_lshl_add_u64 v[6:7], v[6:7], 0, s[18:19]
	s_lshl_b32 s3, s6, 13
	s_lshl_b32 s4, s41, 12
	s_waitcnt vmcnt(4)
	s_barrier
	global_load_lds_dwordx4 v[6:7], off
	v_lshl_add_u64 v[4:5], v[4:5], 0, s[18:19]
	s_add_i32 m0, s37, 0x1a000
	s_add_i32 s42, s37, 0x8000
	s_add_i32 s43, s37, 0xa000
	global_load_lds_dwordx4 v[4:5], off
	v_lshl_add_u64 v[2:3], v[2:3], 0, s[18:19]
	s_mov_b32 m0, s42
	s_add_u32 s0, s22, 0xb0080
	global_load_lds_dwordx4 v[2:3], off
	v_lshl_add_u64 v[0:1], v[0:1], 0, s[18:19]
	s_mov_b32 m0, s43
	s_addc_u32 s1, s23, 0
	global_load_lds_dwordx4 v[0:1], off
	s_add_i32 m0, s37, 0x1c000
	v_lshl_add_u64 v[0:1], s[0:1], 0, v[130:131]
	global_load_lds_dwordx4 v[0:1], off
	v_lshl_add_u64 v[0:1], s[0:1], 0, v[134:135]
	s_add_i32 m0, s37, 0x1e000
	v_bfe_u32 v2, v240, 4, 2
	global_load_lds_dwordx4 v[0:1], off
	v_and_b32_e32 v1, 15, v240
	v_lshlrev_b32_e32 v0, 4, v2
	v_lshlrev_b32_e32 v4, 2, v240
	v_lshl_or_b32 v200, s6, 6, v1
	v_lshl_or_b32 v1, v1, 6, v0
	v_and_b32_e32 v4, 32, v4
	v_bitop3_b32 v5, v1, s3, v4 bitop3:0xde
	v_bitop3_b32 v201, s4, v1, v4 bitop3:0xf6
	v_mov_b32_e32 v1, v131
	v_lshl_add_u64 v[136:137], s[14:15], 0, v[0:1]
	v_lshrrev_b32_e32 v1, 1, v8
	v_mul_lo_u32 v0, v10, s2
	s_mov_b32 s3, 0xb000
	v_mad_u64_u32 v[0:1], s[6:7], v1, s3, v[0:1]
	v_or_b32_e32 v0, v0, v9
	s_mov_b64 s[4:5], 0xb0080
	v_add_lshl_u32 v0, v0, v11, 1
	v_mov_b32_e32 v1, v131
	v_lshl_add_u64 v[138:139], v[0:1], 0, s[4:5]
	v_lshrrev_b32_e32 v1, 1, v12
	v_mul_lo_u32 v0, v13, s2
	v_mad_u64_u32 v[0:1], s[2:3], v1, s3, v[0:1]
	s_waitcnt vmcnt(6)
	v_or_b32_e32 v0, v0, v14
	v_lshlrev_b32_e32 v3, 3, v2
	v_add_lshl_u32 v0, v0, v15, 1
	v_mov_b32_e32 v1, v131
	s_add_i32 s47, 0, 0x10000
	s_add_i32 s48, 0, 0x14000
	v_lshl_or_b32 v202, s41, 5, v3
	v_cmp_eq_u32_e64 s[0:1], 0, v2
	s_ashr_i32 s44, s29, 31
	s_ashr_i32 s45, s28, 31
	v_lshl_add_u64 v[140:141], v[0:1], 0, s[4:5]
	v_mov_b64_e32 v[142:143], 0x300
	v_mov_b64_e32 v[144:145], 0x2ff
	s_movk_i32 s46, 0x61
	v_add_u32_e32 v203, s47, v201
	v_add_u32_e32 v204, 0, v5
	v_add_u32_e32 v205, s48, v201
	v_mbcnt_hi_u32_b32 v206, -1, v241
	v_mov_b32_e32 v207, 0x358637bd
	s_mov_b32 s49, 0x800000
	s_mov_b32 s50, 0
	s_barrier
	s_branch .LBB0_966

.LBB0_972:
	s_add_u32 s54, s22, 0x100
	v_mov_b32_e32 v0, 0
	s_addc_u32 s55, s23, 0
	s_mov_b32 s56, -2
	v_mov_b32_e32 v1, v0
	v_mov_b32_e32 v2, v0
	v_mov_b32_e32 v3, v0
	v_mov_b32_e32 v4, v0
	v_mov_b32_e32 v5, v0
	v_mov_b32_e32 v6, v0
	v_mov_b32_e32 v7, v0
	v_mov_b32_e32 v16, v0
	v_mov_b32_e32 v17, v0
	v_mov_b32_e32 v18, v0
	v_mov_b32_e32 v19, v0
	v_mov_b32_e32 v20, v0
	v_mov_b32_e32 v21, v0
	v_mov_b32_e32 v22, v0
	v_mov_b32_e32 v23, v0
	v_mov_b32_e32 v32, v0
	v_mov_b32_e32 v33, v0
	v_mov_b32_e32 v34, v0
	v_mov_b32_e32 v35, v0
	v_mov_b32_e32 v36, v0
	v_mov_b32_e32 v37, v0
	v_mov_b32_e32 v38, v0
	v_mov_b32_e32 v39, v0
	v_mov_b32_e32 v48, v0
	v_mov_b32_e32 v49, v0
	v_mov_b32_e32 v50, v0
	v_mov_b32_e32 v51, v0
	v_mov_b32_e32 v52, v0
	v_mov_b32_e32 v53, v0
	v_mov_b32_e32 v54, v0
	v_mov_b32_e32 v55, v0
	v_mov_b32_e32 v8, v0
	v_mov_b32_e32 v9, v0
	v_mov_b32_e32 v10, v0
	v_mov_b32_e32 v11, v0
	v_mov_b32_e32 v12, v0
	v_mov_b32_e32 v13, v0
	v_mov_b32_e32 v14, v0
	v_mov_b32_e32 v15, v0
	v_mov_b32_e32 v24, v0
	v_mov_b32_e32 v25, v0
	v_mov_b32_e32 v26, v0
	v_mov_b32_e32 v27, v0
	v_mov_b32_e32 v28, v0
	v_mov_b32_e32 v29, v0
	v_mov_b32_e32 v30, v0
	v_mov_b32_e32 v31, v0
	v_mov_b32_e32 v40, v0
	v_mov_b32_e32 v41, v0
	v_mov_b32_e32 v42, v0
	v_mov_b32_e32 v43, v0
	v_mov_b32_e32 v44, v0
	v_mov_b32_e32 v45, v0
	v_mov_b32_e32 v46, v0
	v_mov_b32_e32 v47, v0
	v_mov_b32_e32 v56, v0
	v_mov_b32_e32 v57, v0
	v_mov_b32_e32 v58, v0
	v_mov_b32_e32 v59, v0
	v_mov_b32_e32 v60, v0
	v_mov_b32_e32 v61, v0
	v_mov_b32_e32 v62, v0
	v_mov_b32_e32 v63, v0
	v_mov_b32_e32 v64, v0
	v_mov_b32_e32 v65, v0
	v_mov_b32_e32 v66, v0
	v_mov_b32_e32 v67, v0
	v_mov_b32_e32 v68, v0
	v_mov_b32_e32 v69, v0
	v_mov_b32_e32 v70, v0
	v_mov_b32_e32 v71, v0
	v_mov_b32_e32 v80, v0
	v_mov_b32_e32 v81, v0
	v_mov_b32_e32 v82, v0
	v_mov_b32_e32 v83, v0
	v_mov_b32_e32 v84, v0
	v_mov_b32_e32 v85, v0
	v_mov_b32_e32 v86, v0
	v_mov_b32_e32 v87, v0
	v_mov_b32_e32 v96, v0
	v_mov_b32_e32 v97, v0
	v_mov_b32_e32 v98, v0
	v_mov_b32_e32 v99, v0
	v_mov_b32_e32 v100, v0
	v_mov_b32_e32 v101, v0
	v_mov_b32_e32 v102, v0
	v_mov_b32_e32 v103, v0
	v_mov_b32_e32 v112, v0
	v_mov_b32_e32 v113, v0
	v_mov_b32_e32 v114, v0
	v_mov_b32_e32 v115, v0
	v_mov_b32_e32 v116, v0
	v_mov_b32_e32 v117, v0
	v_mov_b32_e32 v118, v0
	v_mov_b32_e32 v119, v0
	v_mov_b32_e32 v72, v0
	v_mov_b32_e32 v73, v0
	v_mov_b32_e32 v74, v0
	v_mov_b32_e32 v75, v0
	v_mov_b32_e32 v76, v0
	v_mov_b32_e32 v77, v0
	v_mov_b32_e32 v78, v0
	v_mov_b32_e32 v79, v0
	v_mov_b32_e32 v88, v0
	v_mov_b32_e32 v89, v0
	v_mov_b32_e32 v90, v0
	v_mov_b32_e32 v91, v0
	v_mov_b32_e32 v92, v0
	v_mov_b32_e32 v93, v0
	v_mov_b32_e32 v94, v0
	v_mov_b32_e32 v95, v0
	v_mov_b32_e32 v104, v0
	v_mov_b32_e32 v105, v0
	v_mov_b32_e32 v106, v0
	v_mov_b32_e32 v107, v0
	v_mov_b32_e32 v108, v0
	v_mov_b32_e32 v109, v0
	v_mov_b32_e32 v110, v0
	v_mov_b32_e32 v111, v0
	v_mov_b32_e32 v120, v0
	v_mov_b32_e32 v121, v0
	v_mov_b32_e32 v122, v0
	v_mov_b32_e32 v123, v0
	v_mov_b32_e32 v124, v0
	v_mov_b32_e32 v125, v0
	v_mov_b32_e32 v126, v0
	v_mov_b32_e32 v127, v0
	s_cmpk_lt_u32 s30, 0x100
	s_cbranch_scc1 .Lg973_noy
	s_barrier
.Lg973_noy:
.LBB0_973:
	ds_read_b128 v[146:149], v203
	ds_read_b128 v[150:153], v203 offset:1024
	ds_read_b128 v[154:157], v203 offset:2048
	ds_read_b128 v[158:161], v203 offset:3072
	s_add_u32 s22, s20, 0x100
	s_addc_u32 s23, s21, 0
	s_cmp_eq_u32 s56, 40
	s_cselect_b32 s27, s5, s23
	s_cselect_b32 s26, s4, s22
	s_cselect_b32 s25, s7, s55
	s_cselect_b32 s24, s6, s54
	s_add_i32 m0, s37, 0xc000
	ds_read_b128 v[162:165], v204
	ds_read_b128 v[166:169], v204 offset:1024
	ds_read_b128 v[170:173], v204 offset:2048
	ds_read_b128 v[174:177], v204 offset:3072
	ds_read_b128 v[178:181], v204 offset:4096
	ds_read_b128 v[182:185], v204 offset:5120
	ds_read_b128 v[186:189], v204 offset:6144
	ds_read_b128 v[190:193], v204 offset:7168
	global_load_lds_dwordx4 v138, s[20:21]
	s_add_i32 m0, s37, 0xe000
	s_nop 0
	global_load_lds_dwordx4 v140, s[20:21]
	s_waitcnt lgkmcnt(8)
	s_barrier
	s_waitcnt lgkmcnt(0)
	s_setprio 1
	s_waitcnt lgkmcnt(0)
	v_mfma_f32_16x16x32_bf16 v[124:127], v[146:149], v[162:165], v[124:127]
	v_mfma_f32_16x16x32_bf16 v[120:123], v[154:157], v[162:165], v[120:123]
	v_mfma_f32_16x16x32_bf16 v[108:111], v[146:149], v[170:173], v[108:111]
	v_mfma_f32_16x16x32_bf16 v[104:107], v[154:157], v[170:173], v[104:107]
	v_mfma_f32_16x16x32_bf16 v[92:95], v[146:149], v[178:181], v[92:95]
	v_mfma_f32_16x16x32_bf16 v[88:91], v[154:157], v[178:181], v[88:91]
	v_mfma_f32_16x16x32_bf16 v[76:79], v[146:149], v[186:189], v[76:79]
	v_mfma_f32_16x16x32_bf16 v[72:75], v[154:157], v[186:189], v[72:75]
	v_mfma_f32_16x16x32_bf16 v[124:127], v[150:153], v[166:169], v[124:127]
	v_mfma_f32_16x16x32_bf16 v[120:123], v[158:161], v[166:169], v[120:123]
	v_mfma_f32_16x16x32_bf16 v[108:111], v[150:153], v[174:177], v[108:111]
	v_mfma_f32_16x16x32_bf16 v[104:107], v[158:161], v[174:177], v[104:107]
	v_mfma_f32_16x16x32_bf16 v[92:95], v[150:153], v[182:185], v[92:95]
	v_mfma_f32_16x16x32_bf16 v[88:91], v[158:161], v[182:185], v[88:91]
	v_mfma_f32_16x16x32_bf16 v[76:79], v[150:153], v[190:193], v[76:79]
	v_mfma_f32_16x16x32_bf16 v[72:75], v[158:161], v[190:193], v[72:75]
	s_setprio 0
	s_barrier
	s_add_i32 s20, s47, s36
	s_add_u32 s80, s24, 0x80
	s_addc_u32 s81, s25, 0
	s_mov_b32 m0, s20
	ds_read_b128 v[194:197], v205
	ds_read_b128 v[208:211], v205 offset:1024
	ds_read_b128 v[212:215], v205 offset:2048
	ds_read_b128 v[216:219], v205 offset:3072
	global_load_lds_dwordx4 v130, s[24:25]
	s_add_i32 m0, s20, 0x2000
	s_nop 0
	global_load_lds_dwordx4 v134, s[24:25]
	s_barrier
	s_waitcnt lgkmcnt(0)
	s_setprio 1
	s_waitcnt lgkmcnt(0)
	v_mfma_f32_16x16x32_bf16 v[116:119], v[194:197], v[162:165], v[116:119]
	v_mfma_f32_16x16x32_bf16 v[112:115], v[212:215], v[162:165], v[112:115]
	v_mfma_f32_16x16x32_bf16 v[100:103], v[194:197], v[170:173], v[100:103]
	v_mfma_f32_16x16x32_bf16 v[96:99], v[212:215], v[170:173], v[96:99]
	v_mfma_f32_16x16x32_bf16 v[84:87], v[194:197], v[178:181], v[84:87]
	v_mfma_f32_16x16x32_bf16 v[80:83], v[212:215], v[178:181], v[80:83]
	v_mfma_f32_16x16x32_bf16 v[68:71], v[194:197], v[186:189], v[68:71]
	v_mfma_f32_16x16x32_bf16 v[64:67], v[212:215], v[186:189], v[64:67]
	v_mfma_f32_16x16x32_bf16 v[116:119], v[208:211], v[166:169], v[116:119]
	v_mfma_f32_16x16x32_bf16 v[112:115], v[216:219], v[166:169], v[112:115]
	v_mfma_f32_16x16x32_bf16 v[100:103], v[208:211], v[174:177], v[100:103]
	v_mfma_f32_16x16x32_bf16 v[96:99], v[216:219], v[174:177], v[96:99]
	v_mfma_f32_16x16x32_bf16 v[84:87], v[208:211], v[182:185], v[84:87]
	v_mfma_f32_16x16x32_bf16 v[80:83], v[216:219], v[182:185], v[80:83]
	v_mfma_f32_16x16x32_bf16 v[68:71], v[208:211], v[190:193], v[68:71]
	v_mfma_f32_16x16x32_bf16 v[64:67], v[216:219], v[190:193], v[64:67]
	s_setprio 0
	s_mov_b32 m0, s37
	s_add_u32 s82, s26, 0x80
	s_addc_u32 s83, s27, 0
	s_barrier
	ds_read_b128 v[162:165], v204 offset:16384
	ds_read_b128 v[166:169], v204 offset:17408
	ds_read_b128 v[170:173], v204 offset:18432
	ds_read_b128 v[174:177], v204 offset:19456
	ds_read_b128 v[178:181], v204 offset:20480
	ds_read_b128 v[182:185], v204 offset:21504
	ds_read_b128 v[186:189], v204 offset:22528
	ds_read_b128 v[190:193], v204 offset:23552
	global_load_lds_dwordx4 v128, s[26:27]
	s_mov_b32 m0, s38
	s_nop 0
	global_load_lds_dwordx4 v132, s[26:27]
	s_barrier
	s_waitcnt lgkmcnt(0)
	s_setprio 1
	s_waitcnt lgkmcnt(0)
	v_mfma_f32_16x16x32_bf16 v[60:63], v[146:149], v[162:165], v[60:63]
	v_mfma_f32_16x16x32_bf16 v[56:59], v[154:157], v[162:165], v[56:59]
	v_mfma_f32_16x16x32_bf16 v[44:47], v[146:149], v[170:173], v[44:47]
	v_mfma_f32_16x16x32_bf16 v[40:43], v[154:157], v[170:173], v[40:43]
	v_mfma_f32_16x16x32_bf16 v[28:31], v[146:149], v[178:181], v[28:31]
	v_mfma_f32_16x16x32_bf16 v[24:27], v[154:157], v[178:181], v[24:27]
	v_mfma_f32_16x16x32_bf16 v[12:15], v[146:149], v[186:189], v[12:15]
	v_mfma_f32_16x16x32_bf16 v[8:11], v[154:157], v[186:189], v[8:11]
	v_mfma_f32_16x16x32_bf16 v[60:63], v[150:153], v[166:169], v[60:63]
	v_mfma_f32_16x16x32_bf16 v[56:59], v[158:161], v[166:169], v[56:59]
	v_mfma_f32_16x16x32_bf16 v[44:47], v[150:153], v[174:177], v[44:47]
	v_mfma_f32_16x16x32_bf16 v[40:43], v[158:161], v[174:177], v[40:43]
	v_mfma_f32_16x16x32_bf16 v[28:31], v[150:153], v[182:185], v[28:31]
	v_mfma_f32_16x16x32_bf16 v[24:27], v[158:161], v[182:185], v[24:27]
	v_mfma_f32_16x16x32_bf16 v[12:15], v[150:153], v[190:193], v[12:15]
	v_mfma_f32_16x16x32_bf16 v[8:11], v[158:161], v[190:193], v[8:11]
	s_setprio 0
	s_barrier
	s_add_u32 s20, s24, 0xb0000
	s_addc_u32 s21, s25, 0
	s_add_i32 s57, s48, s36
	s_mov_b32 m0, s57
	s_nop 0
	global_load_lds_dwordx4 v130, s[20:21]
	s_add_i32 m0, s57, 0x2000
	s_nop 0
	global_load_lds_dwordx4 v134, s[20:21]
	s_waitcnt vmcnt(6)
	s_barrier
	s_setprio 1
	v_mfma_f32_16x16x32_bf16 v[52:55], v[194:197], v[162:165], v[52:55]
	v_mfma_f32_16x16x32_bf16 v[48:51], v[212:215], v[162:165], v[48:51]
	v_mfma_f32_16x16x32_bf16 v[36:39], v[194:197], v[170:173], v[36:39]
	v_mfma_f32_16x16x32_bf16 v[32:35], v[212:215], v[170:173], v[32:35]
	v_mfma_f32_16x16x32_bf16 v[20:23], v[194:197], v[178:181], v[20:23]
	v_mfma_f32_16x16x32_bf16 v[16:19], v[212:215], v[178:181], v[16:19]
	v_mfma_f32_16x16x32_bf16 v[4:7], v[194:197], v[186:189], v[4:7]
	v_mfma_f32_16x16x32_bf16 v[0:3], v[212:215], v[186:189], v[0:3]
	v_mfma_f32_16x16x32_bf16 v[52:55], v[208:211], v[166:169], v[52:55]
	v_mfma_f32_16x16x32_bf16 v[48:51], v[216:219], v[166:169], v[48:51]
	v_mfma_f32_16x16x32_bf16 v[36:39], v[208:211], v[174:177], v[36:39]
	v_mfma_f32_16x16x32_bf16 v[32:35], v[216:219], v[174:177], v[32:35]
	v_mfma_f32_16x16x32_bf16 v[20:23], v[208:211], v[182:185], v[20:23]
	v_mfma_f32_16x16x32_bf16 v[16:19], v[216:219], v[182:185], v[16:19]
	v_mfma_f32_16x16x32_bf16 v[4:7], v[208:211], v[190:193], v[4:7]
	v_mfma_f32_16x16x32_bf16 v[0:3], v[216:219], v[190:193], v[0:3]
	s_setprio 0
	s_add_i32 s57, 0, 0x18000
	v_add_u32_e32 v158, s57, v201
	s_barrier
	ds_read_b128 v[146:149], v158
	ds_read_b128 v[150:153], v158 offset:1024
	ds_read_b128 v[154:157], v158 offset:2048
	ds_read_b128 v[158:161], v158 offset:3072
	s_add_u32 s20, s26, 0xb0000
	s_addc_u32 s21, s27, 0
	s_mov_b32 m0, s39
	ds_read_b128 v[162:165], v204 offset:32768
	ds_read_b128 v[166:169], v204 offset:33792
	ds_read_b128 v[170:173], v204 offset:34816
	ds_read_b128 v[174:177], v204 offset:35840
	ds_read_b128 v[178:181], v204 offset:36864
	ds_read_b128 v[182:185], v204 offset:37888
	ds_read_b128 v[186:189], v204 offset:38912
	ds_read_b128 v[190:193], v204 offset:39936
	global_load_lds_dwordx4 v128, s[20:21]
	s_mov_b32 m0, s40
	s_nop 0
	global_load_lds_dwordx4 v132, s[20:21]
	s_waitcnt lgkmcnt(8)
	s_barrier
	s_waitcnt lgkmcnt(0)
	s_setprio 1
	s_waitcnt lgkmcnt(0)
	v_mfma_f32_16x16x32_bf16 v[124:127], v[146:149], v[162:165], v[124:127]
	v_mfma_f32_16x16x32_bf16 v[120:123], v[154:157], v[162:165], v[120:123]
	v_mfma_f32_16x16x32_bf16 v[108:111], v[146:149], v[170:173], v[108:111]
	v_mfma_f32_16x16x32_bf16 v[104:107], v[154:157], v[170:173], v[104:107]
	v_mfma_f32_16x16x32_bf16 v[92:95], v[146:149], v[178:181], v[92:95]
	v_mfma_f32_16x16x32_bf16 v[88:91], v[154:157], v[178:181], v[88:91]
	v_mfma_f32_16x16x32_bf16 v[76:79], v[146:149], v[186:189], v[76:79]
	v_mfma_f32_16x16x32_bf16 v[72:75], v[154:157], v[186:189], v[72:75]
	v_mfma_f32_16x16x32_bf16 v[124:127], v[150:153], v[166:169], v[124:127]
	v_mfma_f32_16x16x32_bf16 v[120:123], v[158:161], v[166:169], v[120:123]
	v_mfma_f32_16x16x32_bf16 v[108:111], v[150:153], v[174:177], v[108:111]
	v_mfma_f32_16x16x32_bf16 v[104:107], v[158:161], v[174:177], v[104:107]
	v_mfma_f32_16x16x32_bf16 v[92:95], v[150:153], v[182:185], v[92:95]
	v_mfma_f32_16x16x32_bf16 v[88:91], v[158:161], v[182:185], v[88:91]
	v_mfma_f32_16x16x32_bf16 v[76:79], v[150:153], v[190:193], v[76:79]
	v_mfma_f32_16x16x32_bf16 v[72:75], v[158:161], v[190:193], v[72:75]
	s_setprio 0
	s_barrier
	s_add_i32 s26, 0, 0x1c000
	s_add_i32 s20, s57, s36
	v_add_u32_e32 v216, s26, v201
	s_mov_b32 m0, s20
	ds_read_b128 v[194:197], v216
	ds_read_b128 v[208:211], v216 offset:1024
	ds_read_b128 v[212:215], v216 offset:2048
	ds_read_b128 v[216:219], v216 offset:3072
	global_load_lds_dwordx4 v130, s[80:81]
	s_add_i32 m0, s20, 0x2000
	s_nop 0
	global_load_lds_dwordx4 v134, s[80:81]
	s_barrier
	s_waitcnt lgkmcnt(0)
	s_setprio 1
	s_waitcnt lgkmcnt(0)
	v_mfma_f32_16x16x32_bf16 v[116:119], v[194:197], v[162:165], v[116:119]
	v_mfma_f32_16x16x32_bf16 v[112:115], v[212:215], v[162:165], v[112:115]
	v_mfma_f32_16x16x32_bf16 v[100:103], v[194:197], v[170:173], v[100:103]
	v_mfma_f32_16x16x32_bf16 v[96:99], v[212:215], v[170:173], v[96:99]
	v_mfma_f32_16x16x32_bf16 v[84:87], v[194:197], v[178:181], v[84:87]
	v_mfma_f32_16x16x32_bf16 v[80:83], v[212:215], v[178:181], v[80:83]
	v_mfma_f32_16x16x32_bf16 v[68:71], v[194:197], v[186:189], v[68:71]
	v_mfma_f32_16x16x32_bf16 v[64:67], v[212:215], v[186:189], v[64:67]
	v_mfma_f32_16x16x32_bf16 v[116:119], v[208:211], v[166:169], v[116:119]
	v_mfma_f32_16x16x32_bf16 v[112:115], v[216:219], v[166:169], v[112:115]
	v_mfma_f32_16x16x32_bf16 v[100:103], v[208:211], v[174:177], v[100:103]
	v_mfma_f32_16x16x32_bf16 v[96:99], v[216:219], v[174:177], v[96:99]
	v_mfma_f32_16x16x32_bf16 v[84:87], v[208:211], v[182:185], v[84:87]
	v_mfma_f32_16x16x32_bf16 v[80:83], v[216:219], v[182:185], v[80:83]
	v_mfma_f32_16x16x32_bf16 v[68:71], v[208:211], v[190:193], v[68:71]
	v_mfma_f32_16x16x32_bf16 v[64:67], v[216:219], v[190:193], v[64:67]
	s_setprio 0
	s_mov_b32 m0, s42
	s_barrier
	ds_read_b128 v[162:165], v204 offset:49152
	ds_read_b128 v[166:169], v204 offset:50176
	ds_read_b128 v[170:173], v204 offset:51200
	ds_read_b128 v[174:177], v204 offset:52224
	ds_read_b128 v[178:181], v204 offset:53248
	ds_read_b128 v[182:185], v204 offset:54272
	ds_read_b128 v[186:189], v204 offset:55296
	ds_read_b128 v[190:193], v204 offset:56320
	global_load_lds_dwordx4 v128, s[82:83]
	s_mov_b32 m0, s43
	s_nop 0
	global_load_lds_dwordx4 v132, s[82:83]
	s_barrier
	s_waitcnt lgkmcnt(0)
	s_setprio 1
	s_waitcnt lgkmcnt(0)
	v_mfma_f32_16x16x32_bf16 v[60:63], v[146:149], v[162:165], v[60:63]
	v_mfma_f32_16x16x32_bf16 v[56:59], v[154:157], v[162:165], v[56:59]
	v_mfma_f32_16x16x32_bf16 v[44:47], v[146:149], v[170:173], v[44:47]
	v_mfma_f32_16x16x32_bf16 v[40:43], v[154:157], v[170:173], v[40:43]
	v_mfma_f32_16x16x32_bf16 v[28:31], v[146:149], v[178:181], v[28:31]
	v_mfma_f32_16x16x32_bf16 v[24:27], v[154:157], v[178:181], v[24:27]
	v_mfma_f32_16x16x32_bf16 v[12:15], v[146:149], v[186:189], v[12:15]
	v_mfma_f32_16x16x32_bf16 v[8:11], v[154:157], v[186:189], v[8:11]
	v_mfma_f32_16x16x32_bf16 v[60:63], v[150:153], v[166:169], v[60:63]
	v_mfma_f32_16x16x32_bf16 v[56:59], v[158:161], v[166:169], v[56:59]
	v_mfma_f32_16x16x32_bf16 v[44:47], v[150:153], v[174:177], v[44:47]
	v_mfma_f32_16x16x32_bf16 v[40:43], v[158:161], v[174:177], v[40:43]
	v_mfma_f32_16x16x32_bf16 v[28:31], v[150:153], v[182:185], v[28:31]
	v_mfma_f32_16x16x32_bf16 v[24:27], v[158:161], v[182:185], v[24:27]
	v_mfma_f32_16x16x32_bf16 v[12:15], v[150:153], v[190:193], v[12:15]
	v_mfma_f32_16x16x32_bf16 v[8:11], v[158:161], v[190:193], v[8:11]
	s_setprio 0
	s_barrier
	s_add_u32 s20, s24, 0xb0080
	s_addc_u32 s21, s25, 0
	s_add_i32 s24, s26, s36
	s_mov_b32 m0, s24
	s_nop 0
	global_load_lds_dwordx4 v130, s[20:21]
	s_add_i32 m0, s24, 0x2000
	s_nop 0
	global_load_lds_dwordx4 v134, s[20:21]
	s_waitcnt vmcnt(6)
	s_barrier
	s_setprio 1
	v_mfma_f32_16x16x32_bf16 v[52:55], v[194:197], v[162:165], v[52:55]
	v_mfma_f32_16x16x32_bf16 v[48:51], v[212:215], v[162:165], v[48:51]
	v_mfma_f32_16x16x32_bf16 v[36:39], v[194:197], v[170:173], v[36:39]
	v_mfma_f32_16x16x32_bf16 v[32:35], v[212:215], v[170:173], v[32:35]
	v_mfma_f32_16x16x32_bf16 v[20:23], v[194:197], v[178:181], v[20:23]
	v_mfma_f32_16x16x32_bf16 v[16:19], v[212:215], v[178:181], v[16:19]
	v_mfma_f32_16x16x32_bf16 v[4:7], v[194:197], v[186:189], v[4:7]
	v_mfma_f32_16x16x32_bf16 v[0:3], v[212:215], v[186:189], v[0:3]
	v_mfma_f32_16x16x32_bf16 v[52:55], v[208:211], v[166:169], v[52:55]
	v_mfma_f32_16x16x32_bf16 v[48:51], v[216:219], v[166:169], v[48:51]
	v_mfma_f32_16x16x32_bf16 v[36:39], v[208:211], v[174:177], v[36:39]
	v_mfma_f32_16x16x32_bf16 v[32:35], v[216:219], v[174:177], v[32:35]
	v_mfma_f32_16x16x32_bf16 v[20:23], v[208:211], v[182:185], v[20:23]
	v_mfma_f32_16x16x32_bf16 v[16:19], v[216:219], v[182:185], v[16:19]
	v_mfma_f32_16x16x32_bf16 v[4:7], v[208:211], v[190:193], v[4:7]
	v_mfma_f32_16x16x32_bf16 v[0:3], v[216:219], v[190:193], v[0:3]
	s_setprio 0
	s_add_i32 s56, s56, 2
	s_add_u32 s54, s54, 0x100
	s_addc_u32 s55, s55, 0
	s_cmp_gt_u32 s56, 41
	s_mov_b64 s[20:21], s[22:23]
	s_barrier
	s_cbranch_scc0 .LBB0_973
	s_cmpk_gt_u32 s30, 0xff
	s_cbranch_scc1 .Lg973_nox
	s_barrier
.Lg973_nox:
	v_lshl_add_u32 v148, s53, 8, v200
	v_ashrrev_i32_e32 v149, 31, v148
	v_lshl_or_b32 v146, s10, 8, v202
	v_lshlrev_b64 v[150:151], 11, v[148:149]
	v_ashrrev_i32_e32 v147, 31, v146
	v_lshl_add_u64 v[150:151], s[12:13], 0, v[150:151]
	v_lshl_add_u64 v[154:155], v[146:147], 1, v[150:151]
	global_load_dwordx4 v[150:153], v[154:155], off
	s_nop 0
	global_load_dwordx4 v[154:157], v[154:155], off offset:256
	v_and_b32_e32 v159, 64, v206
	v_xor_b32_e32 v158, 16, v206
	v_add_u32_e32 v166, 64, v159
	v_cmp_lt_i32_e32 vcc, v158, v166
	s_lshl_b32 s20, s10, 2
	s_ashr_i32 s21, s20, 31
	v_cndmask_b32_e32 v158, v206, v158, vcc
	v_lshlrev_b32_e32 v208, 2, v158
	v_lshlrev_b64 v[182:183], 6, v[148:149]
	s_waitcnt vmcnt(0)
	v_lshlrev_b32_e32 v158, 16, v150
	v_and_b32_e32 v159, 0xffff0000, v150
	v_lshlrev_b32_e32 v150, 16, v151
	v_and_b32_e32 v151, 0xffff0000, v151
	v_lshlrev_b32_e32 v160, 16, v152
	v_and_b32_e32 v161, 0xffff0000, v152
	v_lshlrev_b32_e32 v162, 16, v154
	v_and_b32_e32 v163, 0xffff0000, v154
	v_lshlrev_b32_e32 v154, 16, v155
	v_and_b32_e32 v155, 0xffff0000, v155
	v_lshlrev_b32_e32 v164, 16, v156
	v_and_b32_e32 v165, 0xffff0000, v156
	v_pk_fma_f32 v[126:127], v[126:127], 0.5, v[150:151] op_sel_hi:[1,0,1]
	v_pk_fma_f32 v[150:151], v[124:125], 0.5, v[158:159] op_sel_hi:[1,0,1]
	v_pk_fma_f32 v[124:125], v[120:121], 0.5, v[160:161] op_sel_hi:[1,0,1]
	v_pk_fma_f32 v[118:119], v[118:119], 0.5, v[154:155] op_sel_hi:[1,0,1]
	v_pk_fma_f32 v[120:121], v[116:117], 0.5, v[162:163] op_sel_hi:[1,0,1]
	v_lshlrev_b32_e32 v152, 16, v153
	v_and_b32_e32 v153, 0xffff0000, v153
	v_lshlrev_b32_e32 v156, 16, v157
	v_and_b32_e32 v157, 0xffff0000, v157
	v_pk_fma_f32 v[116:117], v[112:113], 0.5, v[164:165] op_sel_hi:[1,0,1]
	v_mul_f32_e32 v112, v151, v151
	v_mul_f32_e32 v113, v127, v127
	v_mul_f32_e32 v154, v121, v121
	v_mul_f32_e32 v155, v119, v119
	v_pk_fma_f32 v[122:123], v[122:123], 0.5, v[152:153] op_sel_hi:[1,0,1]
	v_pk_fma_f32 v[114:115], v[114:115], 0.5, v[156:157] op_sel_hi:[1,0,1]
	v_mul_f32_e32 v152, v125, v125
	v_mul_f32_e32 v156, v117, v117
	v_fmac_f32_e32 v112, v150, v150
	v_fmac_f32_e32 v113, v126, v126
	v_fmac_f32_e32 v154, v120, v120
	v_fmac_f32_e32 v155, v118, v118
	v_mul_f32_e32 v153, v123, v123
	v_mul_f32_e32 v157, v115, v115
	v_fmac_f32_e32 v152, v124, v124
	v_fmac_f32_e32 v156, v116, v116
	v_add_f32_e32 v112, v112, v113
	v_add_f32_e32 v113, v154, v155
	v_fmac_f32_e32 v153, v122, v122
	v_fmac_f32_e32 v157, v114, v114
	v_add_f32_e32 v112, v152, v112
	v_add_f32_e32 v113, v156, v113
	v_add_f32_e32 v112, v153, v112
	v_add_f32_e32 v113, v157, v113
	v_add_f32_e32 v112, v112, v113
	ds_bpermute_b32 v113, v208, v112
	v_xor_b32_e32 v152, 32, v206
	v_cmp_lt_i32_e32 vcc, v152, v166
	s_waitcnt lgkmcnt(0)
	v_add_f32_e32 v112, v112, v113
	v_cndmask_b32_e32 v152, v206, v152, vcc
	v_lshlrev_b32_e32 v209, 2, v152
	ds_bpermute_b32 v113, v209, v112
	s_and_saveexec_b64 s[22:23], s[0:1]
	s_cbranch_execz .LBB0_976
	s_waitcnt lgkmcnt(0)
	v_add_f32_e32 v152, v112, v113
	v_lshl_add_u64 v[112:113], s[14:15], 0, v[182:183]
	v_lshl_add_u64 v[112:113], s[20:21], 2, v[112:113]
	s_lshl_b32 s10, s41, 2
	v_lshl_add_u64 v[112:113], v[112:113], 0, s[10:11]
	global_store_dword v[112:113], v152, off sc1

.LBB0_1038:
	s_waitcnt vmcnt(0)
	s_cmpk_gt_u32 s30, 0xff
	s_cbranch_scc1 .LBB0_1040
.LBB0_1040:
	s_barrier
	s_endpgm
